# cache policy: residual-add GEMM phases (w_out, w2 x2, w_o) output stores also write-through (sc0 sc1); on top of v68
# speedup vs baseline: 1.0091x; 1.0029x over previous
; #define PG8_STAGE(bufoff, gbase, voff) do { _Pragma("unroll") for (int _i = 0; _i < 2; ++_i) \
;         __builtin_amdgcn_global_load_lds((const unsigned*)((const char*)(gbase) + (voff)[_i]), (LAS unsigned*)(lds + (bufoff) + ldsw + _i * 8192), 16, 0, 0); } while (0)
; #define PG8_LDA(dst, b, h) do { _Pragma("unroll") for (int m = 0; m < 4; ++m) _Pragma("unroll") for (int k = 0; k < 2; ++k) dst[m][k] = *(const LAS bf16x8*)(lds + PG8_SA(b, h) + aoff + m * 2048 + k * 1024); } while (0)
; #define PG8_LDB(dst, b, h) do { _Pragma("unroll") for (int n = 0; n < 2; ++n) _Pragma("unroll") for (int k = 0; k < 2; ++k) dst[n][k] = *(const LAS bf16x8*)(lds + PG8_SB(b, h) + boff + n * 2048 + k * 1024); } while (0)
; #define PG8_MMA(ai, bj, At, Bt) do { __builtin_amdgcn_s_setprio(1); _Pragma("unroll") for (int m = 0; m < 4; ++m) _Pragma("unroll") for (int n = 0; n < 2; ++n) _Pragma("unroll") for (int k = 0; k < 2; ++k) \
;         acc[ai][bj][m][n] = __builtin_amdgcn_mfma_f32_16x16x32_bf16(Bt[n][k], At[m][k], acc[ai][bj][m][n], 0, 0, 0); __builtin_amdgcn_s_setprio(0); } while (0)
; #define PG8_WAIT_L(n) asm volatile("s_waitcnt lgkmcnt(" #n ")" ::: "memory")
; #define PG8_BAR __builtin_amdgcn_s_barrier()
; #define PG8_SCHED __builtin_amdgcn_sched_barrier(0)
; template <class Epi>
; __device__ __forceinline__ void gemm_phase(LAS unsigned char* lds, const Gemm g, const Order& S, const Epi& E, const int tid) {
;     ...
;             PG8_LDB(B0, 0, 0); PG8_SCHED; PG8_LDA(At, 0, 0); PG8_STAGE(PG8_SA(1, 1), a1 + hstepA, voffA);
;             PG8_WAIT_L(8); PG8_BAR; PG8_WAIT_L(0); PG8_MMA(0, 0, At, B0); PG8_BAR; PG8_SCHED;
;             PG8_LDB(B1, 0, 1); PG8_STAGE(PG8_SB(0, 0), b2, voffB);
;             PG8_BAR; PG8_WAIT_L(0); PG8_MMA(0, 1, At, B1); PG8_BAR;
;             PG8_LDA(At, 0, 1); PG8_STAGE(PG8_SA(0, 0), a2, voffA);
;             PG8_BAR; PG8_WAIT_L(0); PG8_MMA(1, 0, At, B0); PG8_BAR; PG8_SCHED;
.LBB0_592:
	ds_read_b128 v[128:131], v171
	ds_read_b128 v[132:135], v171 offset:1024
	ds_read_b128 v[136:139], v171 offset:2048
	ds_read_b128 v[140:143], v171 offset:3072
	s_add_u32 s28, s26, 0xfff80080
	s_addc_u32 s29, s27, -1
	s_cmp_eq_u32 s51, 28
	s_cselect_b32 s31, s7, s29
	s_cselect_b32 s30, s15, s28
	s_cselect_b32 s29, s17, s50
	s_cselect_b32 s28, s48, s49
	v_lshl_add_u64 v[200:201], s[26:27], 0, v[152:153]
	s_add_i32 m0, s34, 0xc000
	ds_read_b128 v[160:163], v172
	ds_read_b128 v[164:167], v172 offset:1024
	ds_read_b128 v[176:179], v172 offset:2048
	ds_read_b128 v[180:183], v172 offset:3072
	ds_read_b128 v[184:187], v172 offset:4096
	ds_read_b128 v[188:191], v172 offset:5120
	ds_read_b128 v[192:195], v172 offset:6144
	ds_read_b128 v[196:199], v172 offset:7168
	global_load_lds_dwordx4 v[200:201], off
	v_lshl_add_u64 v[200:201], s[26:27], 0, v[154:155]
	s_add_i32 m0, s34, 0xe000
	s_nop 0
	global_load_lds_dwordx4 v[200:201], off
	s_waitcnt lgkmcnt(8)
	s_barrier
	s_waitcnt lgkmcnt(0)
	s_setprio 1
	s_waitcnt lgkmcnt(0)
	v_mfma_f32_16x16x32_bf16 v[124:127], v[128:131], v[160:163], v[124:127]
	v_mfma_f32_16x16x32_bf16 v[120:123], v[136:139], v[160:163], v[120:123]
	v_mfma_f32_16x16x32_bf16 v[108:111], v[128:131], v[176:179], v[108:111]
	v_mfma_f32_16x16x32_bf16 v[104:107], v[136:139], v[176:179], v[104:107]
	v_mfma_f32_16x16x32_bf16 v[92:95], v[128:131], v[184:187], v[92:95]
	v_mfma_f32_16x16x32_bf16 v[88:91], v[136:139], v[184:187], v[88:91]
	v_mfma_f32_16x16x32_bf16 v[76:79], v[128:131], v[192:195], v[76:79]
	v_mfma_f32_16x16x32_bf16 v[72:75], v[136:139], v[192:195], v[72:75]
	v_mfma_f32_16x16x32_bf16 v[124:127], v[132:135], v[164:167], v[124:127]
	v_mfma_f32_16x16x32_bf16 v[120:123], v[140:143], v[164:167], v[120:123]
	v_mfma_f32_16x16x32_bf16 v[108:111], v[132:135], v[180:183], v[108:111]
	v_mfma_f32_16x16x32_bf16 v[104:107], v[140:143], v[180:183], v[104:107]
	v_mfma_f32_16x16x32_bf16 v[92:95], v[132:135], v[188:191], v[92:95]
	v_mfma_f32_16x16x32_bf16 v[88:91], v[140:143], v[188:191], v[88:91]
	v_mfma_f32_16x16x32_bf16 v[76:79], v[132:135], v[196:199], v[76:79]
	v_mfma_f32_16x16x32_bf16 v[72:75], v[140:143], v[196:199], v[72:75]
	s_setprio 0
	s_barrier
	s_add_i32 s52, s45, s33
	v_lshl_add_u64 v[216:217], s[28:29], 0, v[146:147]
	s_mov_b32 m0, s52
	ds_read_b128 v[200:203], v173
	ds_read_b128 v[204:207], v173 offset:1024
	ds_read_b128 v[208:211], v173 offset:2048
	ds_read_b128 v[212:215], v173 offset:3072
	global_load_lds_dwordx4 v[216:217], off
	v_lshl_add_u64 v[218:219], s[28:29], 0, v[150:151]
	s_add_i32 m0, s52, 0x2000
	s_nop 0
	global_load_lds_dwordx4 v[218:219], off
	s_barrier
	s_waitcnt lgkmcnt(0)
	s_setprio 1
	s_waitcnt lgkmcnt(0)
	v_mfma_f32_16x16x32_bf16 v[116:119], v[200:203], v[160:163], v[116:119]
	v_mfma_f32_16x16x32_bf16 v[112:115], v[208:211], v[160:163], v[112:115]
	v_mfma_f32_16x16x32_bf16 v[100:103], v[200:203], v[176:179], v[100:103]
	v_mfma_f32_16x16x32_bf16 v[96:99], v[208:211], v[176:179], v[96:99]
	v_mfma_f32_16x16x32_bf16 v[84:87], v[200:203], v[184:187], v[84:87]
	v_mfma_f32_16x16x32_bf16 v[80:83], v[208:211], v[184:187], v[80:83]
	v_mfma_f32_16x16x32_bf16 v[68:71], v[200:203], v[192:195], v[68:71]
	v_mfma_f32_16x16x32_bf16 v[64:67], v[208:211], v[192:195], v[64:67]
	v_mfma_f32_16x16x32_bf16 v[116:119], v[204:207], v[164:167], v[116:119]
	v_mfma_f32_16x16x32_bf16 v[112:115], v[212:215], v[164:167], v[112:115]
	v_mfma_f32_16x16x32_bf16 v[100:103], v[204:207], v[180:183], v[100:103]
	v_mfma_f32_16x16x32_bf16 v[96:99], v[212:215], v[180:183], v[96:99]
	v_mfma_f32_16x16x32_bf16 v[84:87], v[204:207], v[188:191], v[84:87]
	v_mfma_f32_16x16x32_bf16 v[80:83], v[212:215], v[188:191], v[80:83]
	v_mfma_f32_16x16x32_bf16 v[68:71], v[204:207], v[196:199], v[68:71]
	v_mfma_f32_16x16x32_bf16 v[64:67], v[212:215], v[196:199], v[64:67]
	s_setprio 0
	s_mov_b32 m0, s34
	v_lshl_add_u64 v[220:221], s[30:31], 0, v[144:145]
	s_barrier
	ds_read_b128 v[160:163], v172 offset:16384
	ds_read_b128 v[164:167], v172 offset:17408
	ds_read_b128 v[176:179], v172 offset:18432
	ds_read_b128 v[180:183], v172 offset:19456
	ds_read_b128 v[184:187], v172 offset:20480
	ds_read_b128 v[188:191], v172 offset:21504
	ds_read_b128 v[192:195], v172 offset:22528
	ds_read_b128 v[196:199], v172 offset:23552
	global_load_lds_dwordx4 v[220:221], off
	v_lshl_add_u64 v[222:223], s[30:31], 0, v[148:149]
	s_mov_b32 m0, s35
	s_nop 0
	global_load_lds_dwordx4 v[222:223], off
	s_barrier
	s_waitcnt lgkmcnt(0)
	s_setprio 1
	s_waitcnt lgkmcnt(0)
	v_mfma_f32_16x16x32_bf16 v[60:63], v[128:131], v[160:163], v[60:63]
	v_mfma_f32_16x16x32_bf16 v[56:59], v[136:139], v[160:163], v[56:59]
	v_mfma_f32_16x16x32_bf16 v[44:47], v[128:131], v[176:179], v[44:47]
	v_mfma_f32_16x16x32_bf16 v[40:43], v[136:139], v[176:179], v[40:43]
	v_mfma_f32_16x16x32_bf16 v[28:31], v[128:131], v[184:187], v[28:31]
	v_mfma_f32_16x16x32_bf16 v[24:27], v[136:139], v[184:187], v[24:27]
	v_mfma_f32_16x16x32_bf16 v[12:15], v[128:131], v[192:195], v[12:15]
	v_mfma_f32_16x16x32_bf16 v[8:11], v[136:139], v[192:195], v[8:11]
	v_mfma_f32_16x16x32_bf16 v[60:63], v[132:135], v[164:167], v[60:63]
	v_mfma_f32_16x16x32_bf16 v[56:59], v[140:143], v[164:167], v[56:59]
	v_mfma_f32_16x16x32_bf16 v[44:47], v[132:135], v[180:183], v[44:47]
	v_mfma_f32_16x16x32_bf16 v[40:43], v[140:143], v[180:183], v[40:43]
	v_mfma_f32_16x16x32_bf16 v[28:31], v[132:135], v[188:191], v[28:31]
	v_mfma_f32_16x16x32_bf16 v[24:27], v[140:143], v[188:191], v[24:27]
	v_mfma_f32_16x16x32_bf16 v[12:15], v[132:135], v[196:199], v[12:15]
	v_mfma_f32_16x16x32_bf16 v[8:11], v[140:143], v[196:199], v[8:11]
	s_setprio 0
	s_barrier
; #define PG8_STAGE(bufoff, gbase, voff) do { _Pragma("unroll") for (int _i = 0; _i < 2; ++_i) \
;         __builtin_amdgcn_global_load_lds((const unsigned*)((const char*)(gbase) + (voff)[_i]), (LAS unsigned*)(lds + (bufoff) + ldsw + _i * 8192), 16, 0, 0); } while (0)
; #define PG8_LDA(dst, b, h) do { _Pragma("unroll") for (int m = 0; m < 4; ++m) _Pragma("unroll") for (int k = 0; k < 2; ++k) dst[m][k] = *(const LAS bf16x8*)(lds + PG8_SA(b, h) + aoff + m * 2048 + k * 1024); } while (0)
; #define PG8_LDB(dst, b, h) do { _Pragma("unroll") for (int n = 0; n < 2; ++n) _Pragma("unroll") for (int k = 0; k < 2; ++k) dst[n][k] = *(const LAS bf16x8*)(lds + PG8_SB(b, h) + boff + n * 2048 + k * 1024); } while (0)
; #define PG8_MMA(ai, bj, At, Bt) do { __builtin_amdgcn_s_setprio(1); _Pragma("unroll") for (int m = 0; m < 4; ++m) _Pragma("unroll") for (int n = 0; n < 2; ++n) _Pragma("unroll") for (int k = 0; k < 2; ++k) \
;         acc[ai][bj][m][n] = __builtin_amdgcn_mfma_f32_16x16x32_bf16(Bt[n][k], At[m][k], acc[ai][bj][m][n], 0, 0, 0); __builtin_amdgcn_s_setprio(0); } while (0)
; #define PG8_WAIT_V(n) asm volatile("s_waitcnt vmcnt(" #n ")" ::: "memory")
; #define PG8_WAIT_L(n) asm volatile("s_waitcnt lgkmcnt(" #n ")" ::: "memory")
; #define PG8_BAR __builtin_amdgcn_s_barrier()
; #define PG8_SCHED __builtin_amdgcn_sched_barrier(0)
; template <class Epi>
; __device__ __forceinline__ void gemm_phase(LAS unsigned char* lds, const Gemm g, const Order& S, const Epi& E, const int tid) {
;     ...
;             PG8_STAGE(PG8_SB(0, 1), b2 + hstepB, voffB);
;             PG8_WAIT_V(6); PG8_BAR; PG8_MMA(1, 1, At, B1); PG8_BAR;
;             PG8_LDB(B0, 1, 0); PG8_SCHED; PG8_LDA(At, 1, 0); PG8_STAGE(PG8_SA(0, 1), a2 + hstepA, voffA);
;             PG8_WAIT_L(8); PG8_BAR; PG8_WAIT_L(0); PG8_MMA(0, 0, At, B0); PG8_BAR; PG8_SCHED;
;             PG8_LDB(B1, 1, 1); PG8_STAGE(PG8_SB(1, 0), b3, voffB);
;             PG8_BAR; PG8_WAIT_L(0); PG8_MMA(0, 1, At, B1); PG8_BAR;
;             PG8_LDA(At, 1, 1); PG8_STAGE(PG8_SA(1, 0), a3, voffA);
	s_add_u32 s52, s28, 0x80000
	s_addc_u32 s53, s29, 0
	s_add_i32 s55, s46, s33
	v_lshl_add_u64 v[128:129], s[52:53], 0, v[146:147]
	s_mov_b32 m0, s55
	s_nop 0
	global_load_lds_dwordx4 v[128:129], off
	v_lshl_add_u64 v[128:129], s[52:53], 0, v[150:151]
	s_add_i32 m0, s55, 0x2000
	s_nop 0
	global_load_lds_dwordx4 v[128:129], off
	s_waitcnt vmcnt(6)
	s_barrier
	s_setprio 1
	v_mfma_f32_16x16x32_bf16 v[52:55], v[200:203], v[160:163], v[52:55]
	v_mfma_f32_16x16x32_bf16 v[48:51], v[208:211], v[160:163], v[48:51]
	v_mfma_f32_16x16x32_bf16 v[36:39], v[200:203], v[176:179], v[36:39]
	v_mfma_f32_16x16x32_bf16 v[32:35], v[208:211], v[176:179], v[32:35]
	v_mfma_f32_16x16x32_bf16 v[20:23], v[200:203], v[184:187], v[20:23]
	v_mfma_f32_16x16x32_bf16 v[16:19], v[208:211], v[184:187], v[16:19]
	v_mfma_f32_16x16x32_bf16 v[4:7], v[200:203], v[192:195], v[4:7]
	v_mfma_f32_16x16x32_bf16 v[0:3], v[208:211], v[192:195], v[0:3]
	v_mfma_f32_16x16x32_bf16 v[52:55], v[204:207], v[164:167], v[52:55]
	v_mfma_f32_16x16x32_bf16 v[48:51], v[212:215], v[164:167], v[48:51]
	v_mfma_f32_16x16x32_bf16 v[36:39], v[204:207], v[180:183], v[36:39]
	v_mfma_f32_16x16x32_bf16 v[32:35], v[212:215], v[180:183], v[32:35]
	v_mfma_f32_16x16x32_bf16 v[20:23], v[204:207], v[188:191], v[20:23]
	v_mfma_f32_16x16x32_bf16 v[16:19], v[212:215], v[188:191], v[16:19]
	v_mfma_f32_16x16x32_bf16 v[4:7], v[204:207], v[196:199], v[4:7]
	v_mfma_f32_16x16x32_bf16 v[0:3], v[212:215], v[196:199], v[0:3]
	s_setprio 0
	s_add_i32 s52, 0, 0x18000
	v_add_u32_e32 v140, s52, v169
	s_barrier
	ds_read_b128 v[128:131], v140
	ds_read_b128 v[132:135], v140 offset:1024
	ds_read_b128 v[136:139], v140 offset:2048
	ds_read_b128 v[140:143], v140 offset:3072
	s_add_u32 s30, s30, 0x80000
	s_addc_u32 s31, s31, 0
	s_mov_b32 m0, s39
	v_lshl_add_u64 v[200:201], s[30:31], 0, v[144:145]
	ds_read_b128 v[160:163], v172 offset:32768
	ds_read_b128 v[164:167], v172 offset:33792
	ds_read_b128 v[176:179], v172 offset:34816
	ds_read_b128 v[180:183], v172 offset:35840
	ds_read_b128 v[184:187], v172 offset:36864
	ds_read_b128 v[188:191], v172 offset:37888
	ds_read_b128 v[192:195], v172 offset:38912
	ds_read_b128 v[196:199], v172 offset:39936
	global_load_lds_dwordx4 v[200:201], off
	v_lshl_add_u64 v[200:201], s[30:31], 0, v[148:149]
	s_mov_b32 m0, s40
	s_nop 0
	global_load_lds_dwordx4 v[200:201], off
	s_waitcnt lgkmcnt(8)
	s_barrier
	s_waitcnt lgkmcnt(0)
	s_setprio 1
	s_waitcnt lgkmcnt(0)
	v_mfma_f32_16x16x32_bf16 v[124:127], v[128:131], v[160:163], v[124:127]
	v_mfma_f32_16x16x32_bf16 v[120:123], v[136:139], v[160:163], v[120:123]
	v_mfma_f32_16x16x32_bf16 v[108:111], v[128:131], v[176:179], v[108:111]
	v_mfma_f32_16x16x32_bf16 v[104:107], v[136:139], v[176:179], v[104:107]
	v_mfma_f32_16x16x32_bf16 v[92:95], v[128:131], v[184:187], v[92:95]
	v_mfma_f32_16x16x32_bf16 v[88:91], v[136:139], v[184:187], v[88:91]
	v_mfma_f32_16x16x32_bf16 v[76:79], v[128:131], v[192:195], v[76:79]
	v_mfma_f32_16x16x32_bf16 v[72:75], v[136:139], v[192:195], v[72:75]
	v_mfma_f32_16x16x32_bf16 v[124:127], v[132:135], v[164:167], v[124:127]
	v_mfma_f32_16x16x32_bf16 v[120:123], v[140:143], v[164:167], v[120:123]
	v_mfma_f32_16x16x32_bf16 v[108:111], v[132:135], v[180:183], v[108:111]
	v_mfma_f32_16x16x32_bf16 v[104:107], v[140:143], v[180:183], v[104:107]
	v_mfma_f32_16x16x32_bf16 v[92:95], v[132:135], v[188:191], v[92:95]
	v_mfma_f32_16x16x32_bf16 v[88:91], v[140:143], v[188:191], v[88:91]
	v_mfma_f32_16x16x32_bf16 v[76:79], v[132:135], v[196:199], v[76:79]
	v_mfma_f32_16x16x32_bf16 v[72:75], v[140:143], v[196:199], v[72:75]
	s_setprio 0
	s_barrier
	s_add_i32 s30, 0, 0x1c000
	s_add_i32 s31, s52, s33
	v_add_u32_e32 v175, s30, v169
	v_lshl_add_u64 v[216:217], v[216:217], 0, s[12:13]
	s_mov_b32 m0, s31
	ds_read_b128 v[200:203], v175
	ds_read_b128 v[204:207], v175 offset:1024
	ds_read_b128 v[208:211], v175 offset:2048
	ds_read_b128 v[212:215], v175 offset:3072
	global_load_lds_dwordx4 v[216:217], off
	v_lshl_add_u64 v[216:217], v[218:219], 0, s[12:13]
	s_add_i32 m0, s31, 0x2000
	s_nop 0
	global_load_lds_dwordx4 v[216:217], off
	s_barrier
	s_waitcnt lgkmcnt(0)
	s_setprio 1
	s_waitcnt lgkmcnt(0)
	v_mfma_f32_16x16x32_bf16 v[116:119], v[200:203], v[160:163], v[116:119]
	v_mfma_f32_16x16x32_bf16 v[112:115], v[208:211], v[160:163], v[112:115]
	v_mfma_f32_16x16x32_bf16 v[100:103], v[200:203], v[176:179], v[100:103]
	v_mfma_f32_16x16x32_bf16 v[96:99], v[208:211], v[176:179], v[96:99]
	v_mfma_f32_16x16x32_bf16 v[84:87], v[200:203], v[184:187], v[84:87]
	v_mfma_f32_16x16x32_bf16 v[80:83], v[208:211], v[184:187], v[80:83]
	v_mfma_f32_16x16x32_bf16 v[68:71], v[200:203], v[192:195], v[68:71]
	v_mfma_f32_16x16x32_bf16 v[64:67], v[208:211], v[192:195], v[64:67]
	v_mfma_f32_16x16x32_bf16 v[116:119], v[204:207], v[164:167], v[116:119]
	v_mfma_f32_16x16x32_bf16 v[112:115], v[212:215], v[164:167], v[112:115]
	v_mfma_f32_16x16x32_bf16 v[100:103], v[204:207], v[180:183], v[100:103]
	v_mfma_f32_16x16x32_bf16 v[96:99], v[212:215], v[180:183], v[96:99]
	v_mfma_f32_16x16x32_bf16 v[84:87], v[204:207], v[188:191], v[84:87]
	v_mfma_f32_16x16x32_bf16 v[80:83], v[212:215], v[188:191], v[80:83]
	v_mfma_f32_16x16x32_bf16 v[68:71], v[204:207], v[196:199], v[68:71]
	v_mfma_f32_16x16x32_bf16 v[64:67], v[212:215], v[196:199], v[64:67]
	s_setprio 0
	s_mov_b32 m0, s43
	v_lshl_add_u64 v[216:217], v[220:221], 0, s[12:13]
	s_barrier
	ds_read_b128 v[160:163], v172 offset:49152
	ds_read_b128 v[164:167], v172 offset:50176
	ds_read_b128 v[176:179], v172 offset:51200
	ds_read_b128 v[180:183], v172 offset:52224
	ds_read_b128 v[184:187], v172 offset:53248
	ds_read_b128 v[188:191], v172 offset:54272
	ds_read_b128 v[192:195], v172 offset:55296
	ds_read_b128 v[196:199], v172 offset:56320
	global_load_lds_dwordx4 v[216:217], off
	v_lshl_add_u64 v[216:217], v[222:223], 0, s[12:13]
	s_mov_b32 m0, s44
	s_nop 0
	global_load_lds_dwordx4 v[216:217], off
	s_barrier
; #define PG8_STAGE(bufoff, gbase, voff) do { _Pragma("unroll") for (int _i = 0; _i < 2; ++_i) \
;         __builtin_amdgcn_global_load_lds((const unsigned*)((const char*)(gbase) + (voff)[_i]), (LAS unsigned*)(lds + (bufoff) + ldsw + _i * 8192), 16, 0, 0); } while (0)
; #define PG8_WAIT_V(n) asm volatile("s_waitcnt vmcnt(" #n ")" ::: "memory")
; #define PG8_WAIT_L(n) asm volatile("s_waitcnt lgkmcnt(" #n ")" ::: "memory")
; #define PG8_BAR __builtin_amdgcn_s_barrier()
; template <class Epi>
; __device__ __forceinline__ void gemm_phase(LAS unsigned char* lds, const Gemm g, const Order& S, const Epi& E, const int tid) {
;     ...
;             PG8_BAR; PG8_WAIT_L(0); PG8_MMA(1, 0, At, B0); PG8_BAR; PG8_SCHED;
;             PG8_STAGE(PG8_SB(1, 1), b3 + hstepB, voffB);
;             PG8_WAIT_V(6); PG8_BAR; PG8_MMA(1, 1, At, B1); PG8_BAR;
;     __device__ __forceinline__ void operator()(const f32x4 (&acc)[2][2][4][2], const Unit& u, int wr, int wc, int fr, int fq) const {
;     ...
;                 for (int m = 0; m < 4; m += 2) {
;                     f32x4 bs[2][2][2];
; #pragma unroll
;                     for (int mm = 0; mm < 2; ++mm) { const size_t off = (size_t)(row0 + ai * HALF + (m + mm) * 16) * DM + col0;
; #pragma unroll
;                         for (int bj = 0; bj < 2; ++bj)
; #pragma unroll
;                             for (int n = 0; n < 2; ++n) bs[mm][bj][n] = *(const f32x4*)(basef + off + bj * HALF + n * 4); }
; #pragma unroll
;                     for (int mm = 0; mm < 2; ++mm) { const size_t off = (size_t)(row0 + ai * HALF + (m + mm) * 16) * DM + col0;
;                         float ss = 0.f;
; #pragma unroll
;                         for (int bj = 0; bj < 2; ++bj) { const f32x4 v0 = bs[mm][bj][0] + acc[ai][bj][m + mm][0], v1 = bs[mm][bj][1] + acc[ai][bj][m + mm][1];
;                             ss += (v0[0] * v0[0] + v0[1] * v0[1]) + (v0[2] * v0[2] + v0[3] * v0[3]) + (v1[0] * v1[0] + v1[1] * v1[1]) + (v1[2] * v1[2] + v1[3] * v1[3]);
;                             u32x4 w; w.x = pk2(v0[0], v0[1]); w.y = pk2(v0[2], v0[3]); w.z = pk2(v1[0], v1[1]); w.w = pk2(v1[2], v1[3]);
;                             *(u32x4*)(out + off + bj * HALF) = w; }
;                         if (ssqp) { ss += __shfl_xor(ss, 16); ss += __shfl_xor(ss, 32); if (fq == 0) ssqp[(size_t)(row0 + ai * HALF + (m + mm) * 16) * 32 + u.pn * 4 + wc] = ss; } }
	s_waitcnt lgkmcnt(0)
	s_setprio 1
	s_waitcnt lgkmcnt(0)
	v_mfma_f32_16x16x32_bf16 v[60:63], v[128:131], v[160:163], v[60:63]
	v_mfma_f32_16x16x32_bf16 v[56:59], v[136:139], v[160:163], v[56:59]
	v_mfma_f32_16x16x32_bf16 v[44:47], v[128:131], v[176:179], v[44:47]
	v_mfma_f32_16x16x32_bf16 v[40:43], v[136:139], v[176:179], v[40:43]
	v_mfma_f32_16x16x32_bf16 v[28:31], v[128:131], v[184:187], v[28:31]
	v_mfma_f32_16x16x32_bf16 v[24:27], v[136:139], v[184:187], v[24:27]
	v_mfma_f32_16x16x32_bf16 v[12:15], v[128:131], v[192:195], v[12:15]
	v_mfma_f32_16x16x32_bf16 v[8:11], v[136:139], v[192:195], v[8:11]
	v_mfma_f32_16x16x32_bf16 v[60:63], v[132:135], v[164:167], v[60:63]
	v_mfma_f32_16x16x32_bf16 v[56:59], v[140:143], v[164:167], v[56:59]
	v_mfma_f32_16x16x32_bf16 v[44:47], v[132:135], v[180:183], v[44:47]
	v_mfma_f32_16x16x32_bf16 v[40:43], v[140:143], v[180:183], v[40:43]
	v_mfma_f32_16x16x32_bf16 v[28:31], v[132:135], v[188:191], v[28:31]
	v_mfma_f32_16x16x32_bf16 v[24:27], v[140:143], v[188:191], v[24:27]
	v_mfma_f32_16x16x32_bf16 v[12:15], v[132:135], v[196:199], v[12:15]
	v_mfma_f32_16x16x32_bf16 v[8:11], v[140:143], v[196:199], v[8:11]
	s_setprio 0
	s_barrier
	s_add_u32 s28, s28, 0x80080
	s_addc_u32 s29, s29, 0
	s_add_i32 s30, s30, s33
	v_lshl_add_u64 v[128:129], s[28:29], 0, v[146:147]
	s_mov_b32 m0, s30
	s_nop 0
	global_load_lds_dwordx4 v[128:129], off
	v_lshl_add_u64 v[128:129], s[28:29], 0, v[150:151]
	s_add_i32 m0, s30, 0x2000
	s_nop 0
	global_load_lds_dwordx4 v[128:129], off
	s_waitcnt vmcnt(6)
	s_barrier
	s_setprio 1
	v_mfma_f32_16x16x32_bf16 v[52:55], v[200:203], v[160:163], v[52:55]
	v_mfma_f32_16x16x32_bf16 v[48:51], v[208:211], v[160:163], v[48:51]
	v_mfma_f32_16x16x32_bf16 v[36:39], v[200:203], v[176:179], v[36:39]
	v_mfma_f32_16x16x32_bf16 v[32:35], v[208:211], v[176:179], v[32:35]
	v_mfma_f32_16x16x32_bf16 v[20:23], v[200:203], v[184:187], v[20:23]
	v_mfma_f32_16x16x32_bf16 v[16:19], v[208:211], v[184:187], v[16:19]
	v_mfma_f32_16x16x32_bf16 v[4:7], v[200:203], v[192:195], v[4:7]
	v_mfma_f32_16x16x32_bf16 v[0:3], v[208:211], v[192:195], v[0:3]
	v_mfma_f32_16x16x32_bf16 v[52:55], v[204:207], v[164:167], v[52:55]
	v_mfma_f32_16x16x32_bf16 v[48:51], v[212:215], v[164:167], v[48:51]
	v_mfma_f32_16x16x32_bf16 v[36:39], v[204:207], v[180:183], v[36:39]
	v_mfma_f32_16x16x32_bf16 v[32:35], v[212:215], v[180:183], v[32:35]
	v_mfma_f32_16x16x32_bf16 v[20:23], v[204:207], v[188:191], v[20:23]
	v_mfma_f32_16x16x32_bf16 v[16:19], v[212:215], v[188:191], v[16:19]
	v_mfma_f32_16x16x32_bf16 v[4:7], v[204:207], v[196:199], v[4:7]
	v_mfma_f32_16x16x32_bf16 v[0:3], v[212:215], v[196:199], v[0:3]
	s_setprio 0
	s_add_i32 s51, s51, 2
	s_add_u32 s26, s26, 0x100
	s_addc_u32 s27, s27, 0
	s_add_u32 s49, s49, 0x100
	s_addc_u32 s50, s50, 0
	s_cmp_gt_u32 s51, 29
	s_barrier
	s_cbranch_scc0 .LBB0_592
	v_lshl_add_u32 v162, s8, 8, v168
	v_lshl_or_b32 v160, s6, 8, v170
	v_ashrrev_i32_e32 v161, 31, v160
	v_ashrrev_i32_e32 v163, 31, v162
	v_lshl_add_u64 v[164:165], v[160:161], 2, s[56:57]
	v_lshlrev_b64 v[128:129], 13, v[162:163]
	v_or_b32_e32 v166, 16, v162
	v_lshl_add_u64 v[128:129], v[164:165], 0, v[128:129]
	v_ashrrev_i32_e32 v167, 31, v166
	global_load_dwordx4 v[176:179], v[128:129], off
	global_load_dwordx4 v[180:183], v[128:129], off offset:16
	global_load_dwordx4 v[184:187], v[128:129], off offset:512
	global_load_dwordx4 v[188:191], v[128:129], off offset:528
	v_lshlrev_b64 v[128:129], 13, v[166:167]
	v_lshl_add_u64 v[132:133], v[164:165], 0, v[128:129]
	global_load_dwordx4 v[136:139], v[132:133], off offset:16
	global_load_dwordx4 v[140:143], v[132:133], off
	global_load_dwordx4 v[128:131], v[132:133], off offset:528
	s_nop 0
	global_load_dwordx4 v[132:135], v[132:133], off offset:512
	v_lshlrev_b64 v[192:193], 12, v[162:163]
	s_lshl_b32 s26, s6, 2
	v_cndmask_b32_e64 v175, 0, 1, s[10:11]
	v_lshl_add_u64 v[192:193], s[22:23], 0, v[192:193]
	s_ashr_i32 s27, s26, 31
	v_cmp_ne_u32_e64 s[6:7], 1, v175
	s_andn2_b64 vcc, exec, s[10:11]
	v_lshl_add_u64 v[192:193], v[160:161], 1, v[192:193]
	s_waitcnt vmcnt(0)
	v_pk_add_f32 v[126:127], v[126:127], v[178:179]
	v_pk_add_f32 v[124:125], v[124:125], v[176:177]
	v_pk_add_f32 v[122:123], v[122:123], v[182:183]
	v_pk_add_f32 v[120:121], v[120:121], v[180:181]
	v_pk_add_f32 v[118:119], v[118:119], v[186:187]
	v_pk_add_f32 v[116:117], v[116:117], v[184:185]
	v_pk_add_f32 v[114:115], v[114:115], v[190:191]
	v_pk_add_f32 v[112:113], v[112:113], v[188:189]
	v_cvt_pk_bf16_f32 v176, v124, v125
	v_cvt_pk_bf16_f32 v177, v126, v127
	v_cvt_pk_bf16_f32 v178, v120, v121
	v_cvt_pk_bf16_f32 v179, v122, v123
	v_cvt_pk_bf16_f32 v180, v116, v117
	v_cvt_pk_bf16_f32 v181, v118, v119
	v_cvt_pk_bf16_f32 v182, v112, v113
	v_cvt_pk_bf16_f32 v183, v114, v115
	global_store_dwordx4 v[192:193], v[176:179], off sc0 sc1
	global_store_dwordx4 v[192:193], v[180:183], off offset:256 sc0 sc1
	s_cbranch_vccnz .LBB0_597
	v_mul_f32_e32 v115, v115, v115
	v_fmac_f32_e32 v115, v114, v114
	v_mul_f32_e32 v114, v117, v117
	v_mul_f32_e32 v123, v123, v123
	v_fmac_f32_e32 v114, v116, v116
	v_mul_f32_e32 v116, v119, v119
	v_fmac_f32_e32 v123, v122, v122
	v_mul_f32_e32 v122, v125, v125
	v_fmac_f32_e32 v116, v118, v118
	v_mul_f32_e32 v113, v113, v113
	v_fmac_f32_e32 v122, v124, v124
	v_mul_f32_e32 v124, v127, v127
	v_add_f32_e32 v114, v114, v116
	v_fmac_f32_e32 v113, v112, v112
	v_fmac_f32_e32 v124, v126, v126
	v_mul_f32_e32 v121, v121, v121
	v_add_f32_e32 v112, v114, v113
	v_and_b32_e32 v114, 64, v174
	v_add_f32_e32 v122, v122, v124
	v_fmac_f32_e32 v121, v120, v120
	v_xor_b32_e32 v113, 16, v174
	v_add_u32_e32 v114, 64, v114
	v_add_f32_e32 v120, v122, v121
	v_cmp_lt_i32_e32 vcc, v113, v114
	v_add_f32_e32 v120, v123, v120
	v_add_f32_e32 v112, v115, v112
	v_cndmask_b32_e32 v113, v174, v113, vcc
	v_add_f32_e32 v112, v120, v112
	v_lshlrev_b32_e32 v113, 2, v113
	ds_bpermute_b32 v113, v113, v112
	s_waitcnt lgkmcnt(0)
	v_add_f32_e32 v112, v112, v113
	v_xor_b32_e32 v113, 32, v174
	v_cmp_lt_i32_e32 vcc, v113, v114
	s_nop 1
	v_cndmask_b32_e32 v113, v174, v113, vcc
	v_lshlrev_b32_e32 v113, 2, v113
	ds_bpermute_b32 v113, v113, v112
	s_and_saveexec_b64 s[28:29], s[0:1]
	s_cbranch_execz .LBB0_596
	v_lshlrev_b64 v[114:115], 7, v[162:163]
	v_lshl_add_u64 v[114:115], s[24:25], 0, v[114:115]
	v_lshl_add_u64 v[114:115], s[26:27], 2, v[114:115]
	s_lshl_b32 s8, s41, 2
	v_lshl_add_u64 v[114:115], v[114:115], 0, s[8:9]
	s_waitcnt lgkmcnt(0)
	v_add_f32_e32 v112, v112, v113
	global_store_dword v[114:115], v112, off

;     __device__ __forceinline__ void operator()(const f32x4 (&acc)[2][2][4][2], const Unit& u, int wr, int wc, int fr, int fq) const {
;     ...
;                     for (int mm = 0; mm < 2; ++mm) { const size_t off = (size_t)(row0 + ai * HALF + (m + mm) * 16) * DM + col0;
;                         float ss = 0.f;
; #pragma unroll
;                         for (int bj = 0; bj < 2; ++bj) { const f32x4 v0 = bs[mm][bj][0] + acc[ai][bj][m + mm][0], v1 = bs[mm][bj][1] + acc[ai][bj][m + mm][1];
;                             ss += (v0[0] * v0[0] + v0[1] * v0[1]) + (v0[2] * v0[2] + v0[3] * v0[3]) + (v1[0] * v1[0] + v1[1] * v1[1]) + (v1[2] * v1[2] + v1[3] * v1[3]);
;                             u32x4 w; w.x = pk2(v0[0], v0[1]); w.y = pk2(v0[2], v0[3]); w.z = pk2(v1[0], v1[1]); w.w = pk2(v1[2], v1[3]);
;                             *(u32x4*)(out + off + bj * HALF) = w; }
;                         if (ssqp) { ss += __shfl_xor(ss, 16); ss += __shfl_xor(ss, 32); if (fq == 0) ssqp[(size_t)(row0 + ai * HALF + (m + mm) * 16) * 32 + u.pn * 4 + wc] = ss; } }
.LBB0_597:
	v_lshlrev_b64 v[116:117], 12, v[166:167]
	v_pk_add_f32 v[110:111], v[110:111], v[142:143]
	v_pk_add_f32 v[108:109], v[108:109], v[140:141]
	v_pk_add_f32 v[106:107], v[106:107], v[138:139]
	v_pk_add_f32 v[104:105], v[104:105], v[136:137]
	v_lshl_add_u64 v[116:117], s[22:23], 0, v[116:117]
	v_cvt_pk_bf16_f32 v112, v108, v109
	s_waitcnt lgkmcnt(0)
	v_cvt_pk_bf16_f32 v113, v110, v111
	v_cvt_pk_bf16_f32 v114, v104, v105
	v_cvt_pk_bf16_f32 v115, v106, v107
	v_lshl_add_u64 v[116:117], v[160:161], 1, v[116:117]
	v_pk_add_f32 v[102:103], v[102:103], v[134:135]
	v_pk_add_f32 v[100:101], v[100:101], v[132:133]
	v_pk_add_f32 v[98:99], v[98:99], v[130:131]
	v_pk_add_f32 v[96:97], v[96:97], v[128:129]
	global_store_dwordx4 v[116:117], v[112:115], off sc0 sc1
	s_and_b64 vcc, exec, s[6:7]
	s_nop 0
	v_cvt_pk_bf16_f32 v112, v100, v101
	v_cvt_pk_bf16_f32 v113, v102, v103
	v_cvt_pk_bf16_f32 v114, v96, v97
	v_cvt_pk_bf16_f32 v115, v98, v99
	global_store_dwordx4 v[116:117], v[112:115], off offset:256 sc0 sc1
	s_cbranch_vccnz .LBB0_601
	v_mul_f32_e32 v99, v99, v99
	v_fmac_f32_e32 v99, v98, v98
	v_mul_f32_e32 v98, v101, v101
	v_mul_f32_e32 v107, v107, v107
	v_fmac_f32_e32 v98, v100, v100
	v_mul_f32_e32 v100, v103, v103
	v_fmac_f32_e32 v107, v106, v106
	v_mul_f32_e32 v106, v109, v109
	v_fmac_f32_e32 v100, v102, v102
	v_mul_f32_e32 v97, v97, v97
	v_fmac_f32_e32 v106, v108, v108
	v_mul_f32_e32 v108, v111, v111
	v_add_f32_e32 v98, v98, v100
	v_fmac_f32_e32 v97, v96, v96
	v_fmac_f32_e32 v108, v110, v110
	v_mul_f32_e32 v105, v105, v105
	v_add_f32_e32 v96, v98, v97
	v_and_b32_e32 v98, 64, v174
	v_add_f32_e32 v106, v106, v108
	v_fmac_f32_e32 v105, v104, v104
	v_xor_b32_e32 v97, 16, v174
	v_add_u32_e32 v98, 64, v98
	v_add_f32_e32 v104, v106, v105
	v_cmp_lt_i32_e32 vcc, v97, v98
	v_add_f32_e32 v104, v107, v104
	v_add_f32_e32 v96, v99, v96
	v_cndmask_b32_e32 v97, v174, v97, vcc
	v_add_f32_e32 v96, v104, v96
	v_lshlrev_b32_e32 v97, 2, v97
	ds_bpermute_b32 v97, v97, v96
	s_waitcnt lgkmcnt(0)
	v_add_f32_e32 v96, v96, v97
	v_xor_b32_e32 v97, 32, v174
	v_cmp_lt_i32_e32 vcc, v97, v98
	s_nop 1
	v_cndmask_b32_e32 v97, v174, v97, vcc
	v_lshlrev_b32_e32 v97, 2, v97
	ds_bpermute_b32 v97, v97, v96
	s_and_saveexec_b64 s[28:29], s[0:1]
	s_cbranch_execz .LBB0_600
	v_lshlrev_b64 v[98:99], 7, v[166:167]
	v_lshl_add_u64 v[98:99], s[24:25], 0, v[98:99]
	v_lshl_add_u64 v[98:99], s[26:27], 2, v[98:99]
	s_lshl_b32 s8, s41, 2
	v_lshl_add_u64 v[98:99], v[98:99], 0, s[8:9]
	s_waitcnt lgkmcnt(0)
	v_add_f32_e32 v96, v96, v97
	global_store_dword v[98:99], v96, off

;     __device__ __forceinline__ void operator()(const f32x4 (&acc)[2][2][4][2], const Unit& u, int wr, int wc, int fr, int fq) const {
;     ...
;                 for (int m = 0; m < 4; m += 2) {
;                     f32x4 bs[2][2][2];
; #pragma unroll
;                     for (int mm = 0; mm < 2; ++mm) { const size_t off = (size_t)(row0 + ai * HALF + (m + mm) * 16) * DM + col0;
; #pragma unroll
;                         for (int bj = 0; bj < 2; ++bj)
; #pragma unroll
;                             for (int n = 0; n < 2; ++n) bs[mm][bj][n] = *(const f32x4*)(basef + off + bj * HALF + n * 4); }
; #pragma unroll
;                     for (int mm = 0; mm < 2; ++mm) { const size_t off = (size_t)(row0 + ai * HALF + (m + mm) * 16) * DM + col0;
;                         float ss = 0.f;
; #pragma unroll
;                         for (int bj = 0; bj < 2; ++bj) { const f32x4 v0 = bs[mm][bj][0] + acc[ai][bj][m + mm][0], v1 = bs[mm][bj][1] + acc[ai][bj][m + mm][1];
;                             ss += (v0[0] * v0[0] + v0[1] * v0[1]) + (v0[2] * v0[2] + v0[3] * v0[3]) + (v1[0] * v1[0] + v1[1] * v1[1]) + (v1[2] * v1[2] + v1[3] * v1[3]);
;                             u32x4 w; w.x = pk2(v0[0], v0[1]); w.y = pk2(v0[2], v0[3]); w.z = pk2(v1[0], v1[1]); w.w = pk2(v1[2], v1[3]);
;                             *(u32x4*)(out + off + bj * HALF) = w; }
;                         if (ssqp) { ss += __shfl_xor(ss, 16); ss += __shfl_xor(ss, 32); if (fq == 0) ssqp[(size_t)(row0 + ai * HALF + (m + mm) * 16) * 32 + u.pn * 4 + wc] = ss; } }
.LBB0_601:
	s_nop 0
	v_or_b32_e32 v114, 32, v162
	v_ashrrev_i32_e32 v115, 31, v114
	s_waitcnt lgkmcnt(0)
	v_lshlrev_b64 v[96:97], 13, v[114:115]
	v_or_b32_e32 v112, 48, v162
	v_lshl_add_u64 v[96:97], v[164:165], 0, v[96:97]
	v_ashrrev_i32_e32 v113, 31, v112
	global_load_dwordx4 v[116:119], v[96:97], off
	global_load_dwordx4 v[120:123], v[96:97], off offset:16
	global_load_dwordx4 v[124:127], v[96:97], off offset:512
	global_load_dwordx4 v[128:131], v[96:97], off offset:528
	v_lshlrev_b64 v[96:97], 13, v[112:113]
	v_lshl_add_u64 v[100:101], v[164:165], 0, v[96:97]
	global_load_dwordx4 v[104:107], v[100:101], off offset:16
	global_load_dwordx4 v[108:111], v[100:101], off
	global_load_dwordx4 v[96:99], v[100:101], off offset:528
	s_nop 0
	global_load_dwordx4 v[100:103], v[100:101], off offset:512
	v_lshlrev_b64 v[132:133], 12, v[114:115]
	v_lshl_add_u64 v[132:133], s[22:23], 0, v[132:133]
	s_and_b64 vcc, exec, s[6:7]
	v_lshl_add_u64 v[132:133], v[160:161], 1, v[132:133]
	s_waitcnt vmcnt(7)
	v_pk_add_f32 v[94:95], v[94:95], v[118:119]
	v_pk_add_f32 v[92:93], v[92:93], v[116:117]
	s_waitcnt vmcnt(6)
	v_pk_add_f32 v[90:91], v[90:91], v[122:123]
	v_pk_add_f32 v[88:89], v[88:89], v[120:121]
	s_waitcnt vmcnt(5)
	v_pk_add_f32 v[86:87], v[86:87], v[126:127]
	v_pk_add_f32 v[84:85], v[84:85], v[124:125]
	s_waitcnt vmcnt(4)
	v_pk_add_f32 v[82:83], v[82:83], v[130:131]
	v_pk_add_f32 v[80:81], v[80:81], v[128:129]
	v_cvt_pk_bf16_f32 v116, v92, v93
	v_cvt_pk_bf16_f32 v117, v94, v95
	v_cvt_pk_bf16_f32 v118, v88, v89
	v_cvt_pk_bf16_f32 v119, v90, v91
	v_cvt_pk_bf16_f32 v120, v84, v85
	v_cvt_pk_bf16_f32 v121, v86, v87
	v_cvt_pk_bf16_f32 v122, v80, v81
	v_cvt_pk_bf16_f32 v123, v82, v83
	global_store_dwordx4 v[132:133], v[116:119], off sc0 sc1
	global_store_dwordx4 v[132:133], v[120:123], off offset:256 sc0 sc1
	s_cbranch_vccnz .LBB0_605
	v_mul_f32_e32 v83, v83, v83
	v_fmac_f32_e32 v83, v82, v82
	v_mul_f32_e32 v82, v85, v85
	v_mul_f32_e32 v91, v91, v91
	v_fmac_f32_e32 v82, v84, v84
	v_mul_f32_e32 v84, v87, v87
	v_fmac_f32_e32 v91, v90, v90
	v_mul_f32_e32 v90, v93, v93
	v_fmac_f32_e32 v84, v86, v86
	v_mul_f32_e32 v81, v81, v81
	v_fmac_f32_e32 v90, v92, v92
	v_mul_f32_e32 v92, v95, v95
	v_add_f32_e32 v82, v82, v84
	v_fmac_f32_e32 v81, v80, v80
	v_fmac_f32_e32 v92, v94, v94
	v_mul_f32_e32 v89, v89, v89
	v_add_f32_e32 v80, v82, v81
	v_and_b32_e32 v82, 64, v174
	v_add_f32_e32 v90, v90, v92
	v_fmac_f32_e32 v89, v88, v88
	v_xor_b32_e32 v81, 16, v174
	v_add_u32_e32 v82, 64, v82
	v_add_f32_e32 v88, v90, v89
	v_cmp_lt_i32_e32 vcc, v81, v82
	v_add_f32_e32 v88, v91, v88
	v_add_f32_e32 v80, v83, v80
	v_cndmask_b32_e32 v81, v174, v81, vcc
	v_add_f32_e32 v80, v88, v80
	v_lshlrev_b32_e32 v81, 2, v81
	ds_bpermute_b32 v81, v81, v80
	s_waitcnt lgkmcnt(0)
	v_add_f32_e32 v80, v80, v81
	v_xor_b32_e32 v81, 32, v174
	v_cmp_lt_i32_e32 vcc, v81, v82
	s_nop 1
	v_cndmask_b32_e32 v81, v174, v81, vcc
	v_lshlrev_b32_e32 v81, 2, v81
	ds_bpermute_b32 v81, v81, v80
	s_and_saveexec_b64 s[28:29], s[0:1]
	s_cbranch_execz .LBB0_604
	v_lshlrev_b64 v[82:83], 7, v[114:115]
	v_lshl_add_u64 v[82:83], s[24:25], 0, v[82:83]
	v_lshl_add_u64 v[82:83], s[26:27], 2, v[82:83]
	s_lshl_b32 s8, s41, 2
	v_lshl_add_u64 v[82:83], v[82:83], 0, s[8:9]
	s_waitcnt lgkmcnt(0)
	v_add_f32_e32 v80, v80, v81
	global_store_dword v[82:83], v80, off

;     __device__ __forceinline__ void operator()(const f32x4 (&acc)[2][2][4][2], const Unit& u, int wr, int wc, int fr, int fq) const {
;     ...
;                     for (int mm = 0; mm < 2; ++mm) { const size_t off = (size_t)(row0 + ai * HALF + (m + mm) * 16) * DM + col0;
;                         float ss = 0.f;
; #pragma unroll
;                         for (int bj = 0; bj < 2; ++bj) { const f32x4 v0 = bs[mm][bj][0] + acc[ai][bj][m + mm][0], v1 = bs[mm][bj][1] + acc[ai][bj][m + mm][1];
;                             ss += (v0[0] * v0[0] + v0[1] * v0[1]) + (v0[2] * v0[2] + v0[3] * v0[3]) + (v1[0] * v1[0] + v1[1] * v1[1]) + (v1[2] * v1[2] + v1[3] * v1[3]);
;                             u32x4 w; w.x = pk2(v0[0], v0[1]); w.y = pk2(v0[2], v0[3]); w.z = pk2(v1[0], v1[1]); w.w = pk2(v1[2], v1[3]);
;                             *(u32x4*)(out + off + bj * HALF) = w; }
;                         if (ssqp) { ss += __shfl_xor(ss, 16); ss += __shfl_xor(ss, 32); if (fq == 0) ssqp[(size_t)(row0 + ai * HALF + (m + mm) * 16) * 32 + u.pn * 4 + wc] = ss; } }
.LBB0_605:
	v_lshlrev_b64 v[84:85], 12, v[112:113]
	s_waitcnt vmcnt(4)
	v_pk_add_f32 v[78:79], v[78:79], v[110:111]
	v_pk_add_f32 v[76:77], v[76:77], v[108:109]
	v_pk_add_f32 v[74:75], v[74:75], v[106:107]
	v_pk_add_f32 v[72:73], v[72:73], v[104:105]
	v_lshl_add_u64 v[84:85], s[22:23], 0, v[84:85]
	v_cvt_pk_bf16_f32 v80, v76, v77
	s_waitcnt lgkmcnt(0)
	v_cvt_pk_bf16_f32 v81, v78, v79
	v_cvt_pk_bf16_f32 v82, v72, v73
	v_cvt_pk_bf16_f32 v83, v74, v75
	v_lshl_add_u64 v[84:85], v[160:161], 1, v[84:85]
	s_waitcnt vmcnt(2)
	v_pk_add_f32 v[70:71], v[70:71], v[102:103]
	v_pk_add_f32 v[68:69], v[68:69], v[100:101]
	v_pk_add_f32 v[66:67], v[66:67], v[98:99]
	v_pk_add_f32 v[64:65], v[64:65], v[96:97]
	global_store_dwordx4 v[84:85], v[80:83], off sc0 sc1
	s_and_b64 vcc, exec, s[6:7]
	s_nop 0
	v_cvt_pk_bf16_f32 v80, v68, v69
	v_cvt_pk_bf16_f32 v81, v70, v71
	v_cvt_pk_bf16_f32 v82, v64, v65
	v_cvt_pk_bf16_f32 v83, v66, v67
	global_store_dwordx4 v[84:85], v[80:83], off offset:256 sc0 sc1
	s_cbranch_vccnz .LBB0_609
	v_mul_f32_e32 v67, v67, v67
	v_fmac_f32_e32 v67, v66, v66
	v_mul_f32_e32 v66, v69, v69
	v_mul_f32_e32 v75, v75, v75
	v_fmac_f32_e32 v66, v68, v68
	v_mul_f32_e32 v68, v71, v71
	v_fmac_f32_e32 v75, v74, v74
	v_mul_f32_e32 v74, v77, v77
	v_fmac_f32_e32 v68, v70, v70
	v_mul_f32_e32 v65, v65, v65
	v_fmac_f32_e32 v74, v76, v76
	v_mul_f32_e32 v76, v79, v79
	v_add_f32_e32 v66, v66, v68
	v_fmac_f32_e32 v65, v64, v64
	v_fmac_f32_e32 v76, v78, v78
	v_mul_f32_e32 v73, v73, v73
	v_add_f32_e32 v64, v66, v65
	v_and_b32_e32 v66, 64, v174
	v_add_f32_e32 v74, v74, v76
	v_fmac_f32_e32 v73, v72, v72
	v_xor_b32_e32 v65, 16, v174
	v_add_u32_e32 v66, 64, v66
	v_add_f32_e32 v72, v74, v73
	v_cmp_lt_i32_e32 vcc, v65, v66
	v_add_f32_e32 v72, v75, v72
	v_add_f32_e32 v64, v67, v64
	v_cndmask_b32_e32 v65, v174, v65, vcc
	v_add_f32_e32 v64, v72, v64
	v_lshlrev_b32_e32 v65, 2, v65
	ds_bpermute_b32 v65, v65, v64
	s_waitcnt lgkmcnt(0)
	v_add_f32_e32 v64, v64, v65
	v_xor_b32_e32 v65, 32, v174
	v_cmp_lt_i32_e32 vcc, v65, v66
	s_nop 1
	v_cndmask_b32_e32 v65, v174, v65, vcc
	v_lshlrev_b32_e32 v65, 2, v65
	ds_bpermute_b32 v65, v65, v64
	s_and_saveexec_b64 s[28:29], s[0:1]
	s_cbranch_execz .LBB0_608
	v_lshlrev_b64 v[66:67], 7, v[112:113]
	v_lshl_add_u64 v[66:67], s[24:25], 0, v[66:67]
	v_lshl_add_u64 v[66:67], s[26:27], 2, v[66:67]
	s_lshl_b32 s8, s41, 2
	v_lshl_add_u64 v[66:67], v[66:67], 0, s[8:9]
	s_waitcnt lgkmcnt(0)
	v_add_f32_e32 v64, v64, v65
	global_store_dword v[66:67], v64, off

;     __device__ __forceinline__ void operator()(const f32x4 (&acc)[2][2][4][2], const Unit& u, int wr, int wc, int fr, int fq) const {
;     ...
;                 for (int m = 0; m < 4; m += 2) {
;                     f32x4 bs[2][2][2];
; #pragma unroll
;                     for (int mm = 0; mm < 2; ++mm) { const size_t off = (size_t)(row0 + ai * HALF + (m + mm) * 16) * DM + col0;
; #pragma unroll
;                         for (int bj = 0; bj < 2; ++bj)
; #pragma unroll
;                             for (int n = 0; n < 2; ++n) bs[mm][bj][n] = *(const f32x4*)(basef + off + bj * HALF + n * 4); }
; #pragma unroll
;                     for (int mm = 0; mm < 2; ++mm) { const size_t off = (size_t)(row0 + ai * HALF + (m + mm) * 16) * DM + col0;
;                         float ss = 0.f;
; #pragma unroll
;                         for (int bj = 0; bj < 2; ++bj) { const f32x4 v0 = bs[mm][bj][0] + acc[ai][bj][m + mm][0], v1 = bs[mm][bj][1] + acc[ai][bj][m + mm][1];
;                             ss += (v0[0] * v0[0] + v0[1] * v0[1]) + (v0[2] * v0[2] + v0[3] * v0[3]) + (v1[0] * v1[0] + v1[1] * v1[1]) + (v1[2] * v1[2] + v1[3] * v1[3]);
;                             u32x4 w; w.x = pk2(v0[0], v0[1]); w.y = pk2(v0[2], v0[3]); w.z = pk2(v1[0], v1[1]); w.w = pk2(v1[2], v1[3]);
;                             *(u32x4*)(out + off + bj * HALF) = w; }
;                         if (ssqp) { ss += __shfl_xor(ss, 16); ss += __shfl_xor(ss, 32); if (fq == 0) ssqp[(size_t)(row0 + ai * HALF + (m + mm) * 16) * 32 + u.pn * 4 + wc] = ss; } }
.LBB0_609:
	s_nop 0
	v_add_u32_e32 v82, 0x80, v162
	v_ashrrev_i32_e32 v83, 31, v82
	s_waitcnt lgkmcnt(0)
	v_lshlrev_b64 v[64:65], 13, v[82:83]
	v_add_u32_e32 v80, 0x90, v162
	v_lshl_add_u64 v[64:65], v[164:165], 0, v[64:65]
	v_ashrrev_i32_e32 v81, 31, v80
	global_load_dwordx4 v[84:87], v[64:65], off
	global_load_dwordx4 v[88:91], v[64:65], off offset:16
	global_load_dwordx4 v[92:95], v[64:65], off offset:512
	global_load_dwordx4 v[96:99], v[64:65], off offset:528
	v_lshlrev_b64 v[64:65], 13, v[80:81]
	v_lshl_add_u64 v[68:69], v[164:165], 0, v[64:65]
	global_load_dwordx4 v[72:75], v[68:69], off offset:16
	global_load_dwordx4 v[76:79], v[68:69], off
	global_load_dwordx4 v[64:67], v[68:69], off offset:528
	s_nop 0
	global_load_dwordx4 v[68:71], v[68:69], off offset:512
	v_lshlrev_b64 v[100:101], 12, v[82:83]
	v_lshl_add_u64 v[100:101], s[22:23], 0, v[100:101]
	s_and_b64 vcc, exec, s[6:7]
	v_lshl_add_u64 v[100:101], v[160:161], 1, v[100:101]
	s_waitcnt vmcnt(7)
	v_pk_add_f32 v[62:63], v[62:63], v[86:87]
	v_pk_add_f32 v[60:61], v[60:61], v[84:85]
	s_waitcnt vmcnt(6)
	v_pk_add_f32 v[58:59], v[58:59], v[90:91]
	v_pk_add_f32 v[56:57], v[56:57], v[88:89]
	s_waitcnt vmcnt(5)
	v_pk_add_f32 v[54:55], v[54:55], v[94:95]
	v_pk_add_f32 v[52:53], v[52:53], v[92:93]
	s_waitcnt vmcnt(4)
	v_pk_add_f32 v[50:51], v[50:51], v[98:99]
	v_pk_add_f32 v[48:49], v[48:49], v[96:97]
	v_cvt_pk_bf16_f32 v84, v60, v61
	v_cvt_pk_bf16_f32 v85, v62, v63
	v_cvt_pk_bf16_f32 v86, v56, v57
	v_cvt_pk_bf16_f32 v87, v58, v59
	v_cvt_pk_bf16_f32 v88, v52, v53
	v_cvt_pk_bf16_f32 v89, v54, v55
	v_cvt_pk_bf16_f32 v90, v48, v49
	v_cvt_pk_bf16_f32 v91, v50, v51
	global_store_dwordx4 v[100:101], v[84:87], off sc0 sc1
	global_store_dwordx4 v[100:101], v[88:91], off offset:256 sc0 sc1
	s_cbranch_vccnz .LBB0_613
	v_mul_f32_e32 v51, v51, v51
	v_fmac_f32_e32 v51, v50, v50
	v_mul_f32_e32 v50, v53, v53
	v_mul_f32_e32 v59, v59, v59
	v_fmac_f32_e32 v50, v52, v52
	v_mul_f32_e32 v52, v55, v55
	v_fmac_f32_e32 v59, v58, v58
	v_mul_f32_e32 v58, v61, v61
	v_fmac_f32_e32 v52, v54, v54
	v_mul_f32_e32 v49, v49, v49
	v_fmac_f32_e32 v58, v60, v60
	v_mul_f32_e32 v60, v63, v63
	v_add_f32_e32 v50, v50, v52
	v_fmac_f32_e32 v49, v48, v48
	v_fmac_f32_e32 v60, v62, v62
	v_mul_f32_e32 v57, v57, v57
	v_add_f32_e32 v48, v50, v49
	v_and_b32_e32 v50, 64, v174
	v_add_f32_e32 v58, v58, v60
	v_fmac_f32_e32 v57, v56, v56
	v_xor_b32_e32 v49, 16, v174
	v_add_u32_e32 v50, 64, v50
	v_add_f32_e32 v56, v58, v57
	v_cmp_lt_i32_e32 vcc, v49, v50
	v_add_f32_e32 v56, v59, v56
	v_add_f32_e32 v48, v51, v48
	v_cndmask_b32_e32 v49, v174, v49, vcc
	v_add_f32_e32 v48, v56, v48
	v_lshlrev_b32_e32 v49, 2, v49
	ds_bpermute_b32 v49, v49, v48
	s_waitcnt lgkmcnt(0)
	v_add_f32_e32 v48, v48, v49
	v_xor_b32_e32 v49, 32, v174
	v_cmp_lt_i32_e32 vcc, v49, v50
	s_nop 1
	v_cndmask_b32_e32 v49, v174, v49, vcc
	v_lshlrev_b32_e32 v49, 2, v49
	ds_bpermute_b32 v49, v49, v48
	s_and_saveexec_b64 s[28:29], s[0:1]
	s_cbranch_execz .LBB0_612
	v_lshlrev_b64 v[50:51], 7, v[82:83]
	v_lshl_add_u64 v[50:51], s[24:25], 0, v[50:51]
	v_lshl_add_u64 v[50:51], s[26:27], 2, v[50:51]
	s_lshl_b32 s8, s41, 2
	v_lshl_add_u64 v[50:51], v[50:51], 0, s[8:9]
	s_waitcnt lgkmcnt(0)
	v_add_f32_e32 v48, v48, v49
	global_store_dword v[50:51], v48, off

;     __device__ __forceinline__ void operator()(const f32x4 (&acc)[2][2][4][2], const Unit& u, int wr, int wc, int fr, int fq) const {
;     ...
;                     for (int mm = 0; mm < 2; ++mm) { const size_t off = (size_t)(row0 + ai * HALF + (m + mm) * 16) * DM + col0;
;                         float ss = 0.f;
; #pragma unroll
;                         for (int bj = 0; bj < 2; ++bj) { const f32x4 v0 = bs[mm][bj][0] + acc[ai][bj][m + mm][0], v1 = bs[mm][bj][1] + acc[ai][bj][m + mm][1];
;                             ss += (v0[0] * v0[0] + v0[1] * v0[1]) + (v0[2] * v0[2] + v0[3] * v0[3]) + (v1[0] * v1[0] + v1[1] * v1[1]) + (v1[2] * v1[2] + v1[3] * v1[3]);
;                             u32x4 w; w.x = pk2(v0[0], v0[1]); w.y = pk2(v0[2], v0[3]); w.z = pk2(v1[0], v1[1]); w.w = pk2(v1[2], v1[3]);
;                             *(u32x4*)(out + off + bj * HALF) = w; }
;                         if (ssqp) { ss += __shfl_xor(ss, 16); ss += __shfl_xor(ss, 32); if (fq == 0) ssqp[(size_t)(row0 + ai * HALF + (m + mm) * 16) * 32 + u.pn * 4 + wc] = ss; } }
.LBB0_613:
	v_lshlrev_b64 v[52:53], 12, v[80:81]
	s_waitcnt vmcnt(4)
	v_pk_add_f32 v[46:47], v[46:47], v[78:79]
	v_pk_add_f32 v[44:45], v[44:45], v[76:77]
	v_pk_add_f32 v[42:43], v[42:43], v[74:75]
	v_pk_add_f32 v[40:41], v[40:41], v[72:73]
	v_lshl_add_u64 v[52:53], s[22:23], 0, v[52:53]
	v_cvt_pk_bf16_f32 v48, v44, v45
	s_waitcnt lgkmcnt(0)
	v_cvt_pk_bf16_f32 v49, v46, v47
	v_cvt_pk_bf16_f32 v50, v40, v41
	v_cvt_pk_bf16_f32 v51, v42, v43
	v_lshl_add_u64 v[52:53], v[160:161], 1, v[52:53]
	s_waitcnt vmcnt(2)
	v_pk_add_f32 v[38:39], v[38:39], v[70:71]
	v_pk_add_f32 v[36:37], v[36:37], v[68:69]
	v_pk_add_f32 v[34:35], v[34:35], v[66:67]
	v_pk_add_f32 v[32:33], v[32:33], v[64:65]
	global_store_dwordx4 v[52:53], v[48:51], off sc0 sc1
	s_and_b64 vcc, exec, s[6:7]
	s_nop 0
	v_cvt_pk_bf16_f32 v48, v36, v37
	v_cvt_pk_bf16_f32 v49, v38, v39
	v_cvt_pk_bf16_f32 v50, v32, v33
	v_cvt_pk_bf16_f32 v51, v34, v35
	global_store_dwordx4 v[52:53], v[48:51], off offset:256 sc0 sc1
	s_cbranch_vccnz .LBB0_617
	v_mul_f32_e32 v35, v35, v35
	v_fmac_f32_e32 v35, v34, v34
	v_mul_f32_e32 v34, v37, v37
	v_mul_f32_e32 v43, v43, v43
	v_fmac_f32_e32 v34, v36, v36
	v_mul_f32_e32 v36, v39, v39
	v_fmac_f32_e32 v43, v42, v42
	v_mul_f32_e32 v42, v45, v45
	v_fmac_f32_e32 v36, v38, v38
	v_mul_f32_e32 v33, v33, v33
	v_fmac_f32_e32 v42, v44, v44
	v_mul_f32_e32 v44, v47, v47
	v_add_f32_e32 v34, v34, v36
	v_fmac_f32_e32 v33, v32, v32
	v_fmac_f32_e32 v44, v46, v46
	v_mul_f32_e32 v41, v41, v41
	v_add_f32_e32 v32, v34, v33
	v_and_b32_e32 v34, 64, v174
	v_add_f32_e32 v42, v42, v44
	v_fmac_f32_e32 v41, v40, v40
	v_xor_b32_e32 v33, 16, v174
	v_add_u32_e32 v34, 64, v34
	v_add_f32_e32 v40, v42, v41
	v_cmp_lt_i32_e32 vcc, v33, v34
	v_add_f32_e32 v40, v43, v40
	v_add_f32_e32 v32, v35, v32
	v_cndmask_b32_e32 v33, v174, v33, vcc
	v_add_f32_e32 v32, v40, v32
	v_lshlrev_b32_e32 v33, 2, v33
	ds_bpermute_b32 v33, v33, v32
	s_waitcnt lgkmcnt(0)
	v_add_f32_e32 v32, v32, v33
	v_xor_b32_e32 v33, 32, v174
	v_cmp_lt_i32_e32 vcc, v33, v34
	s_nop 1
	v_cndmask_b32_e32 v33, v174, v33, vcc
	v_lshlrev_b32_e32 v33, 2, v33
	ds_bpermute_b32 v33, v33, v32
	s_and_saveexec_b64 s[28:29], s[0:1]
	s_cbranch_execz .LBB0_616
	v_lshlrev_b64 v[34:35], 7, v[80:81]
	v_lshl_add_u64 v[34:35], s[24:25], 0, v[34:35]
	v_lshl_add_u64 v[34:35], s[26:27], 2, v[34:35]
	s_lshl_b32 s8, s41, 2
	v_lshl_add_u64 v[34:35], v[34:35], 0, s[8:9]
	s_waitcnt lgkmcnt(0)
	v_add_f32_e32 v32, v32, v33
	global_store_dword v[34:35], v32, off

;     __device__ __forceinline__ void operator()(const f32x4 (&acc)[2][2][4][2], const Unit& u, int wr, int wc, int fr, int fq) const {
;     ...
;                 for (int m = 0; m < 4; m += 2) {
;                     f32x4 bs[2][2][2];
; #pragma unroll
;                     for (int mm = 0; mm < 2; ++mm) { const size_t off = (size_t)(row0 + ai * HALF + (m + mm) * 16) * DM + col0;
; #pragma unroll
;                         for (int bj = 0; bj < 2; ++bj)
; #pragma unroll
;                             for (int n = 0; n < 2; ++n) bs[mm][bj][n] = *(const f32x4*)(basef + off + bj * HALF + n * 4); }
; #pragma unroll
;                     for (int mm = 0; mm < 2; ++mm) { const size_t off = (size_t)(row0 + ai * HALF + (m + mm) * 16) * DM + col0;
;                         float ss = 0.f;
; #pragma unroll
;                         for (int bj = 0; bj < 2; ++bj) { const f32x4 v0 = bs[mm][bj][0] + acc[ai][bj][m + mm][0], v1 = bs[mm][bj][1] + acc[ai][bj][m + mm][1];
;                             ss += (v0[0] * v0[0] + v0[1] * v0[1]) + (v0[2] * v0[2] + v0[3] * v0[3]) + (v1[0] * v1[0] + v1[1] * v1[1]) + (v1[2] * v1[2] + v1[3] * v1[3]);
;                             u32x4 w; w.x = pk2(v0[0], v0[1]); w.y = pk2(v0[2], v0[3]); w.z = pk2(v1[0], v1[1]); w.w = pk2(v1[2], v1[3]);
;                             *(u32x4*)(out + off + bj * HALF) = w; }
;                         if (ssqp) { ss += __shfl_xor(ss, 16); ss += __shfl_xor(ss, 32); if (fq == 0) ssqp[(size_t)(row0 + ai * HALF + (m + mm) * 16) * 32 + u.pn * 4 + wc] = ss; } }
.LBB0_617:
	s_nop 0
	v_add_u32_e32 v50, 0xa0, v162
	v_ashrrev_i32_e32 v51, 31, v50
	s_waitcnt lgkmcnt(0)
	v_lshlrev_b64 v[32:33], 13, v[50:51]
	v_add_u32_e32 v48, 0xb0, v162
	v_lshl_add_u64 v[32:33], v[164:165], 0, v[32:33]
	v_ashrrev_i32_e32 v49, 31, v48
	global_load_dwordx4 v[52:55], v[32:33], off
	global_load_dwordx4 v[56:59], v[32:33], off offset:16
	global_load_dwordx4 v[60:63], v[32:33], off offset:512
	global_load_dwordx4 v[64:67], v[32:33], off offset:528
	v_lshlrev_b64 v[32:33], 13, v[48:49]
	v_lshl_add_u64 v[36:37], v[164:165], 0, v[32:33]
	global_load_dwordx4 v[40:43], v[36:37], off offset:16
	global_load_dwordx4 v[44:47], v[36:37], off
	global_load_dwordx4 v[32:35], v[36:37], off offset:528
	s_nop 0
	global_load_dwordx4 v[36:39], v[36:37], off offset:512
	v_lshlrev_b64 v[68:69], 12, v[50:51]
	v_lshl_add_u64 v[68:69], s[22:23], 0, v[68:69]
	s_and_b64 vcc, exec, s[6:7]
	v_lshl_add_u64 v[68:69], v[160:161], 1, v[68:69]
	s_waitcnt vmcnt(7)
	v_pk_add_f32 v[30:31], v[30:31], v[54:55]
	v_pk_add_f32 v[28:29], v[28:29], v[52:53]
	s_waitcnt vmcnt(6)
	v_pk_add_f32 v[26:27], v[26:27], v[58:59]
	v_pk_add_f32 v[24:25], v[24:25], v[56:57]
	s_waitcnt vmcnt(5)
	v_pk_add_f32 v[22:23], v[22:23], v[62:63]
	v_pk_add_f32 v[20:21], v[20:21], v[60:61]
	s_waitcnt vmcnt(4)
	v_pk_add_f32 v[18:19], v[18:19], v[66:67]
	v_pk_add_f32 v[16:17], v[16:17], v[64:65]
	v_cvt_pk_bf16_f32 v52, v28, v29
	v_cvt_pk_bf16_f32 v53, v30, v31
	v_cvt_pk_bf16_f32 v54, v24, v25
	v_cvt_pk_bf16_f32 v55, v26, v27
	v_cvt_pk_bf16_f32 v56, v20, v21
	v_cvt_pk_bf16_f32 v57, v22, v23
	v_cvt_pk_bf16_f32 v58, v16, v17
	v_cvt_pk_bf16_f32 v59, v18, v19
	global_store_dwordx4 v[68:69], v[52:55], off sc0 sc1
	global_store_dwordx4 v[68:69], v[56:59], off offset:256 sc0 sc1
	s_cbranch_vccnz .LBB0_621
	v_mul_f32_e32 v19, v19, v19
	v_fmac_f32_e32 v19, v18, v18
	v_mul_f32_e32 v18, v21, v21
	v_mul_f32_e32 v27, v27, v27
	v_fmac_f32_e32 v18, v20, v20
	v_mul_f32_e32 v20, v23, v23
	v_fmac_f32_e32 v27, v26, v26
	v_mul_f32_e32 v26, v29, v29
	v_fmac_f32_e32 v20, v22, v22
	v_mul_f32_e32 v17, v17, v17
	v_fmac_f32_e32 v26, v28, v28
	v_mul_f32_e32 v28, v31, v31
	v_add_f32_e32 v18, v18, v20
	v_fmac_f32_e32 v17, v16, v16
	v_fmac_f32_e32 v28, v30, v30
	v_mul_f32_e32 v25, v25, v25
	v_add_f32_e32 v16, v18, v17
	v_and_b32_e32 v18, 64, v174
	v_add_f32_e32 v26, v26, v28
	v_fmac_f32_e32 v25, v24, v24
	v_xor_b32_e32 v17, 16, v174
	v_add_u32_e32 v18, 64, v18
	v_add_f32_e32 v24, v26, v25
	v_cmp_lt_i32_e32 vcc, v17, v18
	v_add_f32_e32 v24, v27, v24
	v_add_f32_e32 v16, v19, v16
	v_cndmask_b32_e32 v17, v174, v17, vcc
	v_add_f32_e32 v16, v24, v16
	v_lshlrev_b32_e32 v17, 2, v17
	ds_bpermute_b32 v17, v17, v16
	s_waitcnt lgkmcnt(0)
	v_add_f32_e32 v16, v16, v17
	v_xor_b32_e32 v17, 32, v174
	v_cmp_lt_i32_e32 vcc, v17, v18
	s_nop 1
	v_cndmask_b32_e32 v17, v174, v17, vcc
	v_lshlrev_b32_e32 v17, 2, v17
	ds_bpermute_b32 v17, v17, v16
	s_and_saveexec_b64 s[28:29], s[0:1]
	s_cbranch_execz .LBB0_620
	v_lshlrev_b64 v[18:19], 7, v[50:51]
	v_lshl_add_u64 v[18:19], s[24:25], 0, v[18:19]
	v_lshl_add_u64 v[18:19], s[26:27], 2, v[18:19]
	s_lshl_b32 s8, s41, 2
	v_lshl_add_u64 v[18:19], v[18:19], 0, s[8:9]
	s_waitcnt lgkmcnt(0)
	v_add_f32_e32 v16, v16, v17
	global_store_dword v[18:19], v16, off

;     __device__ __forceinline__ void operator()(const f32x4 (&acc)[2][2][4][2], const Unit& u, int wr, int wc, int fr, int fq) const {
;     ...
;                     for (int mm = 0; mm < 2; ++mm) { const size_t off = (size_t)(row0 + ai * HALF + (m + mm) * 16) * DM + col0;
;                         float ss = 0.f;
; #pragma unroll
;                         for (int bj = 0; bj < 2; ++bj) { const f32x4 v0 = bs[mm][bj][0] + acc[ai][bj][m + mm][0], v1 = bs[mm][bj][1] + acc[ai][bj][m + mm][1];
;                             ss += (v0[0] * v0[0] + v0[1] * v0[1]) + (v0[2] * v0[2] + v0[3] * v0[3]) + (v1[0] * v1[0] + v1[1] * v1[1]) + (v1[2] * v1[2] + v1[3] * v1[3]);
;                             u32x4 w; w.x = pk2(v0[0], v0[1]); w.y = pk2(v0[2], v0[3]); w.z = pk2(v1[0], v1[1]); w.w = pk2(v1[2], v1[3]);
;                             *(u32x4*)(out + off + bj * HALF) = w; }
;                         if (ssqp) { ss += __shfl_xor(ss, 16); ss += __shfl_xor(ss, 32); if (fq == 0) ssqp[(size_t)(row0 + ai * HALF + (m + mm) * 16) * 32 + u.pn * 4 + wc] = ss; } }
.LBB0_621:
	v_lshlrev_b64 v[20:21], 12, v[48:49]
	s_waitcnt vmcnt(4)
	v_pk_add_f32 v[14:15], v[14:15], v[46:47]
	v_pk_add_f32 v[12:13], v[12:13], v[44:45]
	v_pk_add_f32 v[10:11], v[10:11], v[42:43]
	v_pk_add_f32 v[8:9], v[8:9], v[40:41]
	v_lshl_add_u64 v[20:21], s[22:23], 0, v[20:21]
	v_cvt_pk_bf16_f32 v16, v12, v13
	s_waitcnt lgkmcnt(0)
	v_cvt_pk_bf16_f32 v17, v14, v15
	v_cvt_pk_bf16_f32 v18, v8, v9
	v_cvt_pk_bf16_f32 v19, v10, v11
	v_lshl_add_u64 v[20:21], v[160:161], 1, v[20:21]
	s_waitcnt vmcnt(2)
	v_pk_add_f32 v[6:7], v[6:7], v[38:39]
	v_pk_add_f32 v[4:5], v[4:5], v[36:37]
	v_pk_add_f32 v[2:3], v[2:3], v[34:35]
	v_pk_add_f32 v[0:1], v[0:1], v[32:33]
	global_store_dwordx4 v[20:21], v[16:19], off sc0 sc1
	s_and_b64 vcc, exec, s[6:7]
	s_nop 0
	v_cvt_pk_bf16_f32 v16, v4, v5
	v_cvt_pk_bf16_f32 v17, v6, v7
	v_cvt_pk_bf16_f32 v18, v0, v1
	v_cvt_pk_bf16_f32 v19, v2, v3
	global_store_dwordx4 v[20:21], v[16:19], off offset:256 sc0 sc1
	s_cbranch_vccnz .LBB0_584
	v_mul_f32_e32 v3, v3, v3
	v_fmac_f32_e32 v3, v2, v2
	v_mul_f32_e32 v2, v5, v5
	v_mul_f32_e32 v11, v11, v11
	v_fmac_f32_e32 v2, v4, v4
	v_mul_f32_e32 v4, v7, v7
	v_fmac_f32_e32 v11, v10, v10
	v_mul_f32_e32 v10, v13, v13
	v_fmac_f32_e32 v4, v6, v6
	v_mul_f32_e32 v1, v1, v1
	v_fmac_f32_e32 v10, v12, v12
	v_mul_f32_e32 v12, v15, v15
	v_add_f32_e32 v2, v2, v4
	v_fmac_f32_e32 v1, v0, v0
	v_fmac_f32_e32 v12, v14, v14
	v_mul_f32_e32 v9, v9, v9
	v_add_f32_e32 v0, v2, v1
	v_and_b32_e32 v2, 64, v174
	v_add_f32_e32 v10, v10, v12
	v_fmac_f32_e32 v9, v8, v8
	v_xor_b32_e32 v1, 16, v174
	v_add_u32_e32 v2, 64, v2
	v_add_f32_e32 v8, v10, v9
	v_cmp_lt_i32_e32 vcc, v1, v2
	v_add_f32_e32 v8, v11, v8
	v_add_f32_e32 v0, v3, v0
	v_cndmask_b32_e32 v1, v174, v1, vcc
	v_add_f32_e32 v0, v8, v0
	v_lshlrev_b32_e32 v1, 2, v1
	ds_bpermute_b32 v1, v1, v0
	s_waitcnt lgkmcnt(0)
	v_add_f32_e32 v0, v0, v1
	v_xor_b32_e32 v1, 32, v174
	v_cmp_lt_i32_e32 vcc, v1, v2
	s_nop 1
	v_cndmask_b32_e32 v1, v174, v1, vcc
	v_lshlrev_b32_e32 v1, 2, v1
	ds_bpermute_b32 v1, v1, v0
	s_and_saveexec_b64 s[6:7], s[0:1]
	s_cbranch_execz .LBB0_583
	v_lshlrev_b64 v[2:3], 7, v[48:49]
	v_lshl_add_u64 v[2:3], s[24:25], 0, v[2:3]
	v_lshl_add_u64 v[2:3], s[26:27], 2, v[2:3]
	s_lshl_b32 s8, s41, 2
	v_lshl_add_u64 v[2:3], v[2:3], 0, s[8:9]
	s_waitcnt lgkmcnt(0)
	v_add_f32_e32 v0, v0, v1
	global_store_dword v[2:3], v0, off
	s_branch .LBB0_583

; #define PG8_STAGE(bufoff, gbase, voff) do { _Pragma("unroll") for (int _i = 0; _i < 2; ++_i) \
;         __builtin_amdgcn_global_load_lds((const unsigned*)((const char*)(gbase) + (voff)[_i]), (LAS unsigned*)(lds + (bufoff) + ldsw + _i * 8192), 16, 0, 0); } while (0)
; #define PG8_LDA(dst, b, h) do { _Pragma("unroll") for (int m = 0; m < 4; ++m) _Pragma("unroll") for (int k = 0; k < 2; ++k) dst[m][k] = *(const LAS bf16x8*)(lds + PG8_SA(b, h) + aoff + m * 2048 + k * 1024); } while (0)
; #define PG8_LDB(dst, b, h) do { _Pragma("unroll") for (int n = 0; n < 2; ++n) _Pragma("unroll") for (int k = 0; k < 2; ++k) dst[n][k] = *(const LAS bf16x8*)(lds + PG8_SB(b, h) + boff + n * 2048 + k * 1024); } while (0)
; #define PG8_MMA(ai, bj, At, Bt) do { __builtin_amdgcn_s_setprio(1); _Pragma("unroll") for (int m = 0; m < 4; ++m) _Pragma("unroll") for (int n = 0; n < 2; ++n) _Pragma("unroll") for (int k = 0; k < 2; ++k) \
;         acc[ai][bj][m][n] = __builtin_amdgcn_mfma_f32_16x16x32_bf16(Bt[n][k], At[m][k], acc[ai][bj][m][n], 0, 0, 0); __builtin_amdgcn_s_setprio(0); } while (0)
; #define PG8_WAIT_V(n) asm volatile("s_waitcnt vmcnt(" #n ")" ::: "memory")
; #define PG8_WAIT_L(n) asm volatile("s_waitcnt lgkmcnt(" #n ")" ::: "memory")
; #define PG8_BAR __builtin_amdgcn_s_barrier()
; #define PG8_SCHED __builtin_amdgcn_sched_barrier(0)
; template <class Epi>
; __device__ __forceinline__ void gemm_phase(LAS unsigned char* lds, const Gemm g, const Order& S, const Epi& E, const int tid) {
;     ...
;             PG8_LDB(B0, 0, 0); PG8_SCHED; PG8_LDA(At, 0, 0); PG8_STAGE(PG8_SA(1, 1), a1 + hstepA, voffA);
;             PG8_WAIT_L(8); PG8_BAR; PG8_WAIT_L(0); PG8_MMA(0, 0, At, B0); PG8_BAR; PG8_SCHED;
;             PG8_LDB(B1, 0, 1); PG8_STAGE(PG8_SB(0, 0), b2, voffB);
;             PG8_BAR; PG8_WAIT_L(0); PG8_MMA(0, 1, At, B1); PG8_BAR;
;             PG8_LDA(At, 0, 1); PG8_STAGE(PG8_SA(0, 0), a2, voffA);
;             PG8_BAR; PG8_WAIT_L(0); PG8_MMA(1, 0, At, B0); PG8_BAR; PG8_SCHED;
;             PG8_STAGE(PG8_SB(0, 1), b2 + hstepB, voffB);
;             PG8_WAIT_V(6); PG8_BAR; PG8_MMA(1, 1, At, B1); PG8_BAR;
;             PG8_LDB(B0, 1, 0); PG8_SCHED; PG8_LDA(At, 1, 0); PG8_STAGE(PG8_SA(0, 1), a2 + hstepA, voffA);
;             PG8_WAIT_L(8); PG8_BAR; PG8_WAIT_L(0); PG8_MMA(0, 0, At, B0); PG8_BAR; PG8_SCHED;
.LBB0_688:
	ds_read_b128 v[128:131], v189
	ds_read_b128 v[132:135], v189 offset:1024
	ds_read_b128 v[136:139], v189 offset:2048
	ds_read_b128 v[140:143], v189 offset:3072
	s_add_u32 s28, s26, 0xffe00080
	s_addc_u32 s29, s27, -1
	s_cmpk_eq_i32 s51, 0x7c
	s_cselect_b32 s31, s7, s29
	s_cselect_b32 s30, s15, s28
	s_cselect_b32 s29, s17, s50
	s_cselect_b32 s28, s48, s49
	v_lshl_add_u64 v[184:185], s[26:27], 0, v[160:161]
	s_add_i32 m0, s34, 0xc000
	ds_read_b128 v[144:147], v190
	ds_read_b128 v[148:151], v190 offset:1024
	ds_read_b128 v[168:171], v190 offset:2048
	ds_read_b128 v[172:175], v190 offset:3072
	ds_read_b128 v[176:179], v190 offset:4096
	ds_read_b128 v[180:183], v190 offset:5120
	ds_read_b128 v[194:197], v190 offset:6144
	ds_read_b128 v[198:201], v190 offset:7168
	global_load_lds_dwordx4 v[184:185], off
	v_lshl_add_u64 v[184:185], s[26:27], 0, v[162:163]
	s_add_i32 m0, s34, 0xe000
	s_nop 0
	global_load_lds_dwordx4 v[184:185], off
	s_waitcnt lgkmcnt(8)
	s_barrier
	s_waitcnt lgkmcnt(0)
	s_setprio 1
	s_waitcnt lgkmcnt(0)
	v_mfma_f32_16x16x32_bf16 v[124:127], v[128:131], v[144:147], v[124:127]
	v_mfma_f32_16x16x32_bf16 v[120:123], v[136:139], v[144:147], v[120:123]
	v_mfma_f32_16x16x32_bf16 v[108:111], v[128:131], v[168:171], v[108:111]
	v_mfma_f32_16x16x32_bf16 v[104:107], v[136:139], v[168:171], v[104:107]
	v_mfma_f32_16x16x32_bf16 v[92:95], v[128:131], v[176:179], v[92:95]
	v_mfma_f32_16x16x32_bf16 v[88:91], v[136:139], v[176:179], v[88:91]
	v_mfma_f32_16x16x32_bf16 v[76:79], v[128:131], v[194:197], v[76:79]
	v_mfma_f32_16x16x32_bf16 v[72:75], v[136:139], v[194:197], v[72:75]
	v_mfma_f32_16x16x32_bf16 v[124:127], v[132:135], v[148:151], v[124:127]
	v_mfma_f32_16x16x32_bf16 v[120:123], v[140:143], v[148:151], v[120:123]
	v_mfma_f32_16x16x32_bf16 v[108:111], v[132:135], v[172:175], v[108:111]
	v_mfma_f32_16x16x32_bf16 v[104:107], v[140:143], v[172:175], v[104:107]
	v_mfma_f32_16x16x32_bf16 v[92:95], v[132:135], v[180:183], v[92:95]
	v_mfma_f32_16x16x32_bf16 v[88:91], v[140:143], v[180:183], v[88:91]
	v_mfma_f32_16x16x32_bf16 v[76:79], v[132:135], v[198:201], v[76:79]
	v_mfma_f32_16x16x32_bf16 v[72:75], v[140:143], v[198:201], v[72:75]
	s_setprio 0
	s_barrier
	s_add_i32 s52, s45, s33
	v_lshl_add_u64 v[184:185], s[28:29], 0, v[154:155]
	s_mov_b32 m0, s52
	ds_read_b128 v[202:205], v191
	ds_read_b128 v[206:209], v191 offset:1024
	ds_read_b128 v[210:213], v191 offset:2048
	ds_read_b128 v[214:217], v191 offset:3072
	global_load_lds_dwordx4 v[184:185], off
	v_lshl_add_u64 v[218:219], s[28:29], 0, v[158:159]
	s_add_i32 m0, s52, 0x2000
	s_nop 0
	global_load_lds_dwordx4 v[218:219], off
	s_barrier
	s_waitcnt lgkmcnt(0)
	s_setprio 1
	s_waitcnt lgkmcnt(0)
	v_mfma_f32_16x16x32_bf16 v[116:119], v[202:205], v[144:147], v[116:119]
	v_mfma_f32_16x16x32_bf16 v[112:115], v[210:213], v[144:147], v[112:115]
	v_mfma_f32_16x16x32_bf16 v[100:103], v[202:205], v[168:171], v[100:103]
	v_mfma_f32_16x16x32_bf16 v[96:99], v[210:213], v[168:171], v[96:99]
	v_mfma_f32_16x16x32_bf16 v[84:87], v[202:205], v[176:179], v[84:87]
	v_mfma_f32_16x16x32_bf16 v[80:83], v[210:213], v[176:179], v[80:83]
	v_mfma_f32_16x16x32_bf16 v[68:71], v[202:205], v[194:197], v[68:71]
	v_mfma_f32_16x16x32_bf16 v[64:67], v[210:213], v[194:197], v[64:67]
	v_mfma_f32_16x16x32_bf16 v[116:119], v[206:209], v[148:151], v[116:119]
	v_mfma_f32_16x16x32_bf16 v[112:115], v[214:217], v[148:151], v[112:115]
	v_mfma_f32_16x16x32_bf16 v[100:103], v[206:209], v[172:175], v[100:103]
	v_mfma_f32_16x16x32_bf16 v[96:99], v[214:217], v[172:175], v[96:99]
	v_mfma_f32_16x16x32_bf16 v[84:87], v[206:209], v[180:183], v[84:87]
	v_mfma_f32_16x16x32_bf16 v[80:83], v[214:217], v[180:183], v[80:83]
	v_mfma_f32_16x16x32_bf16 v[68:71], v[206:209], v[198:201], v[68:71]
	v_mfma_f32_16x16x32_bf16 v[64:67], v[214:217], v[198:201], v[64:67]
	s_setprio 0
	s_mov_b32 m0, s34
	v_lshl_add_u64 v[220:221], s[30:31], 0, v[152:153]
	s_barrier
	ds_read_b128 v[144:147], v190 offset:16384
	ds_read_b128 v[148:151], v190 offset:17408
	ds_read_b128 v[168:171], v190 offset:18432
	ds_read_b128 v[172:175], v190 offset:19456
	ds_read_b128 v[176:179], v190 offset:20480
	ds_read_b128 v[180:183], v190 offset:21504
	ds_read_b128 v[194:197], v190 offset:22528
	ds_read_b128 v[198:201], v190 offset:23552
	global_load_lds_dwordx4 v[220:221], off
	v_lshl_add_u64 v[222:223], s[30:31], 0, v[156:157]
	s_mov_b32 m0, s35
	s_nop 0
	global_load_lds_dwordx4 v[222:223], off
	s_barrier
	s_waitcnt lgkmcnt(0)
	s_setprio 1
	s_waitcnt lgkmcnt(0)
	v_mfma_f32_16x16x32_bf16 v[60:63], v[128:131], v[144:147], v[60:63]
	v_mfma_f32_16x16x32_bf16 v[56:59], v[136:139], v[144:147], v[56:59]
	v_mfma_f32_16x16x32_bf16 v[44:47], v[128:131], v[168:171], v[44:47]
	v_mfma_f32_16x16x32_bf16 v[40:43], v[136:139], v[168:171], v[40:43]
	v_mfma_f32_16x16x32_bf16 v[28:31], v[128:131], v[176:179], v[28:31]
	v_mfma_f32_16x16x32_bf16 v[24:27], v[136:139], v[176:179], v[24:27]
	v_mfma_f32_16x16x32_bf16 v[12:15], v[128:131], v[194:197], v[12:15]
	v_mfma_f32_16x16x32_bf16 v[8:11], v[136:139], v[194:197], v[8:11]
	v_mfma_f32_16x16x32_bf16 v[60:63], v[132:135], v[148:151], v[60:63]
	v_mfma_f32_16x16x32_bf16 v[56:59], v[140:143], v[148:151], v[56:59]
	v_mfma_f32_16x16x32_bf16 v[44:47], v[132:135], v[172:175], v[44:47]
	v_mfma_f32_16x16x32_bf16 v[40:43], v[140:143], v[172:175], v[40:43]
	v_mfma_f32_16x16x32_bf16 v[28:31], v[132:135], v[180:183], v[28:31]
	v_mfma_f32_16x16x32_bf16 v[24:27], v[140:143], v[180:183], v[24:27]
	v_mfma_f32_16x16x32_bf16 v[12:15], v[132:135], v[198:201], v[12:15]
	v_mfma_f32_16x16x32_bf16 v[8:11], v[140:143], v[198:201], v[8:11]
	s_setprio 0
	s_barrier
; #define PG8_STAGE(bufoff, gbase, voff) do { _Pragma("unroll") for (int _i = 0; _i < 2; ++_i) \
;         __builtin_amdgcn_global_load_lds((const unsigned*)((const char*)(gbase) + (voff)[_i]), (LAS unsigned*)(lds + (bufoff) + ldsw + _i * 8192), 16, 0, 0); } while (0)
; #define PG8_LDA(dst, b, h) do { _Pragma("unroll") for (int m = 0; m < 4; ++m) _Pragma("unroll") for (int k = 0; k < 2; ++k) dst[m][k] = *(const LAS bf16x8*)(lds + PG8_SA(b, h) + aoff + m * 2048 + k * 1024); } while (0)
; #define PG8_LDB(dst, b, h) do { _Pragma("unroll") for (int n = 0; n < 2; ++n) _Pragma("unroll") for (int k = 0; k < 2; ++k) dst[n][k] = *(const LAS bf16x8*)(lds + PG8_SB(b, h) + boff + n * 2048 + k * 1024); } while (0)
; #define PG8_MMA(ai, bj, At, Bt) do { __builtin_amdgcn_s_setprio(1); _Pragma("unroll") for (int m = 0; m < 4; ++m) _Pragma("unroll") for (int n = 0; n < 2; ++n) _Pragma("unroll") for (int k = 0; k < 2; ++k) \
;         acc[ai][bj][m][n] = __builtin_amdgcn_mfma_f32_16x16x32_bf16(Bt[n][k], At[m][k], acc[ai][bj][m][n], 0, 0, 0); __builtin_amdgcn_s_setprio(0); } while (0)
; #define PG8_WAIT_V(n) asm volatile("s_waitcnt vmcnt(" #n ")" ::: "memory")
; #define PG8_WAIT_L(n) asm volatile("s_waitcnt lgkmcnt(" #n ")" ::: "memory")
; #define PG8_BAR __builtin_amdgcn_s_barrier()
; #define PG8_SCHED __builtin_amdgcn_sched_barrier(0)
; template <class Epi>
; __device__ __forceinline__ void gemm_phase(LAS unsigned char* lds, const Gemm g, const Order& S, const Epi& E, const int tid) {
;     ...
;             PG8_STAGE(PG8_SB(0, 1), b2 + hstepB, voffB);
;             PG8_WAIT_V(6); PG8_BAR; PG8_MMA(1, 1, At, B1); PG8_BAR;
;             PG8_LDB(B0, 1, 0); PG8_SCHED; PG8_LDA(At, 1, 0); PG8_STAGE(PG8_SA(0, 1), a2 + hstepA, voffA);
;             PG8_WAIT_L(8); PG8_BAR; PG8_WAIT_L(0); PG8_MMA(0, 0, At, B0); PG8_BAR; PG8_SCHED;
;             PG8_LDB(B1, 1, 1); PG8_STAGE(PG8_SB(1, 0), b3, voffB);
;             PG8_BAR; PG8_WAIT_L(0); PG8_MMA(0, 1, At, B1); PG8_BAR;
;             PG8_LDA(At, 1, 1); PG8_STAGE(PG8_SA(1, 0), a3, voffA);
	s_add_u32 s52, s28, 0x200000
	s_addc_u32 s53, s29, 0
	s_add_i32 s55, s46, s33
	v_lshl_add_u64 v[128:129], s[52:53], 0, v[154:155]
	s_mov_b32 m0, s55
	s_nop 0
	global_load_lds_dwordx4 v[128:129], off
	v_lshl_add_u64 v[128:129], s[52:53], 0, v[158:159]
	s_add_i32 m0, s55, 0x2000
	s_nop 0
	global_load_lds_dwordx4 v[128:129], off
	s_waitcnt vmcnt(6)
	s_barrier
	s_setprio 1
	v_mfma_f32_16x16x32_bf16 v[52:55], v[202:205], v[144:147], v[52:55]
	v_mfma_f32_16x16x32_bf16 v[48:51], v[210:213], v[144:147], v[48:51]
	v_mfma_f32_16x16x32_bf16 v[36:39], v[202:205], v[168:171], v[36:39]
	v_mfma_f32_16x16x32_bf16 v[32:35], v[210:213], v[168:171], v[32:35]
	v_mfma_f32_16x16x32_bf16 v[20:23], v[202:205], v[176:179], v[20:23]
	v_mfma_f32_16x16x32_bf16 v[16:19], v[210:213], v[176:179], v[16:19]
	v_mfma_f32_16x16x32_bf16 v[4:7], v[202:205], v[194:197], v[4:7]
	v_mfma_f32_16x16x32_bf16 v[0:3], v[210:213], v[194:197], v[0:3]
	v_mfma_f32_16x16x32_bf16 v[52:55], v[206:209], v[148:151], v[52:55]
	v_mfma_f32_16x16x32_bf16 v[48:51], v[214:217], v[148:151], v[48:51]
	v_mfma_f32_16x16x32_bf16 v[36:39], v[206:209], v[172:175], v[36:39]
	v_mfma_f32_16x16x32_bf16 v[32:35], v[214:217], v[172:175], v[32:35]
	v_mfma_f32_16x16x32_bf16 v[20:23], v[206:209], v[180:183], v[20:23]
	v_mfma_f32_16x16x32_bf16 v[16:19], v[214:217], v[180:183], v[16:19]
	v_mfma_f32_16x16x32_bf16 v[4:7], v[206:209], v[198:201], v[4:7]
	v_mfma_f32_16x16x32_bf16 v[0:3], v[214:217], v[198:201], v[0:3]
	s_setprio 0
	s_add_i32 s52, 0, 0x18000
	v_add_u32_e32 v140, s52, v187
	s_barrier
	ds_read_b128 v[128:131], v140
	ds_read_b128 v[132:135], v140 offset:1024
	ds_read_b128 v[136:139], v140 offset:2048
	ds_read_b128 v[140:143], v140 offset:3072
	s_add_u32 s30, s30, 0x200000
	s_addc_u32 s31, s31, 0
	s_mov_b32 m0, s39
	v_lshl_add_u64 v[202:203], s[30:31], 0, v[152:153]
	ds_read_b128 v[144:147], v190 offset:32768
	ds_read_b128 v[148:151], v190 offset:33792
	ds_read_b128 v[168:171], v190 offset:34816
	ds_read_b128 v[172:175], v190 offset:35840
	ds_read_b128 v[176:179], v190 offset:36864
	ds_read_b128 v[180:183], v190 offset:37888
	ds_read_b128 v[194:197], v190 offset:38912
	ds_read_b128 v[198:201], v190 offset:39936
	global_load_lds_dwordx4 v[202:203], off
	v_lshl_add_u64 v[202:203], s[30:31], 0, v[156:157]
	s_mov_b32 m0, s40
	s_nop 0
	global_load_lds_dwordx4 v[202:203], off
	s_waitcnt lgkmcnt(8)
	s_barrier
	s_waitcnt lgkmcnt(0)
	s_setprio 1
	s_waitcnt lgkmcnt(0)
	v_mfma_f32_16x16x32_bf16 v[124:127], v[128:131], v[144:147], v[124:127]
	v_mfma_f32_16x16x32_bf16 v[120:123], v[136:139], v[144:147], v[120:123]
	v_mfma_f32_16x16x32_bf16 v[108:111], v[128:131], v[168:171], v[108:111]
	v_mfma_f32_16x16x32_bf16 v[104:107], v[136:139], v[168:171], v[104:107]
	v_mfma_f32_16x16x32_bf16 v[92:95], v[128:131], v[176:179], v[92:95]
	v_mfma_f32_16x16x32_bf16 v[88:91], v[136:139], v[176:179], v[88:91]
	v_mfma_f32_16x16x32_bf16 v[76:79], v[128:131], v[194:197], v[76:79]
	v_mfma_f32_16x16x32_bf16 v[72:75], v[136:139], v[194:197], v[72:75]
	v_mfma_f32_16x16x32_bf16 v[124:127], v[132:135], v[148:151], v[124:127]
	v_mfma_f32_16x16x32_bf16 v[120:123], v[140:143], v[148:151], v[120:123]
	v_mfma_f32_16x16x32_bf16 v[108:111], v[132:135], v[172:175], v[108:111]
	v_mfma_f32_16x16x32_bf16 v[104:107], v[140:143], v[172:175], v[104:107]
	v_mfma_f32_16x16x32_bf16 v[92:95], v[132:135], v[180:183], v[92:95]
	v_mfma_f32_16x16x32_bf16 v[88:91], v[140:143], v[180:183], v[88:91]
	v_mfma_f32_16x16x32_bf16 v[76:79], v[132:135], v[198:201], v[76:79]
	v_mfma_f32_16x16x32_bf16 v[72:75], v[140:143], v[198:201], v[72:75]
	s_setprio 0
	s_barrier
	s_add_i32 s30, 0, 0x1c000
	s_add_i32 s31, s52, s33
	v_add_u32_e32 v193, s30, v187
	v_lshl_add_u64 v[184:185], v[184:185], 0, s[12:13]
	s_mov_b32 m0, s31
	ds_read_b128 v[202:205], v193
	ds_read_b128 v[206:209], v193 offset:1024
	ds_read_b128 v[210:213], v193 offset:2048
	ds_read_b128 v[214:217], v193 offset:3072
	global_load_lds_dwordx4 v[184:185], off
	v_lshl_add_u64 v[184:185], v[218:219], 0, s[12:13]
	s_add_i32 m0, s31, 0x2000
	s_nop 0
	global_load_lds_dwordx4 v[184:185], off
	s_barrier
	s_waitcnt lgkmcnt(0)
	s_setprio 1
	s_waitcnt lgkmcnt(0)
	v_mfma_f32_16x16x32_bf16 v[116:119], v[202:205], v[144:147], v[116:119]
	v_mfma_f32_16x16x32_bf16 v[112:115], v[210:213], v[144:147], v[112:115]
	v_mfma_f32_16x16x32_bf16 v[100:103], v[202:205], v[168:171], v[100:103]
	v_mfma_f32_16x16x32_bf16 v[96:99], v[210:213], v[168:171], v[96:99]
	v_mfma_f32_16x16x32_bf16 v[84:87], v[202:205], v[176:179], v[84:87]
	v_mfma_f32_16x16x32_bf16 v[80:83], v[210:213], v[176:179], v[80:83]
	v_mfma_f32_16x16x32_bf16 v[68:71], v[202:205], v[194:197], v[68:71]
	v_mfma_f32_16x16x32_bf16 v[64:67], v[210:213], v[194:197], v[64:67]
	v_mfma_f32_16x16x32_bf16 v[116:119], v[206:209], v[148:151], v[116:119]
	v_mfma_f32_16x16x32_bf16 v[112:115], v[214:217], v[148:151], v[112:115]
	v_mfma_f32_16x16x32_bf16 v[100:103], v[206:209], v[172:175], v[100:103]
	v_mfma_f32_16x16x32_bf16 v[96:99], v[214:217], v[172:175], v[96:99]
	v_mfma_f32_16x16x32_bf16 v[84:87], v[206:209], v[180:183], v[84:87]
	v_mfma_f32_16x16x32_bf16 v[80:83], v[214:217], v[180:183], v[80:83]
	v_mfma_f32_16x16x32_bf16 v[68:71], v[206:209], v[198:201], v[68:71]
	v_mfma_f32_16x16x32_bf16 v[64:67], v[214:217], v[198:201], v[64:67]
	s_setprio 0
	s_mov_b32 m0, s43
	v_lshl_add_u64 v[184:185], v[220:221], 0, s[12:13]
	s_barrier
	ds_read_b128 v[144:147], v190 offset:49152
	ds_read_b128 v[148:151], v190 offset:50176
	ds_read_b128 v[168:171], v190 offset:51200
	ds_read_b128 v[172:175], v190 offset:52224
	ds_read_b128 v[176:179], v190 offset:53248
	ds_read_b128 v[180:183], v190 offset:54272
	ds_read_b128 v[194:197], v190 offset:55296
	ds_read_b128 v[198:201], v190 offset:56320
	global_load_lds_dwordx4 v[184:185], off
	v_lshl_add_u64 v[184:185], v[222:223], 0, s[12:13]
	s_mov_b32 m0, s44
	s_nop 0
	global_load_lds_dwordx4 v[184:185], off
	s_barrier
; #define PG8_STAGE(bufoff, gbase, voff) do { _Pragma("unroll") for (int _i = 0; _i < 2; ++_i) \
;         __builtin_amdgcn_global_load_lds((const unsigned*)((const char*)(gbase) + (voff)[_i]), (LAS unsigned*)(lds + (bufoff) + ldsw + _i * 8192), 16, 0, 0); } while (0)
; #define PG8_MMA(ai, bj, At, Bt) do { __builtin_amdgcn_s_setprio(1); _Pragma("unroll") for (int m = 0; m < 4; ++m) _Pragma("unroll") for (int n = 0; n < 2; ++n) _Pragma("unroll") for (int k = 0; k < 2; ++k) \
;         acc[ai][bj][m][n] = __builtin_amdgcn_mfma_f32_16x16x32_bf16(Bt[n][k], At[m][k], acc[ai][bj][m][n], 0, 0, 0); __builtin_amdgcn_s_setprio(0); } while (0)
; #define PG8_WAIT_V(n) asm volatile("s_waitcnt vmcnt(" #n ")" ::: "memory")
; #define PG8_WAIT_L(n) asm volatile("s_waitcnt lgkmcnt(" #n ")" ::: "memory")
; #define PG8_BAR __builtin_amdgcn_s_barrier()
; #define PG8_SCHED __builtin_amdgcn_sched_barrier(0)
; template <class Epi>
; __device__ __forceinline__ void gemm_phase(LAS unsigned char* lds, const Gemm g, const Order& S, const Epi& E, const int tid) {
;     ...
;             PG8_BAR; PG8_WAIT_L(0); PG8_MMA(1, 0, At, B0); PG8_BAR; PG8_SCHED;
;             PG8_STAGE(PG8_SB(1, 1), b3 + hstepB, voffB);
;             PG8_WAIT_V(6); PG8_BAR; PG8_MMA(1, 1, At, B1); PG8_BAR;
	s_waitcnt lgkmcnt(0)
	s_setprio 1
	s_waitcnt lgkmcnt(0)
	v_mfma_f32_16x16x32_bf16 v[60:63], v[128:131], v[144:147], v[60:63]
	v_mfma_f32_16x16x32_bf16 v[56:59], v[136:139], v[144:147], v[56:59]
	v_mfma_f32_16x16x32_bf16 v[44:47], v[128:131], v[168:171], v[44:47]
	v_mfma_f32_16x16x32_bf16 v[40:43], v[136:139], v[168:171], v[40:43]
	v_mfma_f32_16x16x32_bf16 v[28:31], v[128:131], v[176:179], v[28:31]
	v_mfma_f32_16x16x32_bf16 v[24:27], v[136:139], v[176:179], v[24:27]
	v_mfma_f32_16x16x32_bf16 v[12:15], v[128:131], v[194:197], v[12:15]
	v_mfma_f32_16x16x32_bf16 v[8:11], v[136:139], v[194:197], v[8:11]
	v_mfma_f32_16x16x32_bf16 v[60:63], v[132:135], v[148:151], v[60:63]
	v_mfma_f32_16x16x32_bf16 v[56:59], v[140:143], v[148:151], v[56:59]
	v_mfma_f32_16x16x32_bf16 v[44:47], v[132:135], v[172:175], v[44:47]
	v_mfma_f32_16x16x32_bf16 v[40:43], v[140:143], v[172:175], v[40:43]
	v_mfma_f32_16x16x32_bf16 v[28:31], v[132:135], v[180:183], v[28:31]
	v_mfma_f32_16x16x32_bf16 v[24:27], v[140:143], v[180:183], v[24:27]
	v_mfma_f32_16x16x32_bf16 v[12:15], v[132:135], v[198:201], v[12:15]
	v_mfma_f32_16x16x32_bf16 v[8:11], v[140:143], v[198:201], v[8:11]
	s_setprio 0
	s_barrier
	s_add_u32 s28, s28, 0x200080
	s_addc_u32 s29, s29, 0
	s_add_i32 s30, s30, s33
	v_lshl_add_u64 v[128:129], s[28:29], 0, v[154:155]
	s_mov_b32 m0, s30
	s_nop 0
	global_load_lds_dwordx4 v[128:129], off
	v_lshl_add_u64 v[128:129], s[28:29], 0, v[158:159]
	s_add_i32 m0, s30, 0x2000
	s_nop 0
	global_load_lds_dwordx4 v[128:129], off
	s_waitcnt vmcnt(6)
	s_barrier
	s_setprio 1
	v_mfma_f32_16x16x32_bf16 v[52:55], v[202:205], v[144:147], v[52:55]
	v_mfma_f32_16x16x32_bf16 v[48:51], v[210:213], v[144:147], v[48:51]
	v_mfma_f32_16x16x32_bf16 v[36:39], v[202:205], v[168:171], v[36:39]
	v_mfma_f32_16x16x32_bf16 v[32:35], v[210:213], v[168:171], v[32:35]
	v_mfma_f32_16x16x32_bf16 v[20:23], v[202:205], v[176:179], v[20:23]
	v_mfma_f32_16x16x32_bf16 v[16:19], v[210:213], v[176:179], v[16:19]
	v_mfma_f32_16x16x32_bf16 v[4:7], v[202:205], v[194:197], v[4:7]
	v_mfma_f32_16x16x32_bf16 v[0:3], v[210:213], v[194:197], v[0:3]
	v_mfma_f32_16x16x32_bf16 v[52:55], v[206:209], v[148:151], v[52:55]
	v_mfma_f32_16x16x32_bf16 v[48:51], v[214:217], v[148:151], v[48:51]
	v_mfma_f32_16x16x32_bf16 v[36:39], v[206:209], v[172:175], v[36:39]
	v_mfma_f32_16x16x32_bf16 v[32:35], v[214:217], v[172:175], v[32:35]
	v_mfma_f32_16x16x32_bf16 v[20:23], v[206:209], v[180:183], v[20:23]
	v_mfma_f32_16x16x32_bf16 v[16:19], v[214:217], v[180:183], v[16:19]
	v_mfma_f32_16x16x32_bf16 v[4:7], v[206:209], v[198:201], v[4:7]
	v_mfma_f32_16x16x32_bf16 v[0:3], v[214:217], v[198:201], v[0:3]
	s_setprio 0
	s_add_i32 s51, s51, 2
	s_add_u32 s26, s26, 0x100
	s_addc_u32 s27, s27, 0
	s_add_u32 s49, s49, 0x100
	s_addc_u32 s50, s50, 0
	s_cmpk_gt_u32 s51, 0x7d
	s_barrier
	s_cbranch_scc0 .LBB0_688
; __device__ __forceinline__ float bflo(unsigned w) { return __uint_as_float(w << 16); }
; __device__ __forceinline__ float bfhi(unsigned w) { return __uint_as_float(w & 0xffff0000u); }
;     __device__ __forceinline__ void operator()(const f32x4 (&acc)[2][2][4][2], const Unit& u, int wr, int wc, int fr, int fq) const {
;     ...
;                 u32x4 bs[4][2];
; #pragma unroll
;                 for (int m = 0; m < 4; ++m) { const size_t off = (size_t)(row0 + ai * HALF + m * 16) * DM + col0;
; #pragma unroll
;                     for (int bj = 0; bj < 2; ++bj) bs[m][bj] = *(const u32x4*)(baseb + off + bj * HALF); }
; #pragma unroll
;                 for (int m = 0; m < 4; ++m) { const size_t off = (size_t)(row0 + ai * HALF + m * 16) * DM + col0;
;                     float ss = 0.f;
; #pragma unroll
;                     for (int bj = 0; bj < 2; ++bj) { const u32x4 q = bs[m][bj]; const f32x4 a0 = acc[ai][bj][m][0], a1 = acc[ai][bj][m][1];
;                         const float h0 = bflo(q.x) + a0[0], h1 = bfhi(q.x) + a0[1], h2 = bflo(q.y) + a0[2], h3 = bfhi(q.y) + a0[3], h4 = bflo(q.z) + a1[0], h5 = bfhi(q.z) + a1[1], h6 = bflo(q.w) + a1[2], h7 = bfhi(q.w) + a1[3];
;                         ss += (h0 * h0 + h1 * h1) + (h2 * h2 + h3 * h3) + (h4 * h4 + h5 * h5) + (h6 * h6 + h7 * h7);
;                         u32x4 w; w.x = pk2(h0, h1); w.y = pk2(h2, h3); w.z = pk2(h4, h5); w.w = pk2(h6, h7);
;                         *(u32x4*)(out + off + bj * HALF) = w; }
;                     if (ssqp) { ss += __shfl_xor(ss, 16); ss += __shfl_xor(ss, 32); if (fq == 0) ssqp[(size_t)(row0 + ai * HALF + m * 16) * 32 + u.pn * 4 + wc] = ss; } }
	v_lshl_or_b32 v168, s6, 8, v188
	v_lshl_add_u32 v172, s8, 8, v186
	v_ashrrev_i32_e32 v169, 31, v168
	v_lshlrev_b64 v[202:203], 1, v[168:169]
	v_ashrrev_i32_e32 v173, 31, v172
	v_or_b32_e32 v182, 16, v172
	v_or_b32_e32 v178, 32, v172
	v_lshl_add_u64 v[170:171], s[22:23], 0, v[202:203]
	v_lshlrev_b64 v[204:205], 12, v[172:173]
	v_or_b32_e32 v174, 48, v172
	v_ashrrev_i32_e32 v183, 31, v182
	v_ashrrev_i32_e32 v179, 31, v178
	v_lshl_add_u64 v[128:129], v[170:171], 0, v[204:205]
	v_ashrrev_i32_e32 v175, 31, v174
	v_lshlrev_b64 v[184:185], 12, v[182:183]
	v_lshlrev_b64 v[180:181], 12, v[178:179]
	global_load_dwordx4 v[194:197], v[128:129], off
	global_load_dwordx4 v[198:201], v[128:129], off offset:256
	v_lshlrev_b64 v[176:177], 12, v[174:175]
	v_lshl_add_u64 v[128:129], v[170:171], 0, v[184:185]
	v_lshl_add_u64 v[130:131], v[170:171], 0, v[180:181]
	v_lshl_add_u64 v[206:207], v[170:171], 0, v[176:177]
	global_load_dwordx4 v[148:151], v[128:129], off
	global_load_dwordx4 v[144:147], v[128:129], off offset:256
	global_load_dwordx4 v[140:143], v[130:131], off
	global_load_dwordx4 v[136:139], v[130:131], off offset:256
	global_load_dwordx4 v[132:135], v[206:207], off
	s_nop 0
	global_load_dwordx4 v[128:131], v[206:207], off offset:256
	v_cndmask_b32_e64 v193, 0, 1, s[10:11]
	v_lshl_add_u64 v[204:205], s[22:23], 0, v[204:205]
	s_lshl_b32 s26, s6, 2
	v_cmp_ne_u32_e64 s[6:7], 1, v193
	v_lshl_add_u64 v[204:205], v[204:205], 0, v[202:203]
	s_ashr_i32 s27, s26, 31
	s_andn2_b64 vcc, exec, s[10:11]
	s_waitcnt vmcnt(0)
	v_lshlrev_b32_e32 v193, 16, v194
	v_and_b32_e32 v194, 0xffff0000, v194
	v_lshlrev_b32_e32 v202, 16, v195
	v_and_b32_e32 v195, 0xffff0000, v195
	v_lshlrev_b32_e32 v203, 16, v196
	v_and_b32_e32 v196, 0xffff0000, v196
	v_lshlrev_b32_e32 v206, 16, v197
	v_and_b32_e32 v197, 0xffff0000, v197
	v_lshlrev_b32_e32 v207, 16, v198
	v_and_b32_e32 v198, 0xffff0000, v198
	v_lshlrev_b32_e32 v208, 16, v199
	v_and_b32_e32 v199, 0xffff0000, v199
	v_lshlrev_b32_e32 v209, 16, v200
	v_and_b32_e32 v200, 0xffff0000, v200
	v_lshlrev_b32_e32 v210, 16, v201
	v_and_b32_e32 v201, 0xffff0000, v201
	v_add_f32_e32 v193, v124, v193
	v_add_f32_e32 v194, v125, v194
	v_add_f32_e32 v124, v126, v202
	v_add_f32_e32 v125, v127, v195
	v_add_f32_e32 v126, v120, v203
	v_add_f32_e32 v127, v121, v196
	v_add_f32_e32 v122, v122, v206
	v_add_f32_e32 v123, v123, v197
	v_add_f32_e32 v120, v116, v207
	v_add_f32_e32 v121, v117, v198
	v_add_f32_e32 v116, v118, v208
	v_add_f32_e32 v117, v119, v199
	v_add_f32_e32 v112, v112, v209
	v_add_f32_e32 v113, v113, v200
	v_add_f32_e32 v114, v114, v210
	v_add_f32_e32 v115, v115, v201
	v_cvt_pk_bf16_f32 v196, v193, v194
	v_cvt_pk_bf16_f32 v197, v124, v125
	v_cvt_pk_bf16_f32 v198, v126, v127
	v_cvt_pk_bf16_f32 v199, v122, v123
	v_cvt_pk_bf16_f32 v200, v120, v121
	v_cvt_pk_bf16_f32 v201, v116, v117
	v_cvt_pk_bf16_f32 v202, v112, v113
	v_cvt_pk_bf16_f32 v203, v114, v115
	global_store_dwordx4 v[204:205], v[196:199], off sc0 sc1
	global_store_dwordx4 v[204:205], v[200:203], off offset:256 sc0 sc1
	s_cbranch_vccnz .LBB0_693
	v_mul_f32_e32 v115, v115, v115
	v_mul_f32_e32 v113, v113, v113
	v_mul_f32_e32 v118, v123, v123
	v_fmac_f32_e32 v115, v114, v114
	v_fmac_f32_e32 v113, v112, v112
	v_mul_f32_e32 v112, v121, v121
	v_mul_f32_e32 v114, v117, v117
	v_fmac_f32_e32 v118, v122, v122
	v_mul_f32_e32 v122, v194, v194
	v_mul_f32_e32 v123, v125, v125
	v_fmac_f32_e32 v112, v120, v120
	v_fmac_f32_e32 v114, v116, v116
	v_mul_f32_e32 v119, v127, v127
	v_fmac_f32_e32 v122, v193, v193
	v_fmac_f32_e32 v123, v124, v124
	v_add_f32_e32 v112, v112, v114
	v_and_b32_e32 v114, 64, v192
	v_fmac_f32_e32 v119, v126, v126
	v_add_f32_e32 v122, v122, v123
	v_add_f32_e32 v112, v113, v112
	v_xor_b32_e32 v113, 16, v192
	v_add_u32_e32 v114, 64, v114
	v_add_f32_e32 v119, v119, v122
	v_cmp_lt_i32_e32 vcc, v113, v114
	v_add_f32_e32 v118, v118, v119
	v_add_f32_e32 v112, v115, v112
	v_cndmask_b32_e32 v113, v192, v113, vcc
	v_add_f32_e32 v112, v118, v112
	v_lshlrev_b32_e32 v113, 2, v113
	ds_bpermute_b32 v113, v113, v112
	s_waitcnt lgkmcnt(0)
	v_add_f32_e32 v112, v112, v113
	v_xor_b32_e32 v113, 32, v192
	v_cmp_lt_i32_e32 vcc, v113, v114
	s_nop 1
	v_cndmask_b32_e32 v113, v192, v113, vcc
	v_lshlrev_b32_e32 v113, 2, v113
	ds_bpermute_b32 v113, v113, v112
	s_and_saveexec_b64 s[28:29], s[0:1]
	s_cbranch_execz .LBB0_692
	v_lshlrev_b64 v[114:115], 7, v[172:173]
	v_lshl_add_u64 v[114:115], s[24:25], 0, v[114:115]
	v_lshl_add_u64 v[114:115], s[26:27], 2, v[114:115]
	s_lshl_b32 s8, s41, 2
	v_lshl_add_u64 v[114:115], v[114:115], 0, s[8:9]
	s_waitcnt lgkmcnt(0)
	v_add_f32_e32 v112, v112, v113
	global_store_dword v[114:115], v112, off

; __device__ __forceinline__ float bflo(unsigned w) { return __uint_as_float(w << 16); }
; __device__ __forceinline__ float bfhi(unsigned w) { return __uint_as_float(w & 0xffff0000u); }
;     __device__ __forceinline__ void operator()(const f32x4 (&acc)[2][2][4][2], const Unit& u, int wr, int wc, int fr, int fq) const {
;     ...
;                 for (int m = 0; m < 4; ++m) { const size_t off = (size_t)(row0 + ai * HALF + m * 16) * DM + col0;
;                     float ss = 0.f;
; #pragma unroll
;                     for (int bj = 0; bj < 2; ++bj) { const u32x4 q = bs[m][bj]; const f32x4 a0 = acc[ai][bj][m][0], a1 = acc[ai][bj][m][1];
;                         const float h0 = bflo(q.x) + a0[0], h1 = bfhi(q.x) + a0[1], h2 = bflo(q.y) + a0[2], h3 = bfhi(q.y) + a0[3], h4 = bflo(q.z) + a1[0], h5 = bfhi(q.z) + a1[1], h6 = bflo(q.w) + a1[2], h7 = bfhi(q.w) + a1[3];
;                         ss += (h0 * h0 + h1 * h1) + (h2 * h2 + h3 * h3) + (h4 * h4 + h5 * h5) + (h6 * h6 + h7 * h7);
;                         u32x4 w; w.x = pk2(h0, h1); w.y = pk2(h2, h3); w.z = pk2(h4, h5); w.w = pk2(h6, h7);
;                         *(u32x4*)(out + off + bj * HALF) = w; }
;                     if (ssqp) { ss += __shfl_xor(ss, 16); ss += __shfl_xor(ss, 32); if (fq == 0) ssqp[(size_t)(row0 + ai * HALF + m * 16) * 32 + u.pn * 4 + wc] = ss; } }
.LBB0_693:
	v_lshlrev_b32_e32 v112, 16, v148
	v_add_f32_e32 v108, v108, v112
	v_and_b32_e32 v112, 0xffff0000, v148
	v_add_f32_e32 v112, v109, v112
	v_lshlrev_b32_e32 v109, 16, v149
	v_add_f32_e32 v109, v110, v109
	v_and_b32_e32 v110, 0xffff0000, v149
	v_add_f32_e32 v110, v111, v110
	v_lshlrev_b32_e32 v111, 16, v150
	v_add_f32_e32 v104, v104, v111
	v_and_b32_e32 v111, 0xffff0000, v150
	v_add_f32_e32 v105, v105, v111
	v_lshlrev_b32_e32 v111, 16, v151
	v_add_f32_e32 v111, v106, v111
	v_and_b32_e32 v106, 0xffff0000, v151
	v_add_f32_e32 v107, v107, v106
	v_lshlrev_b32_e32 v106, 16, v144
	v_add_f32_e32 v100, v100, v106
	v_and_b32_e32 v106, 0xffff0000, v144
	v_add_f32_e32 v106, v101, v106
	v_lshlrev_b32_e32 v101, 16, v145
	v_add_f32_e32 v101, v102, v101
	v_and_b32_e32 v102, 0xffff0000, v145
	v_add_f32_e32 v102, v103, v102
	v_lshlrev_b32_e32 v103, 16, v146
	v_add_f32_e32 v96, v96, v103
	v_and_b32_e32 v103, 0xffff0000, v146
	v_add_f32_e32 v97, v97, v103
	v_lshlrev_b32_e32 v103, 16, v147
	v_lshl_add_u64 v[118:119], s[22:23], 0, v[184:185]
	v_add_f32_e32 v98, v98, v103
	v_and_b32_e32 v103, 0xffff0000, v147
	v_cvt_pk_bf16_f32 v114, v108, v112
	v_cvt_pk_bf16_f32 v115, v109, v110
	v_cvt_pk_bf16_f32 v116, v104, v105
	v_cvt_pk_bf16_f32 v117, v111, v107
	v_lshl_add_u64 v[118:119], v[168:169], 1, v[118:119]
	v_add_f32_e32 v99, v99, v103
	global_store_dwordx4 v[118:119], v[114:117], off sc0 sc1
	s_and_b64 vcc, exec, s[6:7]
	s_nop 0
	v_cvt_pk_bf16_f32 v114, v100, v106
	v_cvt_pk_bf16_f32 v115, v101, v102
	v_cvt_pk_bf16_f32 v116, v96, v97
	v_cvt_pk_bf16_f32 v117, v98, v99
	global_store_dwordx4 v[118:119], v[114:117], off offset:256 sc0 sc1
	s_cbranch_vccnz .LBB0_697
	v_mul_f32_e32 v99, v99, v99
	v_mul_f32_e32 v97, v97, v97
	v_mul_f32_e32 v105, v105, v105
	v_fmac_f32_e32 v99, v98, v98
	v_fmac_f32_e32 v97, v96, v96
	v_mul_f32_e32 v96, v106, v106
	v_mul_f32_e32 v98, v102, v102
	v_mul_f32_e32 v103, v107, v107
	v_fmac_f32_e32 v105, v104, v104
	v_mul_f32_e32 v104, v112, v112
	v_mul_f32_e32 v107, v110, v110
	v_fmac_f32_e32 v96, v100, v100
	v_fmac_f32_e32 v98, v101, v101
	v_fmac_f32_e32 v104, v108, v108
	v_fmac_f32_e32 v107, v109, v109
	v_add_f32_e32 v96, v96, v98
	v_and_b32_e32 v98, 64, v192
	v_add_f32_e32 v104, v104, v107
	v_add_f32_e32 v96, v97, v96
	v_xor_b32_e32 v97, 16, v192
	v_add_u32_e32 v98, 64, v98
	v_fmac_f32_e32 v103, v111, v111
	v_add_f32_e32 v104, v105, v104
	v_cmp_lt_i32_e32 vcc, v97, v98
	v_add_f32_e32 v103, v103, v104
	v_add_f32_e32 v96, v99, v96
	v_cndmask_b32_e32 v97, v192, v97, vcc
	v_add_f32_e32 v96, v103, v96
	v_lshlrev_b32_e32 v97, 2, v97
	ds_bpermute_b32 v97, v97, v96
	s_waitcnt lgkmcnt(0)
	v_add_f32_e32 v96, v96, v97
	v_xor_b32_e32 v97, 32, v192
	v_cmp_lt_i32_e32 vcc, v97, v98
	s_nop 1
	v_cndmask_b32_e32 v97, v192, v97, vcc
	v_lshlrev_b32_e32 v97, 2, v97
	ds_bpermute_b32 v97, v97, v96
	s_and_saveexec_b64 s[28:29], s[0:1]
	s_cbranch_execz .LBB0_696
	v_lshlrev_b64 v[98:99], 7, v[182:183]
	v_lshl_add_u64 v[98:99], s[24:25], 0, v[98:99]
	v_lshl_add_u64 v[98:99], s[26:27], 2, v[98:99]
	s_lshl_b32 s8, s41, 2
	v_lshl_add_u64 v[98:99], v[98:99], 0, s[8:9]
	s_waitcnt lgkmcnt(0)
	v_add_f32_e32 v96, v96, v97
	global_store_dword v[98:99], v96, off

; __device__ __forceinline__ float bflo(unsigned w) { return __uint_as_float(w << 16); }
; __device__ __forceinline__ float bfhi(unsigned w) { return __uint_as_float(w & 0xffff0000u); }
;     __device__ __forceinline__ void operator()(const f32x4 (&acc)[2][2][4][2], const Unit& u, int wr, int wc, int fr, int fq) const {
;     ...
;                 for (int m = 0; m < 4; ++m) { const size_t off = (size_t)(row0 + ai * HALF + m * 16) * DM + col0;
;                     float ss = 0.f;
; #pragma unroll
;                     for (int bj = 0; bj < 2; ++bj) { const u32x4 q = bs[m][bj]; const f32x4 a0 = acc[ai][bj][m][0], a1 = acc[ai][bj][m][1];
;                         const float h0 = bflo(q.x) + a0[0], h1 = bfhi(q.x) + a0[1], h2 = bflo(q.y) + a0[2], h3 = bfhi(q.y) + a0[3], h4 = bflo(q.z) + a1[0], h5 = bfhi(q.z) + a1[1], h6 = bflo(q.w) + a1[2], h7 = bfhi(q.w) + a1[3];
;                         ss += (h0 * h0 + h1 * h1) + (h2 * h2 + h3 * h3) + (h4 * h4 + h5 * h5) + (h6 * h6 + h7 * h7);
;                         u32x4 w; w.x = pk2(h0, h1); w.y = pk2(h2, h3); w.z = pk2(h4, h5); w.w = pk2(h6, h7);
;                         *(u32x4*)(out + off + bj * HALF) = w; }
;                     if (ssqp) { ss += __shfl_xor(ss, 16); ss += __shfl_xor(ss, 32); if (fq == 0) ssqp[(size_t)(row0 + ai * HALF + m * 16) * 32 + u.pn * 4 + wc] = ss; } }
.LBB0_697:
	v_lshlrev_b32_e32 v96, 16, v140
	v_add_f32_e32 v92, v92, v96
	v_and_b32_e32 v96, 0xffff0000, v140
	v_add_f32_e32 v96, v93, v96
	v_lshlrev_b32_e32 v93, 16, v141
	v_add_f32_e32 v93, v94, v93
	v_and_b32_e32 v94, 0xffff0000, v141
	v_add_f32_e32 v94, v95, v94
	v_lshlrev_b32_e32 v95, 16, v142
	v_add_f32_e32 v88, v88, v95
	v_and_b32_e32 v95, 0xffff0000, v142
	v_add_f32_e32 v89, v89, v95
	v_lshlrev_b32_e32 v95, 16, v143
	v_add_f32_e32 v95, v90, v95
	v_and_b32_e32 v90, 0xffff0000, v143
	v_add_f32_e32 v91, v91, v90
	v_lshlrev_b32_e32 v90, 16, v136
	v_add_f32_e32 v84, v84, v90
	v_and_b32_e32 v90, 0xffff0000, v136
	v_add_f32_e32 v90, v85, v90
	v_lshlrev_b32_e32 v85, 16, v137
	v_add_f32_e32 v85, v86, v85
	v_and_b32_e32 v86, 0xffff0000, v137
	v_add_f32_e32 v86, v87, v86
	v_lshlrev_b32_e32 v87, 16, v138
	v_add_f32_e32 v80, v80, v87
	v_and_b32_e32 v87, 0xffff0000, v138
	v_add_f32_e32 v81, v81, v87
	v_lshlrev_b32_e32 v87, 16, v139
	v_lshl_add_u64 v[102:103], s[22:23], 0, v[180:181]
	v_add_f32_e32 v82, v82, v87
	v_and_b32_e32 v87, 0xffff0000, v139
	v_cvt_pk_bf16_f32 v98, v92, v96
	v_cvt_pk_bf16_f32 v99, v93, v94
	v_cvt_pk_bf16_f32 v100, v88, v89
	v_cvt_pk_bf16_f32 v101, v95, v91
	v_lshl_add_u64 v[102:103], v[168:169], 1, v[102:103]
	v_add_f32_e32 v83, v83, v87
	global_store_dwordx4 v[102:103], v[98:101], off sc0 sc1
	s_and_b64 vcc, exec, s[6:7]
	s_nop 0
	v_cvt_pk_bf16_f32 v98, v84, v90
	v_cvt_pk_bf16_f32 v99, v85, v86
	v_cvt_pk_bf16_f32 v100, v80, v81
	v_cvt_pk_bf16_f32 v101, v82, v83
	global_store_dwordx4 v[102:103], v[98:101], off offset:256 sc0 sc1
	s_cbranch_vccnz .LBB0_701
	v_mul_f32_e32 v83, v83, v83
	v_mul_f32_e32 v81, v81, v81
	v_mul_f32_e32 v89, v89, v89
	v_fmac_f32_e32 v83, v82, v82
	v_fmac_f32_e32 v81, v80, v80
	v_mul_f32_e32 v80, v90, v90
	v_mul_f32_e32 v82, v86, v86
	v_mul_f32_e32 v87, v91, v91
	v_fmac_f32_e32 v89, v88, v88
	v_mul_f32_e32 v88, v96, v96
	v_mul_f32_e32 v91, v94, v94
	v_fmac_f32_e32 v80, v84, v84
	v_fmac_f32_e32 v82, v85, v85
	v_fmac_f32_e32 v88, v92, v92
	v_fmac_f32_e32 v91, v93, v93
	v_add_f32_e32 v80, v80, v82
	v_and_b32_e32 v82, 64, v192
	v_add_f32_e32 v88, v88, v91
	v_add_f32_e32 v80, v81, v80
	v_xor_b32_e32 v81, 16, v192
	v_add_u32_e32 v82, 64, v82
	v_fmac_f32_e32 v87, v95, v95
	v_add_f32_e32 v88, v89, v88
	v_cmp_lt_i32_e32 vcc, v81, v82
	v_add_f32_e32 v87, v87, v88
	v_add_f32_e32 v80, v83, v80
	v_cndmask_b32_e32 v81, v192, v81, vcc
	v_add_f32_e32 v80, v87, v80
	v_lshlrev_b32_e32 v81, 2, v81
	ds_bpermute_b32 v81, v81, v80
	s_waitcnt lgkmcnt(0)
	v_add_f32_e32 v80, v80, v81
	v_xor_b32_e32 v81, 32, v192
	v_cmp_lt_i32_e32 vcc, v81, v82
	s_nop 1
	v_cndmask_b32_e32 v81, v192, v81, vcc
	v_lshlrev_b32_e32 v81, 2, v81
	ds_bpermute_b32 v81, v81, v80
	s_and_saveexec_b64 s[28:29], s[0:1]
	s_cbranch_execz .LBB0_700
	v_lshlrev_b64 v[82:83], 7, v[178:179]
	v_lshl_add_u64 v[82:83], s[24:25], 0, v[82:83]
	v_lshl_add_u64 v[82:83], s[26:27], 2, v[82:83]
	s_lshl_b32 s8, s41, 2
	v_lshl_add_u64 v[82:83], v[82:83], 0, s[8:9]
	s_waitcnt lgkmcnt(0)
	v_add_f32_e32 v80, v80, v81
	global_store_dword v[82:83], v80, off

; __device__ __forceinline__ float bflo(unsigned w) { return __uint_as_float(w << 16); }
; __device__ __forceinline__ float bfhi(unsigned w) { return __uint_as_float(w & 0xffff0000u); }
;     __device__ __forceinline__ void operator()(const f32x4 (&acc)[2][2][4][2], const Unit& u, int wr, int wc, int fr, int fq) const {
;     ...
;                 for (int m = 0; m < 4; ++m) { const size_t off = (size_t)(row0 + ai * HALF + m * 16) * DM + col0;
;                     float ss = 0.f;
; #pragma unroll
;                     for (int bj = 0; bj < 2; ++bj) { const u32x4 q = bs[m][bj]; const f32x4 a0 = acc[ai][bj][m][0], a1 = acc[ai][bj][m][1];
;                         const float h0 = bflo(q.x) + a0[0], h1 = bfhi(q.x) + a0[1], h2 = bflo(q.y) + a0[2], h3 = bfhi(q.y) + a0[3], h4 = bflo(q.z) + a1[0], h5 = bfhi(q.z) + a1[1], h6 = bflo(q.w) + a1[2], h7 = bfhi(q.w) + a1[3];
;                         ss += (h0 * h0 + h1 * h1) + (h2 * h2 + h3 * h3) + (h4 * h4 + h5 * h5) + (h6 * h6 + h7 * h7);
;                         u32x4 w; w.x = pk2(h0, h1); w.y = pk2(h2, h3); w.z = pk2(h4, h5); w.w = pk2(h6, h7);
;                         *(u32x4*)(out + off + bj * HALF) = w; }
;                     if (ssqp) { ss += __shfl_xor(ss, 16); ss += __shfl_xor(ss, 32); if (fq == 0) ssqp[(size_t)(row0 + ai * HALF + m * 16) * 32 + u.pn * 4 + wc] = ss; } }
.LBB0_701:
	v_lshlrev_b32_e32 v80, 16, v132
	v_add_f32_e32 v76, v76, v80
	v_and_b32_e32 v80, 0xffff0000, v132
	v_add_f32_e32 v80, v77, v80
	v_lshlrev_b32_e32 v77, 16, v133
	v_add_f32_e32 v77, v78, v77
	v_and_b32_e32 v78, 0xffff0000, v133
	v_add_f32_e32 v78, v79, v78
	v_lshlrev_b32_e32 v79, 16, v134
	v_add_f32_e32 v72, v72, v79
	v_and_b32_e32 v79, 0xffff0000, v134
	v_add_f32_e32 v73, v73, v79
	v_lshlrev_b32_e32 v79, 16, v135
	v_add_f32_e32 v79, v74, v79
	v_and_b32_e32 v74, 0xffff0000, v135
	v_add_f32_e32 v75, v75, v74
	v_lshlrev_b32_e32 v74, 16, v128
	v_add_f32_e32 v68, v68, v74
	v_and_b32_e32 v74, 0xffff0000, v128
	v_add_f32_e32 v74, v69, v74
	v_lshlrev_b32_e32 v69, 16, v129
	v_add_f32_e32 v69, v70, v69
	v_and_b32_e32 v70, 0xffff0000, v129
	v_add_f32_e32 v70, v71, v70
	v_lshlrev_b32_e32 v71, 16, v130
	v_add_f32_e32 v64, v64, v71
	v_and_b32_e32 v71, 0xffff0000, v130
	v_add_f32_e32 v65, v65, v71
	v_lshlrev_b32_e32 v71, 16, v131
	v_lshl_add_u64 v[86:87], s[22:23], 0, v[176:177]
	v_add_f32_e32 v66, v66, v71
	v_and_b32_e32 v71, 0xffff0000, v131
	v_cvt_pk_bf16_f32 v82, v76, v80
	v_cvt_pk_bf16_f32 v83, v77, v78
	v_cvt_pk_bf16_f32 v84, v72, v73
	v_cvt_pk_bf16_f32 v85, v79, v75
	v_lshl_add_u64 v[86:87], v[168:169], 1, v[86:87]
	v_add_f32_e32 v67, v67, v71
	global_store_dwordx4 v[86:87], v[82:85], off sc0 sc1
	s_and_b64 vcc, exec, s[6:7]
	s_nop 0
	v_cvt_pk_bf16_f32 v82, v68, v74
	v_cvt_pk_bf16_f32 v83, v69, v70
	v_cvt_pk_bf16_f32 v84, v64, v65
	v_cvt_pk_bf16_f32 v85, v66, v67
	global_store_dwordx4 v[86:87], v[82:85], off offset:256 sc0 sc1
	s_cbranch_vccnz .LBB0_705
	v_mul_f32_e32 v67, v67, v67
	v_mul_f32_e32 v65, v65, v65
	v_mul_f32_e32 v73, v73, v73
	v_fmac_f32_e32 v67, v66, v66
	v_fmac_f32_e32 v65, v64, v64
	v_mul_f32_e32 v64, v74, v74
	v_mul_f32_e32 v66, v70, v70
	v_mul_f32_e32 v71, v75, v75
	v_fmac_f32_e32 v73, v72, v72
	v_mul_f32_e32 v72, v80, v80
	v_mul_f32_e32 v75, v78, v78
	v_fmac_f32_e32 v64, v68, v68
	v_fmac_f32_e32 v66, v69, v69
	v_fmac_f32_e32 v72, v76, v76
	v_fmac_f32_e32 v75, v77, v77
	v_add_f32_e32 v64, v64, v66
	v_and_b32_e32 v66, 64, v192
	v_add_f32_e32 v72, v72, v75
	v_add_f32_e32 v64, v65, v64
	v_xor_b32_e32 v65, 16, v192
	v_add_u32_e32 v66, 64, v66
	v_fmac_f32_e32 v71, v79, v79
	v_add_f32_e32 v72, v73, v72
	v_cmp_lt_i32_e32 vcc, v65, v66
	v_add_f32_e32 v71, v71, v72
	v_add_f32_e32 v64, v67, v64
	v_cndmask_b32_e32 v65, v192, v65, vcc
	v_add_f32_e32 v64, v71, v64
	v_lshlrev_b32_e32 v65, 2, v65
	ds_bpermute_b32 v65, v65, v64
	s_waitcnt lgkmcnt(0)
	v_add_f32_e32 v64, v64, v65
	v_xor_b32_e32 v65, 32, v192
	v_cmp_lt_i32_e32 vcc, v65, v66
	s_nop 1
	v_cndmask_b32_e32 v65, v192, v65, vcc
	v_lshlrev_b32_e32 v65, 2, v65
	ds_bpermute_b32 v65, v65, v64
	s_and_saveexec_b64 s[28:29], s[0:1]
	s_cbranch_execz .LBB0_704
	v_lshlrev_b64 v[66:67], 7, v[174:175]
	v_lshl_add_u64 v[66:67], s[24:25], 0, v[66:67]
	v_lshl_add_u64 v[66:67], s[26:27], 2, v[66:67]
	s_lshl_b32 s8, s41, 2
	v_lshl_add_u64 v[66:67], v[66:67], 0, s[8:9]
	s_waitcnt lgkmcnt(0)
	v_add_f32_e32 v64, v64, v65
	global_store_dword v[66:67], v64, off

; __device__ __forceinline__ float bflo(unsigned w) { return __uint_as_float(w << 16); }
; __device__ __forceinline__ float bfhi(unsigned w) { return __uint_as_float(w & 0xffff0000u); }
;     __device__ __forceinline__ void operator()(const f32x4 (&acc)[2][2][4][2], const Unit& u, int wr, int wc, int fr, int fq) const {
;     ...
;                 for (int m = 0; m < 4; ++m) { const size_t off = (size_t)(row0 + ai * HALF + m * 16) * DM + col0;
; #pragma unroll
;                     for (int bj = 0; bj < 2; ++bj) bs[m][bj] = *(const u32x4*)(baseb + off + bj * HALF); }
; #pragma unroll
;                 for (int m = 0; m < 4; ++m) { const size_t off = (size_t)(row0 + ai * HALF + m * 16) * DM + col0;
;                     float ss = 0.f;
; #pragma unroll
;                     for (int bj = 0; bj < 2; ++bj) { const u32x4 q = bs[m][bj]; const f32x4 a0 = acc[ai][bj][m][0], a1 = acc[ai][bj][m][1];
;                         const float h0 = bflo(q.x) + a0[0], h1 = bfhi(q.x) + a0[1], h2 = bflo(q.y) + a0[2], h3 = bfhi(q.y) + a0[3], h4 = bflo(q.z) + a1[0], h5 = bfhi(q.z) + a1[1], h6 = bflo(q.w) + a1[2], h7 = bfhi(q.w) + a1[3];
;                         ss += (h0 * h0 + h1 * h1) + (h2 * h2 + h3 * h3) + (h4 * h4 + h5 * h5) + (h6 * h6 + h7 * h7);
;                         u32x4 w; w.x = pk2(h0, h1); w.y = pk2(h2, h3); w.z = pk2(h4, h5); w.w = pk2(h6, h7);
;                         *(u32x4*)(out + off + bj * HALF) = w; }
;                     if (ssqp) { ss += __shfl_xor(ss, 16); ss += __shfl_xor(ss, 32); if (fq == 0) ssqp[(size_t)(row0 + ai * HALF + m * 16) * 32 + u.pn * 4 + wc] = ss; } }
.LBB0_705:
	v_add_u32_e32 v100, 0x80, v172
	v_ashrrev_i32_e32 v101, 31, v100
	v_add_u32_e32 v96, 0x90, v172
	v_add_u32_e32 v92, 0xa0, v172
	v_lshlrev_b64 v[110:111], 12, v[100:101]
	v_add_u32_e32 v88, 0xb0, v172
	s_waitcnt lgkmcnt(0)
	v_ashrrev_i32_e32 v97, 31, v96
	v_ashrrev_i32_e32 v93, 31, v92
	v_lshl_add_u64 v[64:65], v[170:171], 0, v[110:111]
	v_ashrrev_i32_e32 v89, 31, v88
	v_lshlrev_b64 v[98:99], 12, v[96:97]
	v_lshlrev_b64 v[94:95], 12, v[92:93]
	global_load_dwordx4 v[102:105], v[64:65], off
	global_load_dwordx4 v[106:109], v[64:65], off offset:256
	v_lshlrev_b64 v[90:91], 12, v[88:89]
	v_lshl_add_u64 v[64:65], v[170:171], 0, v[98:99]
	v_lshl_add_u64 v[66:67], v[170:171], 0, v[94:95]
	v_lshl_add_u64 v[112:113], v[170:171], 0, v[90:91]
	global_load_dwordx4 v[84:87], v[64:65], off
	global_load_dwordx4 v[80:83], v[64:65], off offset:256
	global_load_dwordx4 v[76:79], v[66:67], off
	global_load_dwordx4 v[72:75], v[66:67], off offset:256
	global_load_dwordx4 v[68:71], v[112:113], off
	s_nop 0
	global_load_dwordx4 v[64:67], v[112:113], off offset:256
	v_lshl_add_u64 v[110:111], s[22:23], 0, v[110:111]
	v_lshl_add_u64 v[112:113], v[168:169], 1, v[110:111]
	s_and_b64 vcc, exec, s[6:7]
	s_waitcnt vmcnt(7)
	v_lshlrev_b32_e32 v110, 16, v102
	v_and_b32_e32 v111, 0xffff0000, v102
	v_lshlrev_b32_e32 v114, 16, v103
	v_and_b32_e32 v115, 0xffff0000, v103
	v_lshlrev_b32_e32 v116, 16, v104
	v_and_b32_e32 v104, 0xffff0000, v104
	v_lshlrev_b32_e32 v117, 16, v105
	v_and_b32_e32 v105, 0xffff0000, v105
	s_waitcnt vmcnt(6)
	v_lshlrev_b32_e32 v118, 16, v106
	v_and_b32_e32 v106, 0xffff0000, v106
	v_lshlrev_b32_e32 v119, 16, v107
	v_and_b32_e32 v107, 0xffff0000, v107
	v_lshlrev_b32_e32 v120, 16, v108
	v_and_b32_e32 v108, 0xffff0000, v108
	v_lshlrev_b32_e32 v121, 16, v109
	v_and_b32_e32 v109, 0xffff0000, v109
	v_add_f32_e32 v102, v60, v110
	v_add_f32_e32 v103, v61, v111
	v_add_f32_e32 v60, v62, v114
	v_add_f32_e32 v61, v63, v115
	v_add_f32_e32 v62, v56, v116
	v_add_f32_e32 v63, v57, v104
	v_add_f32_e32 v58, v58, v117
	v_add_f32_e32 v59, v59, v105
	v_add_f32_e32 v56, v52, v118
	v_add_f32_e32 v57, v53, v106
	v_add_f32_e32 v52, v54, v119
	v_add_f32_e32 v53, v55, v107
	v_add_f32_e32 v48, v48, v120
	v_add_f32_e32 v49, v49, v108
	v_add_f32_e32 v50, v50, v121
	v_add_f32_e32 v51, v51, v109
	v_cvt_pk_bf16_f32 v104, v102, v103
	v_cvt_pk_bf16_f32 v105, v60, v61
	v_cvt_pk_bf16_f32 v106, v62, v63
	v_cvt_pk_bf16_f32 v107, v58, v59
	v_cvt_pk_bf16_f32 v108, v56, v57
	v_cvt_pk_bf16_f32 v109, v52, v53
	v_cvt_pk_bf16_f32 v110, v48, v49
	v_cvt_pk_bf16_f32 v111, v50, v51
	global_store_dwordx4 v[112:113], v[104:107], off sc0 sc1
	global_store_dwordx4 v[112:113], v[108:111], off offset:256 sc0 sc1
	s_cbranch_vccnz .LBB0_709
	v_mul_f32_e32 v51, v51, v51
	v_mul_f32_e32 v49, v49, v49
	v_mul_f32_e32 v54, v59, v59
	v_fmac_f32_e32 v51, v50, v50
	v_fmac_f32_e32 v49, v48, v48
	v_mul_f32_e32 v48, v57, v57
	v_mul_f32_e32 v50, v53, v53
	v_fmac_f32_e32 v54, v58, v58
	v_mul_f32_e32 v58, v103, v103
	v_mul_f32_e32 v59, v61, v61
	v_fmac_f32_e32 v48, v56, v56
	v_fmac_f32_e32 v50, v52, v52
	v_mul_f32_e32 v55, v63, v63
	v_fmac_f32_e32 v58, v102, v102
	v_fmac_f32_e32 v59, v60, v60
	v_add_f32_e32 v48, v48, v50
	v_and_b32_e32 v50, 64, v192
	v_fmac_f32_e32 v55, v62, v62
	v_add_f32_e32 v58, v58, v59
	v_add_f32_e32 v48, v49, v48
	v_xor_b32_e32 v49, 16, v192
	v_add_u32_e32 v50, 64, v50
	v_add_f32_e32 v55, v55, v58
	v_cmp_lt_i32_e32 vcc, v49, v50
	v_add_f32_e32 v54, v54, v55
	v_add_f32_e32 v48, v51, v48
	v_cndmask_b32_e32 v49, v192, v49, vcc
	v_add_f32_e32 v48, v54, v48
	v_lshlrev_b32_e32 v49, 2, v49
	ds_bpermute_b32 v49, v49, v48
	s_waitcnt lgkmcnt(0)
	v_add_f32_e32 v48, v48, v49
	v_xor_b32_e32 v49, 32, v192
	v_cmp_lt_i32_e32 vcc, v49, v50
	s_nop 1
	v_cndmask_b32_e32 v49, v192, v49, vcc
	v_lshlrev_b32_e32 v49, 2, v49
	ds_bpermute_b32 v49, v49, v48
	s_and_saveexec_b64 s[28:29], s[0:1]
	s_cbranch_execz .LBB0_708
	v_lshlrev_b64 v[50:51], 7, v[100:101]
	v_lshl_add_u64 v[50:51], s[24:25], 0, v[50:51]
	v_lshl_add_u64 v[50:51], s[26:27], 2, v[50:51]
	s_lshl_b32 s8, s41, 2
	v_lshl_add_u64 v[50:51], v[50:51], 0, s[8:9]
	s_waitcnt lgkmcnt(0)
	v_add_f32_e32 v48, v48, v49
	global_store_dword v[50:51], v48, off

; __device__ __forceinline__ float bflo(unsigned w) { return __uint_as_float(w << 16); }
; __device__ __forceinline__ float bfhi(unsigned w) { return __uint_as_float(w & 0xffff0000u); }
;     __device__ __forceinline__ void operator()(const f32x4 (&acc)[2][2][4][2], const Unit& u, int wr, int wc, int fr, int fq) const {
;     ...
;                 for (int m = 0; m < 4; ++m) { const size_t off = (size_t)(row0 + ai * HALF + m * 16) * DM + col0;
;                     float ss = 0.f;
; #pragma unroll
;                     for (int bj = 0; bj < 2; ++bj) { const u32x4 q = bs[m][bj]; const f32x4 a0 = acc[ai][bj][m][0], a1 = acc[ai][bj][m][1];
;                         const float h0 = bflo(q.x) + a0[0], h1 = bfhi(q.x) + a0[1], h2 = bflo(q.y) + a0[2], h3 = bfhi(q.y) + a0[3], h4 = bflo(q.z) + a1[0], h5 = bfhi(q.z) + a1[1], h6 = bflo(q.w) + a1[2], h7 = bfhi(q.w) + a1[3];
;                         ss += (h0 * h0 + h1 * h1) + (h2 * h2 + h3 * h3) + (h4 * h4 + h5 * h5) + (h6 * h6 + h7 * h7);
;                         u32x4 w; w.x = pk2(h0, h1); w.y = pk2(h2, h3); w.z = pk2(h4, h5); w.w = pk2(h6, h7);
;                         *(u32x4*)(out + off + bj * HALF) = w; }
;                     if (ssqp) { ss += __shfl_xor(ss, 16); ss += __shfl_xor(ss, 32); if (fq == 0) ssqp[(size_t)(row0 + ai * HALF + m * 16) * 32 + u.pn * 4 + wc] = ss; } }
.LBB0_709:
	s_waitcnt vmcnt(7)
	v_lshlrev_b32_e32 v48, 16, v84
	v_add_f32_e32 v44, v44, v48
	v_and_b32_e32 v48, 0xffff0000, v84
	v_add_f32_e32 v48, v45, v48
	v_lshlrev_b32_e32 v45, 16, v85
	v_add_f32_e32 v45, v46, v45
	v_and_b32_e32 v46, 0xffff0000, v85
	v_add_f32_e32 v46, v47, v46
	v_lshlrev_b32_e32 v47, 16, v86
	v_add_f32_e32 v40, v40, v47
	v_and_b32_e32 v47, 0xffff0000, v86
	v_add_f32_e32 v41, v41, v47
	v_lshlrev_b32_e32 v47, 16, v87
	v_add_f32_e32 v47, v42, v47
	v_and_b32_e32 v42, 0xffff0000, v87
	v_add_f32_e32 v43, v43, v42
	s_waitcnt vmcnt(6)
	v_lshlrev_b32_e32 v42, 16, v80
	v_add_f32_e32 v36, v36, v42
	v_and_b32_e32 v42, 0xffff0000, v80
	v_add_f32_e32 v42, v37, v42
	v_lshlrev_b32_e32 v37, 16, v81
	v_add_f32_e32 v37, v38, v37
	v_and_b32_e32 v38, 0xffff0000, v81
	v_add_f32_e32 v38, v39, v38
	v_lshlrev_b32_e32 v39, 16, v82
	v_add_f32_e32 v32, v32, v39
	v_and_b32_e32 v39, 0xffff0000, v82
	v_add_f32_e32 v33, v33, v39
	v_lshlrev_b32_e32 v39, 16, v83
	v_lshl_add_u64 v[54:55], s[22:23], 0, v[98:99]
	v_add_f32_e32 v34, v34, v39
	v_and_b32_e32 v39, 0xffff0000, v83
	v_cvt_pk_bf16_f32 v50, v44, v48
	v_cvt_pk_bf16_f32 v51, v45, v46
	v_cvt_pk_bf16_f32 v52, v40, v41
	v_cvt_pk_bf16_f32 v53, v47, v43
	v_lshl_add_u64 v[54:55], v[168:169], 1, v[54:55]
	v_add_f32_e32 v35, v35, v39
	global_store_dwordx4 v[54:55], v[50:53], off sc0 sc1
	s_and_b64 vcc, exec, s[6:7]
	s_nop 0
	v_cvt_pk_bf16_f32 v50, v36, v42
	v_cvt_pk_bf16_f32 v51, v37, v38
	v_cvt_pk_bf16_f32 v52, v32, v33
	v_cvt_pk_bf16_f32 v53, v34, v35
	global_store_dwordx4 v[54:55], v[50:53], off offset:256 sc0 sc1
	s_cbranch_vccnz .LBB0_713
	v_mul_f32_e32 v35, v35, v35
	v_mul_f32_e32 v33, v33, v33
	v_mul_f32_e32 v41, v41, v41
	v_fmac_f32_e32 v35, v34, v34
	v_fmac_f32_e32 v33, v32, v32
	v_mul_f32_e32 v32, v42, v42
	v_mul_f32_e32 v34, v38, v38
	v_mul_f32_e32 v39, v43, v43
	v_fmac_f32_e32 v41, v40, v40
	v_mul_f32_e32 v40, v48, v48
	v_mul_f32_e32 v43, v46, v46
	v_fmac_f32_e32 v32, v36, v36
	v_fmac_f32_e32 v34, v37, v37
	v_fmac_f32_e32 v40, v44, v44
	v_fmac_f32_e32 v43, v45, v45
	v_add_f32_e32 v32, v32, v34
	v_and_b32_e32 v34, 64, v192
	v_add_f32_e32 v40, v40, v43
	v_add_f32_e32 v32, v33, v32
	v_xor_b32_e32 v33, 16, v192
	v_add_u32_e32 v34, 64, v34
	v_fmac_f32_e32 v39, v47, v47
	v_add_f32_e32 v40, v41, v40
	v_cmp_lt_i32_e32 vcc, v33, v34
	v_add_f32_e32 v39, v39, v40
	v_add_f32_e32 v32, v35, v32
	v_cndmask_b32_e32 v33, v192, v33, vcc
	v_add_f32_e32 v32, v39, v32
	v_lshlrev_b32_e32 v33, 2, v33
	ds_bpermute_b32 v33, v33, v32
	s_waitcnt lgkmcnt(0)
	v_add_f32_e32 v32, v32, v33
	v_xor_b32_e32 v33, 32, v192
	v_cmp_lt_i32_e32 vcc, v33, v34
	s_nop 1
	v_cndmask_b32_e32 v33, v192, v33, vcc
	v_lshlrev_b32_e32 v33, 2, v33
	ds_bpermute_b32 v33, v33, v32
	s_and_saveexec_b64 s[28:29], s[0:1]
	s_cbranch_execz .LBB0_712
	v_lshlrev_b64 v[34:35], 7, v[96:97]
	v_lshl_add_u64 v[34:35], s[24:25], 0, v[34:35]
	v_lshl_add_u64 v[34:35], s[26:27], 2, v[34:35]
	s_lshl_b32 s8, s41, 2
	v_lshl_add_u64 v[34:35], v[34:35], 0, s[8:9]
	s_waitcnt lgkmcnt(0)
	v_add_f32_e32 v32, v32, v33
	global_store_dword v[34:35], v32, off

; __device__ __forceinline__ float bflo(unsigned w) { return __uint_as_float(w << 16); }
; __device__ __forceinline__ float bfhi(unsigned w) { return __uint_as_float(w & 0xffff0000u); }
;     __device__ __forceinline__ void operator()(const f32x4 (&acc)[2][2][4][2], const Unit& u, int wr, int wc, int fr, int fq) const {
;     ...
;                 for (int m = 0; m < 4; ++m) { const size_t off = (size_t)(row0 + ai * HALF + m * 16) * DM + col0;
;                     float ss = 0.f;
; #pragma unroll
;                     for (int bj = 0; bj < 2; ++bj) { const u32x4 q = bs[m][bj]; const f32x4 a0 = acc[ai][bj][m][0], a1 = acc[ai][bj][m][1];
;                         const float h0 = bflo(q.x) + a0[0], h1 = bfhi(q.x) + a0[1], h2 = bflo(q.y) + a0[2], h3 = bfhi(q.y) + a0[3], h4 = bflo(q.z) + a1[0], h5 = bfhi(q.z) + a1[1], h6 = bflo(q.w) + a1[2], h7 = bfhi(q.w) + a1[3];
;                         ss += (h0 * h0 + h1 * h1) + (h2 * h2 + h3 * h3) + (h4 * h4 + h5 * h5) + (h6 * h6 + h7 * h7);
;                         u32x4 w; w.x = pk2(h0, h1); w.y = pk2(h2, h3); w.z = pk2(h4, h5); w.w = pk2(h6, h7);
;                         *(u32x4*)(out + off + bj * HALF) = w; }
;                     if (ssqp) { ss += __shfl_xor(ss, 16); ss += __shfl_xor(ss, 32); if (fq == 0) ssqp[(size_t)(row0 + ai * HALF + m * 16) * 32 + u.pn * 4 + wc] = ss; } }
.LBB0_713:
	s_waitcnt vmcnt(7)
	v_lshlrev_b32_e32 v32, 16, v76
	v_add_f32_e32 v28, v28, v32
	v_and_b32_e32 v32, 0xffff0000, v76
	v_add_f32_e32 v32, v29, v32
	v_lshlrev_b32_e32 v29, 16, v77
	v_add_f32_e32 v29, v30, v29
	v_and_b32_e32 v30, 0xffff0000, v77
	v_add_f32_e32 v30, v31, v30
	v_lshlrev_b32_e32 v31, 16, v78
	v_add_f32_e32 v24, v24, v31
	v_and_b32_e32 v31, 0xffff0000, v78
	v_add_f32_e32 v25, v25, v31
	v_lshlrev_b32_e32 v31, 16, v79
	v_add_f32_e32 v31, v26, v31
	v_and_b32_e32 v26, 0xffff0000, v79
	v_add_f32_e32 v27, v27, v26
	s_waitcnt vmcnt(6)
	v_lshlrev_b32_e32 v26, 16, v72
	v_add_f32_e32 v20, v20, v26
	v_and_b32_e32 v26, 0xffff0000, v72
	v_add_f32_e32 v26, v21, v26
	v_lshlrev_b32_e32 v21, 16, v73
	v_add_f32_e32 v21, v22, v21
	v_and_b32_e32 v22, 0xffff0000, v73
	v_add_f32_e32 v22, v23, v22
	v_lshlrev_b32_e32 v23, 16, v74
	v_add_f32_e32 v16, v16, v23
	v_and_b32_e32 v23, 0xffff0000, v74
	v_add_f32_e32 v17, v17, v23
	v_lshlrev_b32_e32 v23, 16, v75
	v_lshl_add_u64 v[38:39], s[22:23], 0, v[94:95]
	v_add_f32_e32 v18, v18, v23
	v_and_b32_e32 v23, 0xffff0000, v75
	v_cvt_pk_bf16_f32 v34, v28, v32
	v_cvt_pk_bf16_f32 v35, v29, v30
	v_cvt_pk_bf16_f32 v36, v24, v25
	v_cvt_pk_bf16_f32 v37, v31, v27
	v_lshl_add_u64 v[38:39], v[168:169], 1, v[38:39]
	v_add_f32_e32 v19, v19, v23
	global_store_dwordx4 v[38:39], v[34:37], off sc0 sc1
	s_and_b64 vcc, exec, s[6:7]
	s_nop 0
	v_cvt_pk_bf16_f32 v34, v20, v26
	v_cvt_pk_bf16_f32 v35, v21, v22
	v_cvt_pk_bf16_f32 v36, v16, v17
	v_cvt_pk_bf16_f32 v37, v18, v19
	global_store_dwordx4 v[38:39], v[34:37], off offset:256 sc0 sc1
	s_cbranch_vccnz .LBB0_717
	v_mul_f32_e32 v19, v19, v19
	v_mul_f32_e32 v17, v17, v17
	v_mul_f32_e32 v25, v25, v25
	v_fmac_f32_e32 v19, v18, v18
	v_fmac_f32_e32 v17, v16, v16
	v_mul_f32_e32 v16, v26, v26
	v_mul_f32_e32 v18, v22, v22
	v_mul_f32_e32 v23, v27, v27
	v_fmac_f32_e32 v25, v24, v24
	v_mul_f32_e32 v24, v32, v32
	v_mul_f32_e32 v27, v30, v30
	v_fmac_f32_e32 v16, v20, v20
	v_fmac_f32_e32 v18, v21, v21
	v_fmac_f32_e32 v24, v28, v28
	v_fmac_f32_e32 v27, v29, v29
	v_add_f32_e32 v16, v16, v18
	v_and_b32_e32 v18, 64, v192
	v_add_f32_e32 v24, v24, v27
	v_add_f32_e32 v16, v17, v16
	v_xor_b32_e32 v17, 16, v192
	v_add_u32_e32 v18, 64, v18
	v_fmac_f32_e32 v23, v31, v31
	v_add_f32_e32 v24, v25, v24
	v_cmp_lt_i32_e32 vcc, v17, v18
	v_add_f32_e32 v23, v23, v24
	v_add_f32_e32 v16, v19, v16
	v_cndmask_b32_e32 v17, v192, v17, vcc
	v_add_f32_e32 v16, v23, v16
	v_lshlrev_b32_e32 v17, 2, v17
	ds_bpermute_b32 v17, v17, v16
	s_waitcnt lgkmcnt(0)
	v_add_f32_e32 v16, v16, v17
	v_xor_b32_e32 v17, 32, v192
	v_cmp_lt_i32_e32 vcc, v17, v18
	s_nop 1
	v_cndmask_b32_e32 v17, v192, v17, vcc
	v_lshlrev_b32_e32 v17, 2, v17
	ds_bpermute_b32 v17, v17, v16
	s_and_saveexec_b64 s[28:29], s[0:1]
	s_cbranch_execz .LBB0_716
	v_lshlrev_b64 v[18:19], 7, v[92:93]
	v_lshl_add_u64 v[18:19], s[24:25], 0, v[18:19]
	v_lshl_add_u64 v[18:19], s[26:27], 2, v[18:19]
	s_lshl_b32 s8, s41, 2
	v_lshl_add_u64 v[18:19], v[18:19], 0, s[8:9]
	s_waitcnt lgkmcnt(0)
	v_add_f32_e32 v16, v16, v17
	global_store_dword v[18:19], v16, off

; __device__ __forceinline__ float bflo(unsigned w) { return __uint_as_float(w << 16); }
; __device__ __forceinline__ float bfhi(unsigned w) { return __uint_as_float(w & 0xffff0000u); }
;     __device__ __forceinline__ void operator()(const f32x4 (&acc)[2][2][4][2], const Unit& u, int wr, int wc, int fr, int fq) const {
;     ...
;                 for (int m = 0; m < 4; ++m) { const size_t off = (size_t)(row0 + ai * HALF + m * 16) * DM + col0;
;                     float ss = 0.f;
; #pragma unroll
;                     for (int bj = 0; bj < 2; ++bj) { const u32x4 q = bs[m][bj]; const f32x4 a0 = acc[ai][bj][m][0], a1 = acc[ai][bj][m][1];
;                         const float h0 = bflo(q.x) + a0[0], h1 = bfhi(q.x) + a0[1], h2 = bflo(q.y) + a0[2], h3 = bfhi(q.y) + a0[3], h4 = bflo(q.z) + a1[0], h5 = bfhi(q.z) + a1[1], h6 = bflo(q.w) + a1[2], h7 = bfhi(q.w) + a1[3];
;                         ss += (h0 * h0 + h1 * h1) + (h2 * h2 + h3 * h3) + (h4 * h4 + h5 * h5) + (h6 * h6 + h7 * h7);
;                         u32x4 w; w.x = pk2(h0, h1); w.y = pk2(h2, h3); w.z = pk2(h4, h5); w.w = pk2(h6, h7);
;                         *(u32x4*)(out + off + bj * HALF) = w; }
;                     if (ssqp) { ss += __shfl_xor(ss, 16); ss += __shfl_xor(ss, 32); if (fq == 0) ssqp[(size_t)(row0 + ai * HALF + m * 16) * 32 + u.pn * 4 + wc] = ss; } }
.LBB0_717:
	s_waitcnt vmcnt(7)
	v_lshlrev_b32_e32 v16, 16, v68
	v_add_f32_e32 v12, v12, v16
	v_and_b32_e32 v16, 0xffff0000, v68
	v_add_f32_e32 v16, v13, v16
	v_lshlrev_b32_e32 v13, 16, v69
	v_add_f32_e32 v13, v14, v13
	v_and_b32_e32 v14, 0xffff0000, v69
	v_add_f32_e32 v14, v15, v14
	v_lshlrev_b32_e32 v15, 16, v70
	v_add_f32_e32 v8, v8, v15
	v_and_b32_e32 v15, 0xffff0000, v70
	v_add_f32_e32 v9, v9, v15
	v_lshlrev_b32_e32 v15, 16, v71
	v_add_f32_e32 v15, v10, v15
	v_and_b32_e32 v10, 0xffff0000, v71
	v_add_f32_e32 v11, v11, v10
	s_waitcnt vmcnt(6)
	v_lshlrev_b32_e32 v10, 16, v64
	v_add_f32_e32 v4, v4, v10
	v_and_b32_e32 v10, 0xffff0000, v64
	v_add_f32_e32 v10, v5, v10
	v_lshlrev_b32_e32 v5, 16, v65
	v_add_f32_e32 v5, v6, v5
	v_and_b32_e32 v6, 0xffff0000, v65
	v_add_f32_e32 v6, v7, v6
	v_lshlrev_b32_e32 v7, 16, v66
	v_add_f32_e32 v0, v0, v7
	v_and_b32_e32 v7, 0xffff0000, v66
	v_add_f32_e32 v1, v1, v7
	v_lshlrev_b32_e32 v7, 16, v67
	v_lshl_add_u64 v[22:23], s[22:23], 0, v[90:91]
	v_add_f32_e32 v2, v2, v7
	v_and_b32_e32 v7, 0xffff0000, v67
	v_cvt_pk_bf16_f32 v18, v12, v16
	v_cvt_pk_bf16_f32 v19, v13, v14
	v_cvt_pk_bf16_f32 v20, v8, v9
	v_cvt_pk_bf16_f32 v21, v15, v11
	v_lshl_add_u64 v[22:23], v[168:169], 1, v[22:23]
	v_add_f32_e32 v3, v3, v7
	global_store_dwordx4 v[22:23], v[18:21], off sc0 sc1
	s_and_b64 vcc, exec, s[6:7]
	s_nop 0
	v_cvt_pk_bf16_f32 v18, v4, v10
	v_cvt_pk_bf16_f32 v19, v5, v6
	v_cvt_pk_bf16_f32 v20, v0, v1
	v_cvt_pk_bf16_f32 v21, v2, v3
	global_store_dwordx4 v[22:23], v[18:21], off offset:256 sc0 sc1
	s_cbranch_vccnz .LBB0_680
	v_mul_f32_e32 v3, v3, v3
	v_mul_f32_e32 v1, v1, v1
	v_mul_f32_e32 v9, v9, v9
	v_fmac_f32_e32 v3, v2, v2
	v_fmac_f32_e32 v1, v0, v0
	v_mul_f32_e32 v0, v10, v10
	v_mul_f32_e32 v2, v6, v6
	v_mul_f32_e32 v7, v11, v11
	v_fmac_f32_e32 v9, v8, v8
	v_mul_f32_e32 v8, v16, v16
	v_mul_f32_e32 v11, v14, v14
	v_fmac_f32_e32 v0, v4, v4
	v_fmac_f32_e32 v2, v5, v5
	v_fmac_f32_e32 v8, v12, v12
	v_fmac_f32_e32 v11, v13, v13
	v_add_f32_e32 v0, v0, v2
	v_and_b32_e32 v2, 64, v192
	v_add_f32_e32 v8, v8, v11
	v_add_f32_e32 v0, v1, v0
	v_xor_b32_e32 v1, 16, v192
	v_add_u32_e32 v2, 64, v2
	v_fmac_f32_e32 v7, v15, v15
	v_add_f32_e32 v8, v9, v8
	v_cmp_lt_i32_e32 vcc, v1, v2
	v_add_f32_e32 v7, v7, v8
	v_add_f32_e32 v0, v3, v0
	v_cndmask_b32_e32 v1, v192, v1, vcc
	v_add_f32_e32 v0, v7, v0
	v_lshlrev_b32_e32 v1, 2, v1
	ds_bpermute_b32 v1, v1, v0
	s_waitcnt lgkmcnt(0)
	v_add_f32_e32 v0, v0, v1
	v_xor_b32_e32 v1, 32, v192
	v_cmp_lt_i32_e32 vcc, v1, v2
	s_nop 1
	v_cndmask_b32_e32 v1, v192, v1, vcc
	v_lshlrev_b32_e32 v1, 2, v1
	ds_bpermute_b32 v1, v1, v0
	s_and_saveexec_b64 s[6:7], s[0:1]
	s_cbranch_execz .LBB0_679
	v_lshlrev_b64 v[2:3], 7, v[88:89]
	v_lshl_add_u64 v[2:3], s[24:25], 0, v[2:3]
	v_lshl_add_u64 v[2:3], s[26:27], 2, v[2:3]
	s_lshl_b32 s8, s41, 2
	v_lshl_add_u64 v[2:3], v[2:3], 0, s[8:9]
	s_waitcnt lgkmcnt(0)
	v_add_f32_e32 v0, v0, v1
	global_store_dword v[2:3], v0, off
	s_branch .LBB0_679

; #define PG8_STAGE(bufoff, gbase, voff) do { _Pragma("unroll") for (int _i = 0; _i < 2; ++_i) \
;         __builtin_amdgcn_global_load_lds((const unsigned*)((const char*)(gbase) + (voff)[_i]), (LAS unsigned*)(lds + (bufoff) + ldsw + _i * 8192), 16, 0, 0); } while (0)
; #define PG8_LDA(dst, b, h) do { _Pragma("unroll") for (int m = 0; m < 4; ++m) _Pragma("unroll") for (int k = 0; k < 2; ++k) dst[m][k] = *(const LAS bf16x8*)(lds + PG8_SA(b, h) + aoff + m * 2048 + k * 1024); } while (0)
; #define PG8_LDB(dst, b, h) do { _Pragma("unroll") for (int n = 0; n < 2; ++n) _Pragma("unroll") for (int k = 0; k < 2; ++k) dst[n][k] = *(const LAS bf16x8*)(lds + PG8_SB(b, h) + boff + n * 2048 + k * 1024); } while (0)
; #define PG8_MMA(ai, bj, At, Bt) do { __builtin_amdgcn_s_setprio(1); _Pragma("unroll") for (int m = 0; m < 4; ++m) _Pragma("unroll") for (int n = 0; n < 2; ++n) _Pragma("unroll") for (int k = 0; k < 2; ++k) \
;         acc[ai][bj][m][n] = __builtin_amdgcn_mfma_f32_16x16x32_bf16(Bt[n][k], At[m][k], acc[ai][bj][m][n], 0, 0, 0); __builtin_amdgcn_s_setprio(0); } while (0)
; #define PG8_WAIT_V(n) asm volatile("s_waitcnt vmcnt(" #n ")" ::: "memory")
; #define PG8_WAIT_L(n) asm volatile("s_waitcnt lgkmcnt(" #n ")" ::: "memory")
; #define PG8_BAR __builtin_amdgcn_s_barrier()
; #define PG8_SCHED __builtin_amdgcn_sched_barrier(0)
; template <class Epi>
; __device__ __forceinline__ void gemm_phase(LAS unsigned char* lds, const Gemm g, const Order& S, const Epi& E, const int tid) {
;     ...
;             PG8_LDB(B0, 0, 0); PG8_SCHED; PG8_LDA(At, 0, 0); PG8_STAGE(PG8_SA(1, 1), a1 + hstepA, voffA);
;             PG8_WAIT_L(8); PG8_BAR; PG8_WAIT_L(0); PG8_MMA(0, 0, At, B0); PG8_BAR; PG8_SCHED;
;             PG8_LDB(B1, 0, 1); PG8_STAGE(PG8_SB(0, 0), b2, voffB);
;             PG8_BAR; PG8_WAIT_L(0); PG8_MMA(0, 1, At, B1); PG8_BAR;
;             PG8_LDA(At, 0, 1); PG8_STAGE(PG8_SA(0, 0), a2, voffA);
;             PG8_BAR; PG8_WAIT_L(0); PG8_MMA(1, 0, At, B0); PG8_BAR; PG8_SCHED;
;             PG8_STAGE(PG8_SB(0, 1), b2 + hstepB, voffB);
;             PG8_WAIT_V(6); PG8_BAR; PG8_MMA(1, 1, At, B1); PG8_BAR;
;             PG8_LDB(B0, 1, 0); PG8_SCHED; PG8_LDA(At, 1, 0); PG8_STAGE(PG8_SA(0, 1), a2 + hstepA, voffA);
;             PG8_WAIT_L(8); PG8_BAR; PG8_WAIT_L(0); PG8_MMA(0, 0, At, B0); PG8_BAR; PG8_SCHED;
.LBB0_846:
	ds_read_b128 v[128:131], v189
	ds_read_b128 v[132:135], v189 offset:1024
	ds_read_b128 v[136:139], v189 offset:2048
	ds_read_b128 v[140:143], v189 offset:3072
	s_add_u32 s28, s26, 0xfff80080
	s_addc_u32 s29, s27, -1
	s_cmp_eq_u32 s50, 28
	s_cselect_b32 s31, s7, s29
	s_cselect_b32 s30, s15, s28
	s_cselect_b32 s29, s17, s49
	s_cselect_b32 s28, s47, s48
	v_lshl_add_u64 v[184:185], s[26:27], 0, v[160:161]
	s_add_i32 m0, s34, 0xc000
	ds_read_b128 v[144:147], v190
	ds_read_b128 v[148:151], v190 offset:1024
	ds_read_b128 v[168:171], v190 offset:2048
	ds_read_b128 v[172:175], v190 offset:3072
	ds_read_b128 v[176:179], v190 offset:4096
	ds_read_b128 v[180:183], v190 offset:5120
	ds_read_b128 v[194:197], v190 offset:6144
	ds_read_b128 v[198:201], v190 offset:7168
	global_load_lds_dwordx4 v[184:185], off
	v_lshl_add_u64 v[184:185], s[26:27], 0, v[162:163]
	s_add_i32 m0, s34, 0xe000
	s_nop 0
	global_load_lds_dwordx4 v[184:185], off
	s_waitcnt lgkmcnt(8)
	s_barrier
	s_waitcnt lgkmcnt(0)
	s_setprio 1
	s_waitcnt lgkmcnt(0)
	v_mfma_f32_16x16x32_bf16 v[124:127], v[128:131], v[144:147], v[124:127]
	v_mfma_f32_16x16x32_bf16 v[120:123], v[136:139], v[144:147], v[120:123]
	v_mfma_f32_16x16x32_bf16 v[108:111], v[128:131], v[168:171], v[108:111]
	v_mfma_f32_16x16x32_bf16 v[104:107], v[136:139], v[168:171], v[104:107]
	v_mfma_f32_16x16x32_bf16 v[92:95], v[128:131], v[176:179], v[92:95]
	v_mfma_f32_16x16x32_bf16 v[88:91], v[136:139], v[176:179], v[88:91]
	v_mfma_f32_16x16x32_bf16 v[76:79], v[128:131], v[194:197], v[76:79]
	v_mfma_f32_16x16x32_bf16 v[72:75], v[136:139], v[194:197], v[72:75]
	v_mfma_f32_16x16x32_bf16 v[124:127], v[132:135], v[148:151], v[124:127]
	v_mfma_f32_16x16x32_bf16 v[120:123], v[140:143], v[148:151], v[120:123]
	v_mfma_f32_16x16x32_bf16 v[108:111], v[132:135], v[172:175], v[108:111]
	v_mfma_f32_16x16x32_bf16 v[104:107], v[140:143], v[172:175], v[104:107]
	v_mfma_f32_16x16x32_bf16 v[92:95], v[132:135], v[180:183], v[92:95]
	v_mfma_f32_16x16x32_bf16 v[88:91], v[140:143], v[180:183], v[88:91]
	v_mfma_f32_16x16x32_bf16 v[76:79], v[132:135], v[198:201], v[76:79]
	v_mfma_f32_16x16x32_bf16 v[72:75], v[140:143], v[198:201], v[72:75]
	s_setprio 0
	s_barrier
	s_add_i32 s51, s44, s33
	v_lshl_add_u64 v[184:185], s[28:29], 0, v[154:155]
	s_mov_b32 m0, s51
	ds_read_b128 v[202:205], v191
	ds_read_b128 v[206:209], v191 offset:1024
	ds_read_b128 v[210:213], v191 offset:2048
	ds_read_b128 v[214:217], v191 offset:3072
	global_load_lds_dwordx4 v[184:185], off
	v_lshl_add_u64 v[218:219], s[28:29], 0, v[158:159]
	s_add_i32 m0, s51, 0x2000
	s_nop 0
	global_load_lds_dwordx4 v[218:219], off
	s_barrier
	s_waitcnt lgkmcnt(0)
	s_setprio 1
	s_waitcnt lgkmcnt(0)
	v_mfma_f32_16x16x32_bf16 v[116:119], v[202:205], v[144:147], v[116:119]
	v_mfma_f32_16x16x32_bf16 v[112:115], v[210:213], v[144:147], v[112:115]
	v_mfma_f32_16x16x32_bf16 v[100:103], v[202:205], v[168:171], v[100:103]
	v_mfma_f32_16x16x32_bf16 v[96:99], v[210:213], v[168:171], v[96:99]
	v_mfma_f32_16x16x32_bf16 v[84:87], v[202:205], v[176:179], v[84:87]
	v_mfma_f32_16x16x32_bf16 v[80:83], v[210:213], v[176:179], v[80:83]
	v_mfma_f32_16x16x32_bf16 v[68:71], v[202:205], v[194:197], v[68:71]
	v_mfma_f32_16x16x32_bf16 v[64:67], v[210:213], v[194:197], v[64:67]
	v_mfma_f32_16x16x32_bf16 v[116:119], v[206:209], v[148:151], v[116:119]
	v_mfma_f32_16x16x32_bf16 v[112:115], v[214:217], v[148:151], v[112:115]
	v_mfma_f32_16x16x32_bf16 v[100:103], v[206:209], v[172:175], v[100:103]
	v_mfma_f32_16x16x32_bf16 v[96:99], v[214:217], v[172:175], v[96:99]
	v_mfma_f32_16x16x32_bf16 v[84:87], v[206:209], v[180:183], v[84:87]
	v_mfma_f32_16x16x32_bf16 v[80:83], v[214:217], v[180:183], v[80:83]
	v_mfma_f32_16x16x32_bf16 v[68:71], v[206:209], v[198:201], v[68:71]
	v_mfma_f32_16x16x32_bf16 v[64:67], v[214:217], v[198:201], v[64:67]
	s_setprio 0
	s_mov_b32 m0, s34
	v_lshl_add_u64 v[220:221], s[30:31], 0, v[152:153]
	s_barrier
	ds_read_b128 v[144:147], v190 offset:16384
	ds_read_b128 v[148:151], v190 offset:17408
	ds_read_b128 v[168:171], v190 offset:18432
	ds_read_b128 v[172:175], v190 offset:19456
	ds_read_b128 v[176:179], v190 offset:20480
	ds_read_b128 v[180:183], v190 offset:21504
	ds_read_b128 v[194:197], v190 offset:22528
	ds_read_b128 v[198:201], v190 offset:23552
	global_load_lds_dwordx4 v[220:221], off
	v_lshl_add_u64 v[222:223], s[30:31], 0, v[156:157]
	s_mov_b32 m0, s35
	s_nop 0
	global_load_lds_dwordx4 v[222:223], off
	s_barrier
	s_waitcnt lgkmcnt(0)
	s_setprio 1
	s_waitcnt lgkmcnt(0)
	v_mfma_f32_16x16x32_bf16 v[60:63], v[128:131], v[144:147], v[60:63]
	v_mfma_f32_16x16x32_bf16 v[56:59], v[136:139], v[144:147], v[56:59]
	v_mfma_f32_16x16x32_bf16 v[44:47], v[128:131], v[168:171], v[44:47]
	v_mfma_f32_16x16x32_bf16 v[40:43], v[136:139], v[168:171], v[40:43]
	v_mfma_f32_16x16x32_bf16 v[28:31], v[128:131], v[176:179], v[28:31]
	v_mfma_f32_16x16x32_bf16 v[24:27], v[136:139], v[176:179], v[24:27]
	v_mfma_f32_16x16x32_bf16 v[12:15], v[128:131], v[194:197], v[12:15]
	v_mfma_f32_16x16x32_bf16 v[8:11], v[136:139], v[194:197], v[8:11]
	v_mfma_f32_16x16x32_bf16 v[60:63], v[132:135], v[148:151], v[60:63]
	v_mfma_f32_16x16x32_bf16 v[56:59], v[140:143], v[148:151], v[56:59]
	v_mfma_f32_16x16x32_bf16 v[44:47], v[132:135], v[172:175], v[44:47]
	v_mfma_f32_16x16x32_bf16 v[40:43], v[140:143], v[172:175], v[40:43]
	v_mfma_f32_16x16x32_bf16 v[28:31], v[132:135], v[180:183], v[28:31]
	v_mfma_f32_16x16x32_bf16 v[24:27], v[140:143], v[180:183], v[24:27]
	v_mfma_f32_16x16x32_bf16 v[12:15], v[132:135], v[198:201], v[12:15]
	v_mfma_f32_16x16x32_bf16 v[8:11], v[140:143], v[198:201], v[8:11]
	s_setprio 0
	s_barrier
; #define PG8_STAGE(bufoff, gbase, voff) do { _Pragma("unroll") for (int _i = 0; _i < 2; ++_i) \
;         __builtin_amdgcn_global_load_lds((const unsigned*)((const char*)(gbase) + (voff)[_i]), (LAS unsigned*)(lds + (bufoff) + ldsw + _i * 8192), 16, 0, 0); } while (0)
; #define PG8_LDA(dst, b, h) do { _Pragma("unroll") for (int m = 0; m < 4; ++m) _Pragma("unroll") for (int k = 0; k < 2; ++k) dst[m][k] = *(const LAS bf16x8*)(lds + PG8_SA(b, h) + aoff + m * 2048 + k * 1024); } while (0)
; #define PG8_LDB(dst, b, h) do { _Pragma("unroll") for (int n = 0; n < 2; ++n) _Pragma("unroll") for (int k = 0; k < 2; ++k) dst[n][k] = *(const LAS bf16x8*)(lds + PG8_SB(b, h) + boff + n * 2048 + k * 1024); } while (0)
; #define PG8_MMA(ai, bj, At, Bt) do { __builtin_amdgcn_s_setprio(1); _Pragma("unroll") for (int m = 0; m < 4; ++m) _Pragma("unroll") for (int n = 0; n < 2; ++n) _Pragma("unroll") for (int k = 0; k < 2; ++k) \
;         acc[ai][bj][m][n] = __builtin_amdgcn_mfma_f32_16x16x32_bf16(Bt[n][k], At[m][k], acc[ai][bj][m][n], 0, 0, 0); __builtin_amdgcn_s_setprio(0); } while (0)
; #define PG8_WAIT_V(n) asm volatile("s_waitcnt vmcnt(" #n ")" ::: "memory")
; #define PG8_WAIT_L(n) asm volatile("s_waitcnt lgkmcnt(" #n ")" ::: "memory")
; #define PG8_BAR __builtin_amdgcn_s_barrier()
; #define PG8_SCHED __builtin_amdgcn_sched_barrier(0)
; template <class Epi>
; __device__ __forceinline__ void gemm_phase(LAS unsigned char* lds, const Gemm g, const Order& S, const Epi& E, const int tid) {
;     ...
;             PG8_STAGE(PG8_SB(0, 1), b2 + hstepB, voffB);
;             PG8_WAIT_V(6); PG8_BAR; PG8_MMA(1, 1, At, B1); PG8_BAR;
;             PG8_LDB(B0, 1, 0); PG8_SCHED; PG8_LDA(At, 1, 0); PG8_STAGE(PG8_SA(0, 1), a2 + hstepA, voffA);
;             PG8_WAIT_L(8); PG8_BAR; PG8_WAIT_L(0); PG8_MMA(0, 0, At, B0); PG8_BAR; PG8_SCHED;
;             PG8_LDB(B1, 1, 1); PG8_STAGE(PG8_SB(1, 0), b3, voffB);
;             PG8_BAR; PG8_WAIT_L(0); PG8_MMA(0, 1, At, B1); PG8_BAR;
;             PG8_LDA(At, 1, 1); PG8_STAGE(PG8_SA(1, 0), a3, voffA);
	s_add_u32 s52, s28, 0x80000
	s_addc_u32 s53, s29, 0
	s_add_i32 s51, s45, s33
	v_lshl_add_u64 v[128:129], s[52:53], 0, v[154:155]
	s_mov_b32 m0, s51
	s_nop 0
	global_load_lds_dwordx4 v[128:129], off
	v_lshl_add_u64 v[128:129], s[52:53], 0, v[158:159]
	s_add_i32 m0, s51, 0x2000
	s_nop 0
	global_load_lds_dwordx4 v[128:129], off
	s_waitcnt vmcnt(6)
	s_barrier
	s_setprio 1
	v_mfma_f32_16x16x32_bf16 v[52:55], v[202:205], v[144:147], v[52:55]
	v_mfma_f32_16x16x32_bf16 v[48:51], v[210:213], v[144:147], v[48:51]
	v_mfma_f32_16x16x32_bf16 v[36:39], v[202:205], v[168:171], v[36:39]
	v_mfma_f32_16x16x32_bf16 v[32:35], v[210:213], v[168:171], v[32:35]
	v_mfma_f32_16x16x32_bf16 v[20:23], v[202:205], v[176:179], v[20:23]
	v_mfma_f32_16x16x32_bf16 v[16:19], v[210:213], v[176:179], v[16:19]
	v_mfma_f32_16x16x32_bf16 v[4:7], v[202:205], v[194:197], v[4:7]
	v_mfma_f32_16x16x32_bf16 v[0:3], v[210:213], v[194:197], v[0:3]
	v_mfma_f32_16x16x32_bf16 v[52:55], v[206:209], v[148:151], v[52:55]
	v_mfma_f32_16x16x32_bf16 v[48:51], v[214:217], v[148:151], v[48:51]
	v_mfma_f32_16x16x32_bf16 v[36:39], v[206:209], v[172:175], v[36:39]
	v_mfma_f32_16x16x32_bf16 v[32:35], v[214:217], v[172:175], v[32:35]
	v_mfma_f32_16x16x32_bf16 v[20:23], v[206:209], v[180:183], v[20:23]
	v_mfma_f32_16x16x32_bf16 v[16:19], v[214:217], v[180:183], v[16:19]
	v_mfma_f32_16x16x32_bf16 v[4:7], v[206:209], v[198:201], v[4:7]
	v_mfma_f32_16x16x32_bf16 v[0:3], v[214:217], v[198:201], v[0:3]
	s_setprio 0
	s_add_i32 s51, 0, 0x18000
	v_add_u32_e32 v140, s51, v187
	s_barrier
	ds_read_b128 v[128:131], v140
	ds_read_b128 v[132:135], v140 offset:1024
	ds_read_b128 v[136:139], v140 offset:2048
	ds_read_b128 v[140:143], v140 offset:3072
	s_add_u32 s30, s30, 0x80000
	s_addc_u32 s31, s31, 0
	s_mov_b32 m0, s38
	v_lshl_add_u64 v[202:203], s[30:31], 0, v[152:153]
	ds_read_b128 v[144:147], v190 offset:32768
	ds_read_b128 v[148:151], v190 offset:33792
	ds_read_b128 v[168:171], v190 offset:34816
	ds_read_b128 v[172:175], v190 offset:35840
	ds_read_b128 v[176:179], v190 offset:36864
	ds_read_b128 v[180:183], v190 offset:37888
	ds_read_b128 v[194:197], v190 offset:38912
	ds_read_b128 v[198:201], v190 offset:39936
	global_load_lds_dwordx4 v[202:203], off
	v_lshl_add_u64 v[202:203], s[30:31], 0, v[156:157]
	s_mov_b32 m0, s39
	s_nop 0
	global_load_lds_dwordx4 v[202:203], off
	s_waitcnt lgkmcnt(8)
	s_barrier
	s_waitcnt lgkmcnt(0)
	s_setprio 1
	s_waitcnt lgkmcnt(0)
	v_mfma_f32_16x16x32_bf16 v[124:127], v[128:131], v[144:147], v[124:127]
	v_mfma_f32_16x16x32_bf16 v[120:123], v[136:139], v[144:147], v[120:123]
	v_mfma_f32_16x16x32_bf16 v[108:111], v[128:131], v[168:171], v[108:111]
	v_mfma_f32_16x16x32_bf16 v[104:107], v[136:139], v[168:171], v[104:107]
	v_mfma_f32_16x16x32_bf16 v[92:95], v[128:131], v[176:179], v[92:95]
	v_mfma_f32_16x16x32_bf16 v[88:91], v[136:139], v[176:179], v[88:91]
	v_mfma_f32_16x16x32_bf16 v[76:79], v[128:131], v[194:197], v[76:79]
	v_mfma_f32_16x16x32_bf16 v[72:75], v[136:139], v[194:197], v[72:75]
	v_mfma_f32_16x16x32_bf16 v[124:127], v[132:135], v[148:151], v[124:127]
	v_mfma_f32_16x16x32_bf16 v[120:123], v[140:143], v[148:151], v[120:123]
	v_mfma_f32_16x16x32_bf16 v[108:111], v[132:135], v[172:175], v[108:111]
	v_mfma_f32_16x16x32_bf16 v[104:107], v[140:143], v[172:175], v[104:107]
	v_mfma_f32_16x16x32_bf16 v[92:95], v[132:135], v[180:183], v[92:95]
	v_mfma_f32_16x16x32_bf16 v[88:91], v[140:143], v[180:183], v[88:91]
	v_mfma_f32_16x16x32_bf16 v[76:79], v[132:135], v[198:201], v[76:79]
	v_mfma_f32_16x16x32_bf16 v[72:75], v[140:143], v[198:201], v[72:75]
	s_setprio 0
	s_barrier
	s_add_i32 s30, 0, 0x1c000
	s_add_i32 s31, s51, s33
	v_add_u32_e32 v193, s30, v187
	v_lshl_add_u64 v[184:185], v[184:185], 0, s[12:13]
	s_mov_b32 m0, s31
	ds_read_b128 v[202:205], v193
	ds_read_b128 v[206:209], v193 offset:1024
	ds_read_b128 v[210:213], v193 offset:2048
	ds_read_b128 v[214:217], v193 offset:3072
	global_load_lds_dwordx4 v[184:185], off
	v_lshl_add_u64 v[184:185], v[218:219], 0, s[12:13]
	s_add_i32 m0, s31, 0x2000
	s_nop 0
	global_load_lds_dwordx4 v[184:185], off
	s_barrier
	s_waitcnt lgkmcnt(0)
	s_setprio 1
	s_waitcnt lgkmcnt(0)
	v_mfma_f32_16x16x32_bf16 v[116:119], v[202:205], v[144:147], v[116:119]
	v_mfma_f32_16x16x32_bf16 v[112:115], v[210:213], v[144:147], v[112:115]
	v_mfma_f32_16x16x32_bf16 v[100:103], v[202:205], v[168:171], v[100:103]
	v_mfma_f32_16x16x32_bf16 v[96:99], v[210:213], v[168:171], v[96:99]
	v_mfma_f32_16x16x32_bf16 v[84:87], v[202:205], v[176:179], v[84:87]
	v_mfma_f32_16x16x32_bf16 v[80:83], v[210:213], v[176:179], v[80:83]
	v_mfma_f32_16x16x32_bf16 v[68:71], v[202:205], v[194:197], v[68:71]
	v_mfma_f32_16x16x32_bf16 v[64:67], v[210:213], v[194:197], v[64:67]
	v_mfma_f32_16x16x32_bf16 v[116:119], v[206:209], v[148:151], v[116:119]
	v_mfma_f32_16x16x32_bf16 v[112:115], v[214:217], v[148:151], v[112:115]
	v_mfma_f32_16x16x32_bf16 v[100:103], v[206:209], v[172:175], v[100:103]
	v_mfma_f32_16x16x32_bf16 v[96:99], v[214:217], v[172:175], v[96:99]
	v_mfma_f32_16x16x32_bf16 v[84:87], v[206:209], v[180:183], v[84:87]
	v_mfma_f32_16x16x32_bf16 v[80:83], v[214:217], v[180:183], v[80:83]
	v_mfma_f32_16x16x32_bf16 v[68:71], v[206:209], v[198:201], v[68:71]
	v_mfma_f32_16x16x32_bf16 v[64:67], v[214:217], v[198:201], v[64:67]
	s_setprio 0
	s_mov_b32 m0, s42
	v_lshl_add_u64 v[184:185], v[220:221], 0, s[12:13]
	s_barrier
	ds_read_b128 v[144:147], v190 offset:49152
	ds_read_b128 v[148:151], v190 offset:50176
	ds_read_b128 v[168:171], v190 offset:51200
	ds_read_b128 v[172:175], v190 offset:52224
	ds_read_b128 v[176:179], v190 offset:53248
	ds_read_b128 v[180:183], v190 offset:54272
	ds_read_b128 v[194:197], v190 offset:55296
	ds_read_b128 v[198:201], v190 offset:56320
	global_load_lds_dwordx4 v[184:185], off
	v_lshl_add_u64 v[184:185], v[222:223], 0, s[12:13]
	s_mov_b32 m0, s43
	s_nop 0
	global_load_lds_dwordx4 v[184:185], off
	s_barrier
; #define PG8_STAGE(bufoff, gbase, voff) do { _Pragma("unroll") for (int _i = 0; _i < 2; ++_i) \
;         __builtin_amdgcn_global_load_lds((const unsigned*)((const char*)(gbase) + (voff)[_i]), (LAS unsigned*)(lds + (bufoff) + ldsw + _i * 8192), 16, 0, 0); } while (0)
; #define PG8_MMA(ai, bj, At, Bt) do { __builtin_amdgcn_s_setprio(1); _Pragma("unroll") for (int m = 0; m < 4; ++m) _Pragma("unroll") for (int n = 0; n < 2; ++n) _Pragma("unroll") for (int k = 0; k < 2; ++k) \
;         acc[ai][bj][m][n] = __builtin_amdgcn_mfma_f32_16x16x32_bf16(Bt[n][k], At[m][k], acc[ai][bj][m][n], 0, 0, 0); __builtin_amdgcn_s_setprio(0); } while (0)
; #define PG8_WAIT_V(n) asm volatile("s_waitcnt vmcnt(" #n ")" ::: "memory")
; #define PG8_WAIT_L(n) asm volatile("s_waitcnt lgkmcnt(" #n ")" ::: "memory")
; #define PG8_BAR __builtin_amdgcn_s_barrier()
; #define PG8_SCHED __builtin_amdgcn_sched_barrier(0)
; template <class Epi>
; __device__ __forceinline__ void gemm_phase(LAS unsigned char* lds, const Gemm g, const Order& S, const Epi& E, const int tid) {
;     ...
;             PG8_BAR; PG8_WAIT_L(0); PG8_MMA(1, 0, At, B0); PG8_BAR; PG8_SCHED;
;             PG8_STAGE(PG8_SB(1, 1), b3 + hstepB, voffB);
;             PG8_WAIT_V(6); PG8_BAR; PG8_MMA(1, 1, At, B1); PG8_BAR;
	s_waitcnt lgkmcnt(0)
	s_setprio 1
	s_waitcnt lgkmcnt(0)
	v_mfma_f32_16x16x32_bf16 v[60:63], v[128:131], v[144:147], v[60:63]
	v_mfma_f32_16x16x32_bf16 v[56:59], v[136:139], v[144:147], v[56:59]
	v_mfma_f32_16x16x32_bf16 v[44:47], v[128:131], v[168:171], v[44:47]
	v_mfma_f32_16x16x32_bf16 v[40:43], v[136:139], v[168:171], v[40:43]
	v_mfma_f32_16x16x32_bf16 v[28:31], v[128:131], v[176:179], v[28:31]
	v_mfma_f32_16x16x32_bf16 v[24:27], v[136:139], v[176:179], v[24:27]
	v_mfma_f32_16x16x32_bf16 v[12:15], v[128:131], v[194:197], v[12:15]
	v_mfma_f32_16x16x32_bf16 v[8:11], v[136:139], v[194:197], v[8:11]
	v_mfma_f32_16x16x32_bf16 v[60:63], v[132:135], v[148:151], v[60:63]
	v_mfma_f32_16x16x32_bf16 v[56:59], v[140:143], v[148:151], v[56:59]
	v_mfma_f32_16x16x32_bf16 v[44:47], v[132:135], v[172:175], v[44:47]
	v_mfma_f32_16x16x32_bf16 v[40:43], v[140:143], v[172:175], v[40:43]
	v_mfma_f32_16x16x32_bf16 v[28:31], v[132:135], v[180:183], v[28:31]
	v_mfma_f32_16x16x32_bf16 v[24:27], v[140:143], v[180:183], v[24:27]
	v_mfma_f32_16x16x32_bf16 v[12:15], v[132:135], v[198:201], v[12:15]
	v_mfma_f32_16x16x32_bf16 v[8:11], v[140:143], v[198:201], v[8:11]
	s_setprio 0
	s_barrier
	s_add_u32 s28, s28, 0x80080
	s_addc_u32 s29, s29, 0
	s_add_i32 s30, s30, s33
	v_lshl_add_u64 v[128:129], s[28:29], 0, v[154:155]
	s_mov_b32 m0, s30
	s_nop 0
	global_load_lds_dwordx4 v[128:129], off
	v_lshl_add_u64 v[128:129], s[28:29], 0, v[158:159]
	s_add_i32 m0, s30, 0x2000
	s_nop 0
	global_load_lds_dwordx4 v[128:129], off
	s_waitcnt vmcnt(6)
	s_barrier
	s_setprio 1
	v_mfma_f32_16x16x32_bf16 v[52:55], v[202:205], v[144:147], v[52:55]
	v_mfma_f32_16x16x32_bf16 v[48:51], v[210:213], v[144:147], v[48:51]
	v_mfma_f32_16x16x32_bf16 v[36:39], v[202:205], v[168:171], v[36:39]
	v_mfma_f32_16x16x32_bf16 v[32:35], v[210:213], v[168:171], v[32:35]
	v_mfma_f32_16x16x32_bf16 v[20:23], v[202:205], v[176:179], v[20:23]
	v_mfma_f32_16x16x32_bf16 v[16:19], v[210:213], v[176:179], v[16:19]
	v_mfma_f32_16x16x32_bf16 v[4:7], v[202:205], v[194:197], v[4:7]
	v_mfma_f32_16x16x32_bf16 v[0:3], v[210:213], v[194:197], v[0:3]
	v_mfma_f32_16x16x32_bf16 v[52:55], v[206:209], v[148:151], v[52:55]
	v_mfma_f32_16x16x32_bf16 v[48:51], v[214:217], v[148:151], v[48:51]
	v_mfma_f32_16x16x32_bf16 v[36:39], v[206:209], v[172:175], v[36:39]
	v_mfma_f32_16x16x32_bf16 v[32:35], v[214:217], v[172:175], v[32:35]
	v_mfma_f32_16x16x32_bf16 v[20:23], v[206:209], v[180:183], v[20:23]
	v_mfma_f32_16x16x32_bf16 v[16:19], v[214:217], v[180:183], v[16:19]
	v_mfma_f32_16x16x32_bf16 v[4:7], v[206:209], v[198:201], v[4:7]
	v_mfma_f32_16x16x32_bf16 v[0:3], v[214:217], v[198:201], v[0:3]
	s_setprio 0
	s_add_i32 s50, s50, 2
	s_add_u32 s26, s26, 0x100
	s_addc_u32 s27, s27, 0
	s_add_u32 s48, s48, 0x100
	s_addc_u32 s49, s49, 0
	s_cmp_gt_u32 s50, 29
	s_barrier
	s_cbranch_scc0 .LBB0_846
; __device__ __forceinline__ float bflo(unsigned w) { return __uint_as_float(w << 16); }
; __device__ __forceinline__ float bfhi(unsigned w) { return __uint_as_float(w & 0xffff0000u); }
;     __device__ __forceinline__ void operator()(const f32x4 (&acc)[2][2][4][2], const Unit& u, int wr, int wc, int fr, int fq) const {
;     ...
;                 u32x4 bs[4][2];
; #pragma unroll
;                 for (int m = 0; m < 4; ++m) { const size_t off = (size_t)(row0 + ai * HALF + m * 16) * DM + col0;
; #pragma unroll
;                     for (int bj = 0; bj < 2; ++bj) bs[m][bj] = *(const u32x4*)(baseb + off + bj * HALF); }
; #pragma unroll
;                 for (int m = 0; m < 4; ++m) { const size_t off = (size_t)(row0 + ai * HALF + m * 16) * DM + col0;
;                     float ss = 0.f;
; #pragma unroll
;                     for (int bj = 0; bj < 2; ++bj) { const u32x4 q = bs[m][bj]; const f32x4 a0 = acc[ai][bj][m][0], a1 = acc[ai][bj][m][1];
;                         const float h0 = bflo(q.x) + a0[0], h1 = bfhi(q.x) + a0[1], h2 = bflo(q.y) + a0[2], h3 = bfhi(q.y) + a0[3], h4 = bflo(q.z) + a1[0], h5 = bfhi(q.z) + a1[1], h6 = bflo(q.w) + a1[2], h7 = bfhi(q.w) + a1[3];
;                         ss += (h0 * h0 + h1 * h1) + (h2 * h2 + h3 * h3) + (h4 * h4 + h5 * h5) + (h6 * h6 + h7 * h7);
;                         u32x4 w; w.x = pk2(h0, h1); w.y = pk2(h2, h3); w.z = pk2(h4, h5); w.w = pk2(h6, h7);
;                         *(u32x4*)(out + off + bj * HALF) = w; }
;                     if (ssqp) { ss += __shfl_xor(ss, 16); ss += __shfl_xor(ss, 32); if (fq == 0) ssqp[(size_t)(row0 + ai * HALF + m * 16) * 32 + u.pn * 4 + wc] = ss; } }
	v_lshl_or_b32 v168, s6, 8, v188
	v_lshl_add_u32 v172, s8, 8, v186
	v_ashrrev_i32_e32 v169, 31, v168
	v_lshlrev_b64 v[202:203], 1, v[168:169]
	v_ashrrev_i32_e32 v173, 31, v172
	v_or_b32_e32 v182, 16, v172
	v_or_b32_e32 v178, 32, v172
	v_lshl_add_u64 v[170:171], s[22:23], 0, v[202:203]
	v_lshlrev_b64 v[204:205], 12, v[172:173]
	v_or_b32_e32 v174, 48, v172
	v_ashrrev_i32_e32 v183, 31, v182
	v_ashrrev_i32_e32 v179, 31, v178
	v_lshl_add_u64 v[128:129], v[170:171], 0, v[204:205]
	v_ashrrev_i32_e32 v175, 31, v174
	v_lshlrev_b64 v[184:185], 12, v[182:183]
	v_lshlrev_b64 v[180:181], 12, v[178:179]
	global_load_dwordx4 v[194:197], v[128:129], off
	global_load_dwordx4 v[198:201], v[128:129], off offset:256
	v_lshlrev_b64 v[176:177], 12, v[174:175]
	v_lshl_add_u64 v[128:129], v[170:171], 0, v[184:185]
	v_lshl_add_u64 v[130:131], v[170:171], 0, v[180:181]
	v_lshl_add_u64 v[206:207], v[170:171], 0, v[176:177]
	global_load_dwordx4 v[148:151], v[128:129], off
	global_load_dwordx4 v[144:147], v[128:129], off offset:256
	global_load_dwordx4 v[140:143], v[130:131], off
	global_load_dwordx4 v[136:139], v[130:131], off offset:256
	global_load_dwordx4 v[132:135], v[206:207], off
	s_nop 0
	global_load_dwordx4 v[128:131], v[206:207], off offset:256
	v_cndmask_b32_e64 v193, 0, 1, s[10:11]
	v_lshl_add_u64 v[204:205], s[22:23], 0, v[204:205]
	s_lshl_b32 s26, s6, 2
	v_cmp_ne_u32_e64 s[6:7], 1, v193
	v_lshl_add_u64 v[204:205], v[204:205], 0, v[202:203]
	s_ashr_i32 s27, s26, 31
	s_andn2_b64 vcc, exec, s[10:11]
	s_waitcnt vmcnt(0)
	v_lshlrev_b32_e32 v193, 16, v194
	v_and_b32_e32 v194, 0xffff0000, v194
	v_lshlrev_b32_e32 v202, 16, v195
	v_and_b32_e32 v195, 0xffff0000, v195
	v_lshlrev_b32_e32 v203, 16, v196
	v_and_b32_e32 v196, 0xffff0000, v196
	v_lshlrev_b32_e32 v206, 16, v197
	v_and_b32_e32 v197, 0xffff0000, v197
	v_lshlrev_b32_e32 v207, 16, v198
	v_and_b32_e32 v198, 0xffff0000, v198
	v_lshlrev_b32_e32 v208, 16, v199
	v_and_b32_e32 v199, 0xffff0000, v199
	v_lshlrev_b32_e32 v209, 16, v200
	v_and_b32_e32 v200, 0xffff0000, v200
	v_lshlrev_b32_e32 v210, 16, v201
	v_and_b32_e32 v201, 0xffff0000, v201
	v_add_f32_e32 v193, v124, v193
	v_add_f32_e32 v194, v125, v194
	v_add_f32_e32 v124, v126, v202
	v_add_f32_e32 v125, v127, v195
	v_add_f32_e32 v126, v120, v203
	v_add_f32_e32 v127, v121, v196
	v_add_f32_e32 v122, v122, v206
	v_add_f32_e32 v123, v123, v197
	v_add_f32_e32 v120, v116, v207
	v_add_f32_e32 v121, v117, v198
	v_add_f32_e32 v116, v118, v208
	v_add_f32_e32 v117, v119, v199
	v_add_f32_e32 v112, v112, v209
	v_add_f32_e32 v113, v113, v200
	v_add_f32_e32 v114, v114, v210
	v_add_f32_e32 v115, v115, v201
	v_cvt_pk_bf16_f32 v196, v193, v194
	v_cvt_pk_bf16_f32 v197, v124, v125
	v_cvt_pk_bf16_f32 v198, v126, v127
	v_cvt_pk_bf16_f32 v199, v122, v123
	v_cvt_pk_bf16_f32 v200, v120, v121
	v_cvt_pk_bf16_f32 v201, v116, v117
	v_cvt_pk_bf16_f32 v202, v112, v113
	v_cvt_pk_bf16_f32 v203, v114, v115
	global_store_dwordx4 v[204:205], v[196:199], off sc0 sc1
	global_store_dwordx4 v[204:205], v[200:203], off offset:256 sc0 sc1
	s_cbranch_vccnz .LBB0_851
	v_mul_f32_e32 v115, v115, v115
	v_mul_f32_e32 v113, v113, v113
	v_mul_f32_e32 v118, v123, v123
	v_fmac_f32_e32 v115, v114, v114
	v_fmac_f32_e32 v113, v112, v112
	v_mul_f32_e32 v112, v121, v121
	v_mul_f32_e32 v114, v117, v117
	v_fmac_f32_e32 v118, v122, v122
	v_mul_f32_e32 v122, v194, v194
	v_mul_f32_e32 v123, v125, v125
	v_fmac_f32_e32 v112, v120, v120
	v_fmac_f32_e32 v114, v116, v116
	v_mul_f32_e32 v119, v127, v127
	v_fmac_f32_e32 v122, v193, v193
	v_fmac_f32_e32 v123, v124, v124
	v_add_f32_e32 v112, v112, v114
	v_and_b32_e32 v114, 64, v192
	v_fmac_f32_e32 v119, v126, v126
	v_add_f32_e32 v122, v122, v123
	v_add_f32_e32 v112, v113, v112
	v_xor_b32_e32 v113, 16, v192
	v_add_u32_e32 v114, 64, v114
	v_add_f32_e32 v119, v119, v122
	v_cmp_lt_i32_e32 vcc, v113, v114
	v_add_f32_e32 v118, v118, v119
	v_add_f32_e32 v112, v115, v112
	v_cndmask_b32_e32 v113, v192, v113, vcc
	v_add_f32_e32 v112, v118, v112
	v_lshlrev_b32_e32 v113, 2, v113
	ds_bpermute_b32 v113, v113, v112
	s_waitcnt lgkmcnt(0)
	v_add_f32_e32 v112, v112, v113
	v_xor_b32_e32 v113, 32, v192
	v_cmp_lt_i32_e32 vcc, v113, v114
	s_nop 1
	v_cndmask_b32_e32 v113, v192, v113, vcc
	v_lshlrev_b32_e32 v113, 2, v113
	ds_bpermute_b32 v113, v113, v112
	s_and_saveexec_b64 s[28:29], s[0:1]
	s_cbranch_execz .LBB0_850
	v_lshlrev_b64 v[114:115], 7, v[172:173]
	v_lshl_add_u64 v[114:115], s[24:25], 0, v[114:115]
	v_lshl_add_u64 v[114:115], s[26:27], 2, v[114:115]
	s_lshl_b32 s8, s40, 2
	v_lshl_add_u64 v[114:115], v[114:115], 0, s[8:9]
	s_waitcnt lgkmcnt(0)
	v_add_f32_e32 v112, v112, v113
	global_store_dword v[114:115], v112, off

; __device__ __forceinline__ float bflo(unsigned w) { return __uint_as_float(w << 16); }
; __device__ __forceinline__ float bfhi(unsigned w) { return __uint_as_float(w & 0xffff0000u); }
;     __device__ __forceinline__ void operator()(const f32x4 (&acc)[2][2][4][2], const Unit& u, int wr, int wc, int fr, int fq) const {
;     ...
;                 for (int m = 0; m < 4; ++m) { const size_t off = (size_t)(row0 + ai * HALF + m * 16) * DM + col0;
;                     float ss = 0.f;
; #pragma unroll
;                     for (int bj = 0; bj < 2; ++bj) { const u32x4 q = bs[m][bj]; const f32x4 a0 = acc[ai][bj][m][0], a1 = acc[ai][bj][m][1];
;                         const float h0 = bflo(q.x) + a0[0], h1 = bfhi(q.x) + a0[1], h2 = bflo(q.y) + a0[2], h3 = bfhi(q.y) + a0[3], h4 = bflo(q.z) + a1[0], h5 = bfhi(q.z) + a1[1], h6 = bflo(q.w) + a1[2], h7 = bfhi(q.w) + a1[3];
;                         ss += (h0 * h0 + h1 * h1) + (h2 * h2 + h3 * h3) + (h4 * h4 + h5 * h5) + (h6 * h6 + h7 * h7);
;                         u32x4 w; w.x = pk2(h0, h1); w.y = pk2(h2, h3); w.z = pk2(h4, h5); w.w = pk2(h6, h7);
;                         *(u32x4*)(out + off + bj * HALF) = w; }
;                     if (ssqp) { ss += __shfl_xor(ss, 16); ss += __shfl_xor(ss, 32); if (fq == 0) ssqp[(size_t)(row0 + ai * HALF + m * 16) * 32 + u.pn * 4 + wc] = ss; } }
.LBB0_851:
	v_lshlrev_b32_e32 v112, 16, v148
	v_add_f32_e32 v108, v108, v112
	v_and_b32_e32 v112, 0xffff0000, v148
	v_add_f32_e32 v112, v109, v112
	v_lshlrev_b32_e32 v109, 16, v149
	v_add_f32_e32 v109, v110, v109
	v_and_b32_e32 v110, 0xffff0000, v149
	v_add_f32_e32 v110, v111, v110
	v_lshlrev_b32_e32 v111, 16, v150
	v_add_f32_e32 v104, v104, v111
	v_and_b32_e32 v111, 0xffff0000, v150
	v_add_f32_e32 v105, v105, v111
	v_lshlrev_b32_e32 v111, 16, v151
	v_add_f32_e32 v111, v106, v111
	v_and_b32_e32 v106, 0xffff0000, v151
	v_add_f32_e32 v107, v107, v106
	v_lshlrev_b32_e32 v106, 16, v144
	v_add_f32_e32 v100, v100, v106
	v_and_b32_e32 v106, 0xffff0000, v144
	v_add_f32_e32 v106, v101, v106
	v_lshlrev_b32_e32 v101, 16, v145
	v_add_f32_e32 v101, v102, v101
	v_and_b32_e32 v102, 0xffff0000, v145
	v_add_f32_e32 v102, v103, v102
	v_lshlrev_b32_e32 v103, 16, v146
	v_add_f32_e32 v96, v96, v103
	v_and_b32_e32 v103, 0xffff0000, v146
	v_add_f32_e32 v97, v97, v103
	v_lshlrev_b32_e32 v103, 16, v147
	v_lshl_add_u64 v[118:119], s[22:23], 0, v[184:185]
	v_add_f32_e32 v98, v98, v103
	v_and_b32_e32 v103, 0xffff0000, v147
	v_cvt_pk_bf16_f32 v114, v108, v112
	v_cvt_pk_bf16_f32 v115, v109, v110
	v_cvt_pk_bf16_f32 v116, v104, v105
	v_cvt_pk_bf16_f32 v117, v111, v107
	v_lshl_add_u64 v[118:119], v[168:169], 1, v[118:119]
	v_add_f32_e32 v99, v99, v103
	global_store_dwordx4 v[118:119], v[114:117], off sc0 sc1
	s_and_b64 vcc, exec, s[6:7]
	s_nop 0
	v_cvt_pk_bf16_f32 v114, v100, v106
	v_cvt_pk_bf16_f32 v115, v101, v102
	v_cvt_pk_bf16_f32 v116, v96, v97
	v_cvt_pk_bf16_f32 v117, v98, v99
	global_store_dwordx4 v[118:119], v[114:117], off offset:256 sc0 sc1
	s_cbranch_vccnz .LBB0_855
	v_mul_f32_e32 v99, v99, v99
	v_mul_f32_e32 v97, v97, v97
	v_mul_f32_e32 v105, v105, v105
	v_fmac_f32_e32 v99, v98, v98
	v_fmac_f32_e32 v97, v96, v96
	v_mul_f32_e32 v96, v106, v106
	v_mul_f32_e32 v98, v102, v102
	v_mul_f32_e32 v103, v107, v107
	v_fmac_f32_e32 v105, v104, v104
	v_mul_f32_e32 v104, v112, v112
	v_mul_f32_e32 v107, v110, v110
	v_fmac_f32_e32 v96, v100, v100
	v_fmac_f32_e32 v98, v101, v101
	v_fmac_f32_e32 v104, v108, v108
	v_fmac_f32_e32 v107, v109, v109
	v_add_f32_e32 v96, v96, v98
	v_and_b32_e32 v98, 64, v192
	v_add_f32_e32 v104, v104, v107
	v_add_f32_e32 v96, v97, v96
	v_xor_b32_e32 v97, 16, v192
	v_add_u32_e32 v98, 64, v98
	v_fmac_f32_e32 v103, v111, v111
	v_add_f32_e32 v104, v105, v104
	v_cmp_lt_i32_e32 vcc, v97, v98
	v_add_f32_e32 v103, v103, v104
	v_add_f32_e32 v96, v99, v96
	v_cndmask_b32_e32 v97, v192, v97, vcc
	v_add_f32_e32 v96, v103, v96
	v_lshlrev_b32_e32 v97, 2, v97
	ds_bpermute_b32 v97, v97, v96
	s_waitcnt lgkmcnt(0)
	v_add_f32_e32 v96, v96, v97
	v_xor_b32_e32 v97, 32, v192
	v_cmp_lt_i32_e32 vcc, v97, v98
	s_nop 1
	v_cndmask_b32_e32 v97, v192, v97, vcc
	v_lshlrev_b32_e32 v97, 2, v97
	ds_bpermute_b32 v97, v97, v96
	s_and_saveexec_b64 s[28:29], s[0:1]
	s_cbranch_execz .LBB0_854
	v_lshlrev_b64 v[98:99], 7, v[182:183]
	v_lshl_add_u64 v[98:99], s[24:25], 0, v[98:99]
	v_lshl_add_u64 v[98:99], s[26:27], 2, v[98:99]
	s_lshl_b32 s8, s40, 2
	v_lshl_add_u64 v[98:99], v[98:99], 0, s[8:9]
	s_waitcnt lgkmcnt(0)
	v_add_f32_e32 v96, v96, v97
	global_store_dword v[98:99], v96, off

; __device__ __forceinline__ float bflo(unsigned w) { return __uint_as_float(w << 16); }
; __device__ __forceinline__ float bfhi(unsigned w) { return __uint_as_float(w & 0xffff0000u); }
;     __device__ __forceinline__ void operator()(const f32x4 (&acc)[2][2][4][2], const Unit& u, int wr, int wc, int fr, int fq) const {
;     ...
;                 for (int m = 0; m < 4; ++m) { const size_t off = (size_t)(row0 + ai * HALF + m * 16) * DM + col0;
;                     float ss = 0.f;
; #pragma unroll
;                     for (int bj = 0; bj < 2; ++bj) { const u32x4 q = bs[m][bj]; const f32x4 a0 = acc[ai][bj][m][0], a1 = acc[ai][bj][m][1];
;                         const float h0 = bflo(q.x) + a0[0], h1 = bfhi(q.x) + a0[1], h2 = bflo(q.y) + a0[2], h3 = bfhi(q.y) + a0[3], h4 = bflo(q.z) + a1[0], h5 = bfhi(q.z) + a1[1], h6 = bflo(q.w) + a1[2], h7 = bfhi(q.w) + a1[3];
;                         ss += (h0 * h0 + h1 * h1) + (h2 * h2 + h3 * h3) + (h4 * h4 + h5 * h5) + (h6 * h6 + h7 * h7);
;                         u32x4 w; w.x = pk2(h0, h1); w.y = pk2(h2, h3); w.z = pk2(h4, h5); w.w = pk2(h6, h7);
;                         *(u32x4*)(out + off + bj * HALF) = w; }
;                     if (ssqp) { ss += __shfl_xor(ss, 16); ss += __shfl_xor(ss, 32); if (fq == 0) ssqp[(size_t)(row0 + ai * HALF + m * 16) * 32 + u.pn * 4 + wc] = ss; } }
.LBB0_855:
	v_lshlrev_b32_e32 v96, 16, v140
	v_add_f32_e32 v92, v92, v96
	v_and_b32_e32 v96, 0xffff0000, v140
	v_add_f32_e32 v96, v93, v96
	v_lshlrev_b32_e32 v93, 16, v141
	v_add_f32_e32 v93, v94, v93
	v_and_b32_e32 v94, 0xffff0000, v141
	v_add_f32_e32 v94, v95, v94
	v_lshlrev_b32_e32 v95, 16, v142
	v_add_f32_e32 v88, v88, v95
	v_and_b32_e32 v95, 0xffff0000, v142
	v_add_f32_e32 v89, v89, v95
	v_lshlrev_b32_e32 v95, 16, v143
	v_add_f32_e32 v95, v90, v95
	v_and_b32_e32 v90, 0xffff0000, v143
	v_add_f32_e32 v91, v91, v90
	v_lshlrev_b32_e32 v90, 16, v136
	v_add_f32_e32 v84, v84, v90
	v_and_b32_e32 v90, 0xffff0000, v136
	v_add_f32_e32 v90, v85, v90
	v_lshlrev_b32_e32 v85, 16, v137
	v_add_f32_e32 v85, v86, v85
	v_and_b32_e32 v86, 0xffff0000, v137
	v_add_f32_e32 v86, v87, v86
	v_lshlrev_b32_e32 v87, 16, v138
	v_add_f32_e32 v80, v80, v87
	v_and_b32_e32 v87, 0xffff0000, v138
	v_add_f32_e32 v81, v81, v87
	v_lshlrev_b32_e32 v87, 16, v139
	v_lshl_add_u64 v[102:103], s[22:23], 0, v[180:181]
	v_add_f32_e32 v82, v82, v87
	v_and_b32_e32 v87, 0xffff0000, v139
	v_cvt_pk_bf16_f32 v98, v92, v96
	v_cvt_pk_bf16_f32 v99, v93, v94
	v_cvt_pk_bf16_f32 v100, v88, v89
	v_cvt_pk_bf16_f32 v101, v95, v91
	v_lshl_add_u64 v[102:103], v[168:169], 1, v[102:103]
	v_add_f32_e32 v83, v83, v87
	global_store_dwordx4 v[102:103], v[98:101], off sc0 sc1
	s_and_b64 vcc, exec, s[6:7]
	s_nop 0
	v_cvt_pk_bf16_f32 v98, v84, v90
	v_cvt_pk_bf16_f32 v99, v85, v86
	v_cvt_pk_bf16_f32 v100, v80, v81
	v_cvt_pk_bf16_f32 v101, v82, v83
	global_store_dwordx4 v[102:103], v[98:101], off offset:256 sc0 sc1
	s_cbranch_vccnz .LBB0_859
	v_mul_f32_e32 v83, v83, v83
	v_mul_f32_e32 v81, v81, v81
	v_mul_f32_e32 v89, v89, v89
	v_fmac_f32_e32 v83, v82, v82
	v_fmac_f32_e32 v81, v80, v80
	v_mul_f32_e32 v80, v90, v90
	v_mul_f32_e32 v82, v86, v86
	v_mul_f32_e32 v87, v91, v91
	v_fmac_f32_e32 v89, v88, v88
	v_mul_f32_e32 v88, v96, v96
	v_mul_f32_e32 v91, v94, v94
	v_fmac_f32_e32 v80, v84, v84
	v_fmac_f32_e32 v82, v85, v85
	v_fmac_f32_e32 v88, v92, v92
	v_fmac_f32_e32 v91, v93, v93
	v_add_f32_e32 v80, v80, v82
	v_and_b32_e32 v82, 64, v192
	v_add_f32_e32 v88, v88, v91
	v_add_f32_e32 v80, v81, v80
	v_xor_b32_e32 v81, 16, v192
	v_add_u32_e32 v82, 64, v82
	v_fmac_f32_e32 v87, v95, v95
	v_add_f32_e32 v88, v89, v88
	v_cmp_lt_i32_e32 vcc, v81, v82
	v_add_f32_e32 v87, v87, v88
	v_add_f32_e32 v80, v83, v80
	v_cndmask_b32_e32 v81, v192, v81, vcc
	v_add_f32_e32 v80, v87, v80
	v_lshlrev_b32_e32 v81, 2, v81
	ds_bpermute_b32 v81, v81, v80
	s_waitcnt lgkmcnt(0)
	v_add_f32_e32 v80, v80, v81
	v_xor_b32_e32 v81, 32, v192
	v_cmp_lt_i32_e32 vcc, v81, v82
	s_nop 1
	v_cndmask_b32_e32 v81, v192, v81, vcc
	v_lshlrev_b32_e32 v81, 2, v81
	ds_bpermute_b32 v81, v81, v80
	s_and_saveexec_b64 s[28:29], s[0:1]
	s_cbranch_execz .LBB0_858
	v_lshlrev_b64 v[82:83], 7, v[178:179]
	v_lshl_add_u64 v[82:83], s[24:25], 0, v[82:83]
	v_lshl_add_u64 v[82:83], s[26:27], 2, v[82:83]
	s_lshl_b32 s8, s40, 2
	v_lshl_add_u64 v[82:83], v[82:83], 0, s[8:9]
	s_waitcnt lgkmcnt(0)
	v_add_f32_e32 v80, v80, v81
	global_store_dword v[82:83], v80, off

; __device__ __forceinline__ float bflo(unsigned w) { return __uint_as_float(w << 16); }
; __device__ __forceinline__ float bfhi(unsigned w) { return __uint_as_float(w & 0xffff0000u); }
;     __device__ __forceinline__ void operator()(const f32x4 (&acc)[2][2][4][2], const Unit& u, int wr, int wc, int fr, int fq) const {
;     ...
;                 for (int m = 0; m < 4; ++m) { const size_t off = (size_t)(row0 + ai * HALF + m * 16) * DM + col0;
;                     float ss = 0.f;
; #pragma unroll
;                     for (int bj = 0; bj < 2; ++bj) { const u32x4 q = bs[m][bj]; const f32x4 a0 = acc[ai][bj][m][0], a1 = acc[ai][bj][m][1];
;                         const float h0 = bflo(q.x) + a0[0], h1 = bfhi(q.x) + a0[1], h2 = bflo(q.y) + a0[2], h3 = bfhi(q.y) + a0[3], h4 = bflo(q.z) + a1[0], h5 = bfhi(q.z) + a1[1], h6 = bflo(q.w) + a1[2], h7 = bfhi(q.w) + a1[3];
;                         ss += (h0 * h0 + h1 * h1) + (h2 * h2 + h3 * h3) + (h4 * h4 + h5 * h5) + (h6 * h6 + h7 * h7);
;                         u32x4 w; w.x = pk2(h0, h1); w.y = pk2(h2, h3); w.z = pk2(h4, h5); w.w = pk2(h6, h7);
;                         *(u32x4*)(out + off + bj * HALF) = w; }
;                     if (ssqp) { ss += __shfl_xor(ss, 16); ss += __shfl_xor(ss, 32); if (fq == 0) ssqp[(size_t)(row0 + ai * HALF + m * 16) * 32 + u.pn * 4 + wc] = ss; } }
.LBB0_859:
	v_lshlrev_b32_e32 v80, 16, v132
	v_add_f32_e32 v76, v76, v80
	v_and_b32_e32 v80, 0xffff0000, v132
	v_add_f32_e32 v80, v77, v80
	v_lshlrev_b32_e32 v77, 16, v133
	v_add_f32_e32 v77, v78, v77
	v_and_b32_e32 v78, 0xffff0000, v133
	v_add_f32_e32 v78, v79, v78
	v_lshlrev_b32_e32 v79, 16, v134
	v_add_f32_e32 v72, v72, v79
	v_and_b32_e32 v79, 0xffff0000, v134
	v_add_f32_e32 v73, v73, v79
	v_lshlrev_b32_e32 v79, 16, v135
	v_add_f32_e32 v79, v74, v79
	v_and_b32_e32 v74, 0xffff0000, v135
	v_add_f32_e32 v75, v75, v74
	v_lshlrev_b32_e32 v74, 16, v128
	v_add_f32_e32 v68, v68, v74
	v_and_b32_e32 v74, 0xffff0000, v128
	v_add_f32_e32 v74, v69, v74
	v_lshlrev_b32_e32 v69, 16, v129
	v_add_f32_e32 v69, v70, v69
	v_and_b32_e32 v70, 0xffff0000, v129
	v_add_f32_e32 v70, v71, v70
	v_lshlrev_b32_e32 v71, 16, v130
	v_add_f32_e32 v64, v64, v71
	v_and_b32_e32 v71, 0xffff0000, v130
	v_add_f32_e32 v65, v65, v71
	v_lshlrev_b32_e32 v71, 16, v131
	v_lshl_add_u64 v[86:87], s[22:23], 0, v[176:177]
	v_add_f32_e32 v66, v66, v71
	v_and_b32_e32 v71, 0xffff0000, v131
	v_cvt_pk_bf16_f32 v82, v76, v80
	v_cvt_pk_bf16_f32 v83, v77, v78
	v_cvt_pk_bf16_f32 v84, v72, v73
	v_cvt_pk_bf16_f32 v85, v79, v75
	v_lshl_add_u64 v[86:87], v[168:169], 1, v[86:87]
	v_add_f32_e32 v67, v67, v71
	global_store_dwordx4 v[86:87], v[82:85], off sc0 sc1
	s_and_b64 vcc, exec, s[6:7]
	s_nop 0
	v_cvt_pk_bf16_f32 v82, v68, v74
	v_cvt_pk_bf16_f32 v83, v69, v70
	v_cvt_pk_bf16_f32 v84, v64, v65
	v_cvt_pk_bf16_f32 v85, v66, v67
	global_store_dwordx4 v[86:87], v[82:85], off offset:256 sc0 sc1
	s_cbranch_vccnz .LBB0_863
	v_mul_f32_e32 v67, v67, v67
	v_mul_f32_e32 v65, v65, v65
	v_mul_f32_e32 v73, v73, v73
	v_fmac_f32_e32 v67, v66, v66
	v_fmac_f32_e32 v65, v64, v64
	v_mul_f32_e32 v64, v74, v74
	v_mul_f32_e32 v66, v70, v70
	v_mul_f32_e32 v71, v75, v75
	v_fmac_f32_e32 v73, v72, v72
	v_mul_f32_e32 v72, v80, v80
	v_mul_f32_e32 v75, v78, v78
	v_fmac_f32_e32 v64, v68, v68
	v_fmac_f32_e32 v66, v69, v69
	v_fmac_f32_e32 v72, v76, v76
	v_fmac_f32_e32 v75, v77, v77
	v_add_f32_e32 v64, v64, v66
	v_and_b32_e32 v66, 64, v192
	v_add_f32_e32 v72, v72, v75
	v_add_f32_e32 v64, v65, v64
	v_xor_b32_e32 v65, 16, v192
	v_add_u32_e32 v66, 64, v66
	v_fmac_f32_e32 v71, v79, v79
	v_add_f32_e32 v72, v73, v72
	v_cmp_lt_i32_e32 vcc, v65, v66
	v_add_f32_e32 v71, v71, v72
	v_add_f32_e32 v64, v67, v64
	v_cndmask_b32_e32 v65, v192, v65, vcc
	v_add_f32_e32 v64, v71, v64
	v_lshlrev_b32_e32 v65, 2, v65
	ds_bpermute_b32 v65, v65, v64
	s_waitcnt lgkmcnt(0)
	v_add_f32_e32 v64, v64, v65
	v_xor_b32_e32 v65, 32, v192
	v_cmp_lt_i32_e32 vcc, v65, v66
	s_nop 1
	v_cndmask_b32_e32 v65, v192, v65, vcc
	v_lshlrev_b32_e32 v65, 2, v65
	ds_bpermute_b32 v65, v65, v64
	s_and_saveexec_b64 s[28:29], s[0:1]
	s_cbranch_execz .LBB0_862
	v_lshlrev_b64 v[66:67], 7, v[174:175]
	v_lshl_add_u64 v[66:67], s[24:25], 0, v[66:67]
	v_lshl_add_u64 v[66:67], s[26:27], 2, v[66:67]
	s_lshl_b32 s8, s40, 2
	v_lshl_add_u64 v[66:67], v[66:67], 0, s[8:9]
	s_waitcnt lgkmcnt(0)
	v_add_f32_e32 v64, v64, v65
	global_store_dword v[66:67], v64, off

; __device__ __forceinline__ float bflo(unsigned w) { return __uint_as_float(w << 16); }
; __device__ __forceinline__ float bfhi(unsigned w) { return __uint_as_float(w & 0xffff0000u); }
;     __device__ __forceinline__ void operator()(const f32x4 (&acc)[2][2][4][2], const Unit& u, int wr, int wc, int fr, int fq) const {
;     ...
;                 for (int m = 0; m < 4; ++m) { const size_t off = (size_t)(row0 + ai * HALF + m * 16) * DM + col0;
; #pragma unroll
;                     for (int bj = 0; bj < 2; ++bj) bs[m][bj] = *(const u32x4*)(baseb + off + bj * HALF); }
; #pragma unroll
;                 for (int m = 0; m < 4; ++m) { const size_t off = (size_t)(row0 + ai * HALF + m * 16) * DM + col0;
;                     float ss = 0.f;
; #pragma unroll
;                     for (int bj = 0; bj < 2; ++bj) { const u32x4 q = bs[m][bj]; const f32x4 a0 = acc[ai][bj][m][0], a1 = acc[ai][bj][m][1];
;                         const float h0 = bflo(q.x) + a0[0], h1 = bfhi(q.x) + a0[1], h2 = bflo(q.y) + a0[2], h3 = bfhi(q.y) + a0[3], h4 = bflo(q.z) + a1[0], h5 = bfhi(q.z) + a1[1], h6 = bflo(q.w) + a1[2], h7 = bfhi(q.w) + a1[3];
;                         ss += (h0 * h0 + h1 * h1) + (h2 * h2 + h3 * h3) + (h4 * h4 + h5 * h5) + (h6 * h6 + h7 * h7);
;                         u32x4 w; w.x = pk2(h0, h1); w.y = pk2(h2, h3); w.z = pk2(h4, h5); w.w = pk2(h6, h7);
;                         *(u32x4*)(out + off + bj * HALF) = w; }
;                     if (ssqp) { ss += __shfl_xor(ss, 16); ss += __shfl_xor(ss, 32); if (fq == 0) ssqp[(size_t)(row0 + ai * HALF + m * 16) * 32 + u.pn * 4 + wc] = ss; } }
.LBB0_863:
	v_add_u32_e32 v100, 0x80, v172
	v_ashrrev_i32_e32 v101, 31, v100
	v_add_u32_e32 v96, 0x90, v172
	v_add_u32_e32 v92, 0xa0, v172
	v_lshlrev_b64 v[110:111], 12, v[100:101]
	v_add_u32_e32 v88, 0xb0, v172
	s_waitcnt lgkmcnt(0)
	v_ashrrev_i32_e32 v97, 31, v96
	v_ashrrev_i32_e32 v93, 31, v92
	v_lshl_add_u64 v[64:65], v[170:171], 0, v[110:111]
	v_ashrrev_i32_e32 v89, 31, v88
	v_lshlrev_b64 v[98:99], 12, v[96:97]
	v_lshlrev_b64 v[94:95], 12, v[92:93]
	global_load_dwordx4 v[102:105], v[64:65], off
	global_load_dwordx4 v[106:109], v[64:65], off offset:256
	v_lshlrev_b64 v[90:91], 12, v[88:89]
	v_lshl_add_u64 v[64:65], v[170:171], 0, v[98:99]
	v_lshl_add_u64 v[66:67], v[170:171], 0, v[94:95]
	v_lshl_add_u64 v[112:113], v[170:171], 0, v[90:91]
	global_load_dwordx4 v[84:87], v[64:65], off
	global_load_dwordx4 v[80:83], v[64:65], off offset:256
	global_load_dwordx4 v[76:79], v[66:67], off
	global_load_dwordx4 v[72:75], v[66:67], off offset:256
	global_load_dwordx4 v[68:71], v[112:113], off
	s_nop 0
	global_load_dwordx4 v[64:67], v[112:113], off offset:256
	v_lshl_add_u64 v[110:111], s[22:23], 0, v[110:111]
	v_lshl_add_u64 v[112:113], v[168:169], 1, v[110:111]
	s_and_b64 vcc, exec, s[6:7]
	s_waitcnt vmcnt(7)
	v_lshlrev_b32_e32 v110, 16, v102
	v_and_b32_e32 v111, 0xffff0000, v102
	v_lshlrev_b32_e32 v114, 16, v103
	v_and_b32_e32 v115, 0xffff0000, v103
	v_lshlrev_b32_e32 v116, 16, v104
	v_and_b32_e32 v104, 0xffff0000, v104
	v_lshlrev_b32_e32 v117, 16, v105
	v_and_b32_e32 v105, 0xffff0000, v105
	s_waitcnt vmcnt(6)
	v_lshlrev_b32_e32 v118, 16, v106
	v_and_b32_e32 v106, 0xffff0000, v106
	v_lshlrev_b32_e32 v119, 16, v107
	v_and_b32_e32 v107, 0xffff0000, v107
	v_lshlrev_b32_e32 v120, 16, v108
	v_and_b32_e32 v108, 0xffff0000, v108
	v_lshlrev_b32_e32 v121, 16, v109
	v_and_b32_e32 v109, 0xffff0000, v109
	v_add_f32_e32 v102, v60, v110
	v_add_f32_e32 v103, v61, v111
	v_add_f32_e32 v60, v62, v114
	v_add_f32_e32 v61, v63, v115
	v_add_f32_e32 v62, v56, v116
	v_add_f32_e32 v63, v57, v104
	v_add_f32_e32 v58, v58, v117
	v_add_f32_e32 v59, v59, v105
	v_add_f32_e32 v56, v52, v118
	v_add_f32_e32 v57, v53, v106
	v_add_f32_e32 v52, v54, v119
	v_add_f32_e32 v53, v55, v107
	v_add_f32_e32 v48, v48, v120
	v_add_f32_e32 v49, v49, v108
	v_add_f32_e32 v50, v50, v121
	v_add_f32_e32 v51, v51, v109
	v_cvt_pk_bf16_f32 v104, v102, v103
	v_cvt_pk_bf16_f32 v105, v60, v61
	v_cvt_pk_bf16_f32 v106, v62, v63
	v_cvt_pk_bf16_f32 v107, v58, v59
	v_cvt_pk_bf16_f32 v108, v56, v57
	v_cvt_pk_bf16_f32 v109, v52, v53
	v_cvt_pk_bf16_f32 v110, v48, v49
	v_cvt_pk_bf16_f32 v111, v50, v51
	global_store_dwordx4 v[112:113], v[104:107], off sc0 sc1
	global_store_dwordx4 v[112:113], v[108:111], off offset:256 sc0 sc1
	s_cbranch_vccnz .LBB0_867
	v_mul_f32_e32 v51, v51, v51
	v_mul_f32_e32 v49, v49, v49
	v_mul_f32_e32 v54, v59, v59
	v_fmac_f32_e32 v51, v50, v50
	v_fmac_f32_e32 v49, v48, v48
	v_mul_f32_e32 v48, v57, v57
	v_mul_f32_e32 v50, v53, v53
	v_fmac_f32_e32 v54, v58, v58
	v_mul_f32_e32 v58, v103, v103
	v_mul_f32_e32 v59, v61, v61
	v_fmac_f32_e32 v48, v56, v56
	v_fmac_f32_e32 v50, v52, v52
	v_mul_f32_e32 v55, v63, v63
	v_fmac_f32_e32 v58, v102, v102
	v_fmac_f32_e32 v59, v60, v60
	v_add_f32_e32 v48, v48, v50
	v_and_b32_e32 v50, 64, v192
	v_fmac_f32_e32 v55, v62, v62
	v_add_f32_e32 v58, v58, v59
	v_add_f32_e32 v48, v49, v48
	v_xor_b32_e32 v49, 16, v192
	v_add_u32_e32 v50, 64, v50
	v_add_f32_e32 v55, v55, v58
	v_cmp_lt_i32_e32 vcc, v49, v50
	v_add_f32_e32 v54, v54, v55
	v_add_f32_e32 v48, v51, v48
	v_cndmask_b32_e32 v49, v192, v49, vcc
	v_add_f32_e32 v48, v54, v48
	v_lshlrev_b32_e32 v49, 2, v49
	ds_bpermute_b32 v49, v49, v48
	s_waitcnt lgkmcnt(0)
	v_add_f32_e32 v48, v48, v49
	v_xor_b32_e32 v49, 32, v192
	v_cmp_lt_i32_e32 vcc, v49, v50
	s_nop 1
	v_cndmask_b32_e32 v49, v192, v49, vcc
	v_lshlrev_b32_e32 v49, 2, v49
	ds_bpermute_b32 v49, v49, v48
	s_and_saveexec_b64 s[28:29], s[0:1]
	s_cbranch_execz .LBB0_866
	v_lshlrev_b64 v[50:51], 7, v[100:101]
	v_lshl_add_u64 v[50:51], s[24:25], 0, v[50:51]
	v_lshl_add_u64 v[50:51], s[26:27], 2, v[50:51]
	s_lshl_b32 s8, s40, 2
	v_lshl_add_u64 v[50:51], v[50:51], 0, s[8:9]
	s_waitcnt lgkmcnt(0)
	v_add_f32_e32 v48, v48, v49
	global_store_dword v[50:51], v48, off

; __device__ __forceinline__ float bflo(unsigned w) { return __uint_as_float(w << 16); }
; __device__ __forceinline__ float bfhi(unsigned w) { return __uint_as_float(w & 0xffff0000u); }
;     __device__ __forceinline__ void operator()(const f32x4 (&acc)[2][2][4][2], const Unit& u, int wr, int wc, int fr, int fq) const {
;     ...
;                 for (int m = 0; m < 4; ++m) { const size_t off = (size_t)(row0 + ai * HALF + m * 16) * DM + col0;
;                     float ss = 0.f;
; #pragma unroll
;                     for (int bj = 0; bj < 2; ++bj) { const u32x4 q = bs[m][bj]; const f32x4 a0 = acc[ai][bj][m][0], a1 = acc[ai][bj][m][1];
;                         const float h0 = bflo(q.x) + a0[0], h1 = bfhi(q.x) + a0[1], h2 = bflo(q.y) + a0[2], h3 = bfhi(q.y) + a0[3], h4 = bflo(q.z) + a1[0], h5 = bfhi(q.z) + a1[1], h6 = bflo(q.w) + a1[2], h7 = bfhi(q.w) + a1[3];
;                         ss += (h0 * h0 + h1 * h1) + (h2 * h2 + h3 * h3) + (h4 * h4 + h5 * h5) + (h6 * h6 + h7 * h7);
;                         u32x4 w; w.x = pk2(h0, h1); w.y = pk2(h2, h3); w.z = pk2(h4, h5); w.w = pk2(h6, h7);
;                         *(u32x4*)(out + off + bj * HALF) = w; }
;                     if (ssqp) { ss += __shfl_xor(ss, 16); ss += __shfl_xor(ss, 32); if (fq == 0) ssqp[(size_t)(row0 + ai * HALF + m * 16) * 32 + u.pn * 4 + wc] = ss; } }
.LBB0_867:
	s_waitcnt vmcnt(7)
	v_lshlrev_b32_e32 v48, 16, v84
	v_add_f32_e32 v44, v44, v48
	v_and_b32_e32 v48, 0xffff0000, v84
	v_add_f32_e32 v48, v45, v48
	v_lshlrev_b32_e32 v45, 16, v85
	v_add_f32_e32 v45, v46, v45
	v_and_b32_e32 v46, 0xffff0000, v85
	v_add_f32_e32 v46, v47, v46
	v_lshlrev_b32_e32 v47, 16, v86
	v_add_f32_e32 v40, v40, v47
	v_and_b32_e32 v47, 0xffff0000, v86
	v_add_f32_e32 v41, v41, v47
	v_lshlrev_b32_e32 v47, 16, v87
	v_add_f32_e32 v47, v42, v47
	v_and_b32_e32 v42, 0xffff0000, v87
	v_add_f32_e32 v43, v43, v42
	s_waitcnt vmcnt(6)
	v_lshlrev_b32_e32 v42, 16, v80
	v_add_f32_e32 v36, v36, v42
	v_and_b32_e32 v42, 0xffff0000, v80
	v_add_f32_e32 v42, v37, v42
	v_lshlrev_b32_e32 v37, 16, v81
	v_add_f32_e32 v37, v38, v37
	v_and_b32_e32 v38, 0xffff0000, v81
	v_add_f32_e32 v38, v39, v38
	v_lshlrev_b32_e32 v39, 16, v82
	v_add_f32_e32 v32, v32, v39
	v_and_b32_e32 v39, 0xffff0000, v82
	v_add_f32_e32 v33, v33, v39
	v_lshlrev_b32_e32 v39, 16, v83
	v_lshl_add_u64 v[54:55], s[22:23], 0, v[98:99]
	v_add_f32_e32 v34, v34, v39
	v_and_b32_e32 v39, 0xffff0000, v83
	v_cvt_pk_bf16_f32 v50, v44, v48
	v_cvt_pk_bf16_f32 v51, v45, v46
	v_cvt_pk_bf16_f32 v52, v40, v41
	v_cvt_pk_bf16_f32 v53, v47, v43
	v_lshl_add_u64 v[54:55], v[168:169], 1, v[54:55]
	v_add_f32_e32 v35, v35, v39
	global_store_dwordx4 v[54:55], v[50:53], off sc0 sc1
	s_and_b64 vcc, exec, s[6:7]
	s_nop 0
	v_cvt_pk_bf16_f32 v50, v36, v42
	v_cvt_pk_bf16_f32 v51, v37, v38
	v_cvt_pk_bf16_f32 v52, v32, v33
	v_cvt_pk_bf16_f32 v53, v34, v35
	global_store_dwordx4 v[54:55], v[50:53], off offset:256 sc0 sc1
	s_cbranch_vccnz .LBB0_871
	v_mul_f32_e32 v35, v35, v35
	v_mul_f32_e32 v33, v33, v33
	v_mul_f32_e32 v41, v41, v41
	v_fmac_f32_e32 v35, v34, v34
	v_fmac_f32_e32 v33, v32, v32
	v_mul_f32_e32 v32, v42, v42
	v_mul_f32_e32 v34, v38, v38
	v_mul_f32_e32 v39, v43, v43
	v_fmac_f32_e32 v41, v40, v40
	v_mul_f32_e32 v40, v48, v48
	v_mul_f32_e32 v43, v46, v46
	v_fmac_f32_e32 v32, v36, v36
	v_fmac_f32_e32 v34, v37, v37
	v_fmac_f32_e32 v40, v44, v44
	v_fmac_f32_e32 v43, v45, v45
	v_add_f32_e32 v32, v32, v34
	v_and_b32_e32 v34, 64, v192
	v_add_f32_e32 v40, v40, v43
	v_add_f32_e32 v32, v33, v32
	v_xor_b32_e32 v33, 16, v192
	v_add_u32_e32 v34, 64, v34
	v_fmac_f32_e32 v39, v47, v47
	v_add_f32_e32 v40, v41, v40
	v_cmp_lt_i32_e32 vcc, v33, v34
	v_add_f32_e32 v39, v39, v40
	v_add_f32_e32 v32, v35, v32
	v_cndmask_b32_e32 v33, v192, v33, vcc
	v_add_f32_e32 v32, v39, v32
	v_lshlrev_b32_e32 v33, 2, v33
	ds_bpermute_b32 v33, v33, v32
	s_waitcnt lgkmcnt(0)
	v_add_f32_e32 v32, v32, v33
	v_xor_b32_e32 v33, 32, v192
	v_cmp_lt_i32_e32 vcc, v33, v34
	s_nop 1
	v_cndmask_b32_e32 v33, v192, v33, vcc
	v_lshlrev_b32_e32 v33, 2, v33
	ds_bpermute_b32 v33, v33, v32
	s_and_saveexec_b64 s[28:29], s[0:1]
	s_cbranch_execz .LBB0_870
	v_lshlrev_b64 v[34:35], 7, v[96:97]
	v_lshl_add_u64 v[34:35], s[24:25], 0, v[34:35]
	v_lshl_add_u64 v[34:35], s[26:27], 2, v[34:35]
	s_lshl_b32 s8, s40, 2
	v_lshl_add_u64 v[34:35], v[34:35], 0, s[8:9]
	s_waitcnt lgkmcnt(0)
	v_add_f32_e32 v32, v32, v33
	global_store_dword v[34:35], v32, off

; __device__ __forceinline__ float bflo(unsigned w) { return __uint_as_float(w << 16); }
; __device__ __forceinline__ float bfhi(unsigned w) { return __uint_as_float(w & 0xffff0000u); }
;     __device__ __forceinline__ void operator()(const f32x4 (&acc)[2][2][4][2], const Unit& u, int wr, int wc, int fr, int fq) const {
;     ...
;                 for (int m = 0; m < 4; ++m) { const size_t off = (size_t)(row0 + ai * HALF + m * 16) * DM + col0;
;                     float ss = 0.f;
; #pragma unroll
;                     for (int bj = 0; bj < 2; ++bj) { const u32x4 q = bs[m][bj]; const f32x4 a0 = acc[ai][bj][m][0], a1 = acc[ai][bj][m][1];
;                         const float h0 = bflo(q.x) + a0[0], h1 = bfhi(q.x) + a0[1], h2 = bflo(q.y) + a0[2], h3 = bfhi(q.y) + a0[3], h4 = bflo(q.z) + a1[0], h5 = bfhi(q.z) + a1[1], h6 = bflo(q.w) + a1[2], h7 = bfhi(q.w) + a1[3];
;                         ss += (h0 * h0 + h1 * h1) + (h2 * h2 + h3 * h3) + (h4 * h4 + h5 * h5) + (h6 * h6 + h7 * h7);
;                         u32x4 w; w.x = pk2(h0, h1); w.y = pk2(h2, h3); w.z = pk2(h4, h5); w.w = pk2(h6, h7);
;                         *(u32x4*)(out + off + bj * HALF) = w; }
;                     if (ssqp) { ss += __shfl_xor(ss, 16); ss += __shfl_xor(ss, 32); if (fq == 0) ssqp[(size_t)(row0 + ai * HALF + m * 16) * 32 + u.pn * 4 + wc] = ss; } }
.LBB0_871:
	s_waitcnt vmcnt(7)
	v_lshlrev_b32_e32 v32, 16, v76
	v_add_f32_e32 v28, v28, v32
	v_and_b32_e32 v32, 0xffff0000, v76
	v_add_f32_e32 v32, v29, v32
	v_lshlrev_b32_e32 v29, 16, v77
	v_add_f32_e32 v29, v30, v29
	v_and_b32_e32 v30, 0xffff0000, v77
	v_add_f32_e32 v30, v31, v30
	v_lshlrev_b32_e32 v31, 16, v78
	v_add_f32_e32 v24, v24, v31
	v_and_b32_e32 v31, 0xffff0000, v78
	v_add_f32_e32 v25, v25, v31
	v_lshlrev_b32_e32 v31, 16, v79
	v_add_f32_e32 v31, v26, v31
	v_and_b32_e32 v26, 0xffff0000, v79
	v_add_f32_e32 v27, v27, v26
	s_waitcnt vmcnt(6)
	v_lshlrev_b32_e32 v26, 16, v72
	v_add_f32_e32 v20, v20, v26
	v_and_b32_e32 v26, 0xffff0000, v72
	v_add_f32_e32 v26, v21, v26
	v_lshlrev_b32_e32 v21, 16, v73
	v_add_f32_e32 v21, v22, v21
	v_and_b32_e32 v22, 0xffff0000, v73
	v_add_f32_e32 v22, v23, v22
	v_lshlrev_b32_e32 v23, 16, v74
	v_add_f32_e32 v16, v16, v23
	v_and_b32_e32 v23, 0xffff0000, v74
	v_add_f32_e32 v17, v17, v23
	v_lshlrev_b32_e32 v23, 16, v75
	v_lshl_add_u64 v[38:39], s[22:23], 0, v[94:95]
	v_add_f32_e32 v18, v18, v23
	v_and_b32_e32 v23, 0xffff0000, v75
	v_cvt_pk_bf16_f32 v34, v28, v32
	v_cvt_pk_bf16_f32 v35, v29, v30
	v_cvt_pk_bf16_f32 v36, v24, v25
	v_cvt_pk_bf16_f32 v37, v31, v27
	v_lshl_add_u64 v[38:39], v[168:169], 1, v[38:39]
	v_add_f32_e32 v19, v19, v23
	global_store_dwordx4 v[38:39], v[34:37], off sc0 sc1
	s_and_b64 vcc, exec, s[6:7]
	s_nop 0
	v_cvt_pk_bf16_f32 v34, v20, v26
	v_cvt_pk_bf16_f32 v35, v21, v22
	v_cvt_pk_bf16_f32 v36, v16, v17
	v_cvt_pk_bf16_f32 v37, v18, v19
	global_store_dwordx4 v[38:39], v[34:37], off offset:256 sc0 sc1
	s_cbranch_vccnz .LBB0_875
	v_mul_f32_e32 v19, v19, v19
	v_mul_f32_e32 v17, v17, v17
	v_mul_f32_e32 v25, v25, v25
	v_fmac_f32_e32 v19, v18, v18
	v_fmac_f32_e32 v17, v16, v16
	v_mul_f32_e32 v16, v26, v26
	v_mul_f32_e32 v18, v22, v22
	v_mul_f32_e32 v23, v27, v27
	v_fmac_f32_e32 v25, v24, v24
	v_mul_f32_e32 v24, v32, v32
	v_mul_f32_e32 v27, v30, v30
	v_fmac_f32_e32 v16, v20, v20
	v_fmac_f32_e32 v18, v21, v21
	v_fmac_f32_e32 v24, v28, v28
	v_fmac_f32_e32 v27, v29, v29
	v_add_f32_e32 v16, v16, v18
	v_and_b32_e32 v18, 64, v192
	v_add_f32_e32 v24, v24, v27
	v_add_f32_e32 v16, v17, v16
	v_xor_b32_e32 v17, 16, v192
	v_add_u32_e32 v18, 64, v18
	v_fmac_f32_e32 v23, v31, v31
	v_add_f32_e32 v24, v25, v24
	v_cmp_lt_i32_e32 vcc, v17, v18
	v_add_f32_e32 v23, v23, v24
	v_add_f32_e32 v16, v19, v16
	v_cndmask_b32_e32 v17, v192, v17, vcc
	v_add_f32_e32 v16, v23, v16
	v_lshlrev_b32_e32 v17, 2, v17
	ds_bpermute_b32 v17, v17, v16
	s_waitcnt lgkmcnt(0)
	v_add_f32_e32 v16, v16, v17
	v_xor_b32_e32 v17, 32, v192
	v_cmp_lt_i32_e32 vcc, v17, v18
	s_nop 1
	v_cndmask_b32_e32 v17, v192, v17, vcc
	v_lshlrev_b32_e32 v17, 2, v17
	ds_bpermute_b32 v17, v17, v16
	s_and_saveexec_b64 s[28:29], s[0:1]
	s_cbranch_execz .LBB0_874
	v_lshlrev_b64 v[18:19], 7, v[92:93]
	v_lshl_add_u64 v[18:19], s[24:25], 0, v[18:19]
	v_lshl_add_u64 v[18:19], s[26:27], 2, v[18:19]
	s_lshl_b32 s8, s40, 2
	v_lshl_add_u64 v[18:19], v[18:19], 0, s[8:9]
	s_waitcnt lgkmcnt(0)
	v_add_f32_e32 v16, v16, v17
	global_store_dword v[18:19], v16, off

; __device__ __forceinline__ float bflo(unsigned w) { return __uint_as_float(w << 16); }
; __device__ __forceinline__ float bfhi(unsigned w) { return __uint_as_float(w & 0xffff0000u); }
;     __device__ __forceinline__ void operator()(const f32x4 (&acc)[2][2][4][2], const Unit& u, int wr, int wc, int fr, int fq) const {
;     ...
;                 for (int m = 0; m < 4; ++m) { const size_t off = (size_t)(row0 + ai * HALF + m * 16) * DM + col0;
;                     float ss = 0.f;
; #pragma unroll
;                     for (int bj = 0; bj < 2; ++bj) { const u32x4 q = bs[m][bj]; const f32x4 a0 = acc[ai][bj][m][0], a1 = acc[ai][bj][m][1];
;                         const float h0 = bflo(q.x) + a0[0], h1 = bfhi(q.x) + a0[1], h2 = bflo(q.y) + a0[2], h3 = bfhi(q.y) + a0[3], h4 = bflo(q.z) + a1[0], h5 = bfhi(q.z) + a1[1], h6 = bflo(q.w) + a1[2], h7 = bfhi(q.w) + a1[3];
;                         ss += (h0 * h0 + h1 * h1) + (h2 * h2 + h3 * h3) + (h4 * h4 + h5 * h5) + (h6 * h6 + h7 * h7);
;                         u32x4 w; w.x = pk2(h0, h1); w.y = pk2(h2, h3); w.z = pk2(h4, h5); w.w = pk2(h6, h7);
;                         *(u32x4*)(out + off + bj * HALF) = w; }
;                     if (ssqp) { ss += __shfl_xor(ss, 16); ss += __shfl_xor(ss, 32); if (fq == 0) ssqp[(size_t)(row0 + ai * HALF + m * 16) * 32 + u.pn * 4 + wc] = ss; } }
.LBB0_875:
	s_waitcnt vmcnt(7)
	v_lshlrev_b32_e32 v16, 16, v68
	v_add_f32_e32 v12, v12, v16
	v_and_b32_e32 v16, 0xffff0000, v68
	v_add_f32_e32 v16, v13, v16
	v_lshlrev_b32_e32 v13, 16, v69
	v_add_f32_e32 v13, v14, v13
	v_and_b32_e32 v14, 0xffff0000, v69
	v_add_f32_e32 v14, v15, v14
	v_lshlrev_b32_e32 v15, 16, v70
	v_add_f32_e32 v8, v8, v15
	v_and_b32_e32 v15, 0xffff0000, v70
	v_add_f32_e32 v9, v9, v15
	v_lshlrev_b32_e32 v15, 16, v71
	v_add_f32_e32 v15, v10, v15
	v_and_b32_e32 v10, 0xffff0000, v71
	v_add_f32_e32 v11, v11, v10
	s_waitcnt vmcnt(6)
	v_lshlrev_b32_e32 v10, 16, v64
	v_add_f32_e32 v4, v4, v10
	v_and_b32_e32 v10, 0xffff0000, v64
	v_add_f32_e32 v10, v5, v10
	v_lshlrev_b32_e32 v5, 16, v65
	v_add_f32_e32 v5, v6, v5
	v_and_b32_e32 v6, 0xffff0000, v65
	v_add_f32_e32 v6, v7, v6
	v_lshlrev_b32_e32 v7, 16, v66
	v_add_f32_e32 v0, v0, v7
	v_and_b32_e32 v7, 0xffff0000, v66
	v_add_f32_e32 v1, v1, v7
	v_lshlrev_b32_e32 v7, 16, v67
	v_lshl_add_u64 v[22:23], s[22:23], 0, v[90:91]
	v_add_f32_e32 v2, v2, v7
	v_and_b32_e32 v7, 0xffff0000, v67
	v_cvt_pk_bf16_f32 v18, v12, v16
	v_cvt_pk_bf16_f32 v19, v13, v14
	v_cvt_pk_bf16_f32 v20, v8, v9
	v_cvt_pk_bf16_f32 v21, v15, v11
	v_lshl_add_u64 v[22:23], v[168:169], 1, v[22:23]
	v_add_f32_e32 v3, v3, v7
	global_store_dwordx4 v[22:23], v[18:21], off sc0 sc1
	s_and_b64 vcc, exec, s[6:7]
	s_nop 0
	v_cvt_pk_bf16_f32 v18, v4, v10
	v_cvt_pk_bf16_f32 v19, v5, v6
	v_cvt_pk_bf16_f32 v20, v0, v1
	v_cvt_pk_bf16_f32 v21, v2, v3
	global_store_dwordx4 v[22:23], v[18:21], off offset:256 sc0 sc1
	s_cbranch_vccnz .LBB0_838
	v_mul_f32_e32 v3, v3, v3
	v_mul_f32_e32 v1, v1, v1
	v_mul_f32_e32 v9, v9, v9
	v_fmac_f32_e32 v3, v2, v2
	v_fmac_f32_e32 v1, v0, v0
	v_mul_f32_e32 v0, v10, v10
	v_mul_f32_e32 v2, v6, v6
	v_mul_f32_e32 v7, v11, v11
	v_fmac_f32_e32 v9, v8, v8
	v_mul_f32_e32 v8, v16, v16
	v_mul_f32_e32 v11, v14, v14
	v_fmac_f32_e32 v0, v4, v4
	v_fmac_f32_e32 v2, v5, v5
	v_fmac_f32_e32 v8, v12, v12
	v_fmac_f32_e32 v11, v13, v13
	v_add_f32_e32 v0, v0, v2
	v_and_b32_e32 v2, 64, v192
	v_add_f32_e32 v8, v8, v11
	v_add_f32_e32 v0, v1, v0
	v_xor_b32_e32 v1, 16, v192
	v_add_u32_e32 v2, 64, v2
	v_fmac_f32_e32 v7, v15, v15
	v_add_f32_e32 v8, v9, v8
	v_cmp_lt_i32_e32 vcc, v1, v2
	v_add_f32_e32 v7, v7, v8
	v_add_f32_e32 v0, v3, v0
	v_cndmask_b32_e32 v1, v192, v1, vcc
	v_add_f32_e32 v0, v7, v0
	v_lshlrev_b32_e32 v1, 2, v1
	ds_bpermute_b32 v1, v1, v0
	s_waitcnt lgkmcnt(0)
	v_add_f32_e32 v0, v0, v1
	v_xor_b32_e32 v1, 32, v192
	v_cmp_lt_i32_e32 vcc, v1, v2
	s_nop 1
	v_cndmask_b32_e32 v1, v192, v1, vcc
	v_lshlrev_b32_e32 v1, 2, v1
	ds_bpermute_b32 v1, v1, v0
	s_and_saveexec_b64 s[6:7], s[0:1]
	s_cbranch_execz .LBB0_837
	v_lshlrev_b64 v[2:3], 7, v[88:89]
	v_lshl_add_u64 v[2:3], s[24:25], 0, v[2:3]
	v_lshl_add_u64 v[2:3], s[26:27], 2, v[2:3]
	s_lshl_b32 s8, s40, 2
	v_lshl_add_u64 v[2:3], v[2:3], 0, s[8:9]
	s_waitcnt lgkmcnt(0)
	v_add_f32_e32 v0, v0, v1
	global_store_dword v[2:3], v0, off
	s_branch .LBB0_837

; #define PG8_STAGE(bufoff, gbase, voff) do { _Pragma("unroll") for (int _i = 0; _i < 2; ++_i) \
;         __builtin_amdgcn_global_load_lds((const unsigned*)((const char*)(gbase) + (voff)[_i]), (LAS unsigned*)(lds + (bufoff) + ldsw + _i * 8192), 16, 0, 0); } while (0)
; #define PG8_LDA(dst, b, h) do { _Pragma("unroll") for (int m = 0; m < 4; ++m) _Pragma("unroll") for (int k = 0; k < 2; ++k) dst[m][k] = *(const LAS bf16x8*)(lds + PG8_SA(b, h) + aoff + m * 2048 + k * 1024); } while (0)
; #define PG8_LDB(dst, b, h) do { _Pragma("unroll") for (int n = 0; n < 2; ++n) _Pragma("unroll") for (int k = 0; k < 2; ++k) dst[n][k] = *(const LAS bf16x8*)(lds + PG8_SB(b, h) + boff + n * 2048 + k * 1024); } while (0)
; #define PG8_MMA(ai, bj, At, Bt) do { __builtin_amdgcn_s_setprio(1); _Pragma("unroll") for (int m = 0; m < 4; ++m) _Pragma("unroll") for (int n = 0; n < 2; ++n) _Pragma("unroll") for (int k = 0; k < 2; ++k) \
;         acc[ai][bj][m][n] = __builtin_amdgcn_mfma_f32_16x16x32_bf16(Bt[n][k], At[m][k], acc[ai][bj][m][n], 0, 0, 0); __builtin_amdgcn_s_setprio(0); } while (0)
; #define PG8_WAIT_V(n) asm volatile("s_waitcnt vmcnt(" #n ")" ::: "memory")
; #define PG8_WAIT_L(n) asm volatile("s_waitcnt lgkmcnt(" #n ")" ::: "memory")
; #define PG8_BAR __builtin_amdgcn_s_barrier()
; #define PG8_SCHED __builtin_amdgcn_sched_barrier(0)
; template <class Epi>
; __device__ __forceinline__ void gemm_phase(LAS unsigned char* lds, const Gemm g, const Order& S, const Epi& E, const int tid) {
;     ...
;             PG8_LDB(B0, 0, 0); PG8_SCHED; PG8_LDA(At, 0, 0); PG8_STAGE(PG8_SA(1, 1), a1 + hstepA, voffA);
;             PG8_WAIT_L(8); PG8_BAR; PG8_WAIT_L(0); PG8_MMA(0, 0, At, B0); PG8_BAR; PG8_SCHED;
;             PG8_LDB(B1, 0, 1); PG8_STAGE(PG8_SB(0, 0), b2, voffB);
;             PG8_BAR; PG8_WAIT_L(0); PG8_MMA(0, 1, At, B1); PG8_BAR;
;             PG8_LDA(At, 0, 1); PG8_STAGE(PG8_SA(0, 0), a2, voffA);
;             PG8_BAR; PG8_WAIT_L(0); PG8_MMA(1, 0, At, B0); PG8_BAR; PG8_SCHED;
;             PG8_STAGE(PG8_SB(0, 1), b2 + hstepB, voffB);
;             PG8_WAIT_V(6); PG8_BAR; PG8_MMA(1, 1, At, B1); PG8_BAR;
;             PG8_LDB(B0, 1, 0); PG8_SCHED; PG8_LDA(At, 1, 0); PG8_STAGE(PG8_SA(0, 1), a2 + hstepA, voffA);
;             PG8_WAIT_L(8); PG8_BAR; PG8_WAIT_L(0); PG8_MMA(0, 0, At, B0); PG8_BAR; PG8_SCHED;
.LBB0_938:
	ds_read_b128 v[144:147], v153
	ds_read_b128 v[156:159], v153 offset:1024
	ds_read_b128 v[160:163], v153 offset:2048
	ds_read_b128 v[164:167], v153 offset:3072
	s_add_u32 s28, s26, 0xffe00080
	s_addc_u32 s29, s27, -1
	s_cmpk_eq_i32 s48, 0x7c
	s_cselect_b32 s31, s15, s29
	s_cselect_b32 s30, s44, s28
	s_cselect_b32 s29, s17, s47
	s_cselect_b32 s28, s45, s46
	v_lshl_add_u64 v[148:149], s[26:27], 0, v[136:137]
	s_add_i32 m0, s25, 0xc000
	ds_read_b128 v[168:171], v154
	ds_read_b128 v[172:175], v154 offset:1024
	ds_read_b128 v[176:179], v154 offset:2048
	ds_read_b128 v[180:183], v154 offset:3072
	ds_read_b128 v[184:187], v154 offset:4096
	ds_read_b128 v[188:191], v154 offset:5120
	ds_read_b128 v[192:195], v154 offset:6144
	ds_read_b128 v[196:199], v154 offset:7168
	global_load_lds_dwordx4 v[148:149], off
	v_lshl_add_u64 v[148:149], s[26:27], 0, v[138:139]
	s_add_i32 m0, s25, 0xe000
	s_nop 0
	global_load_lds_dwordx4 v[148:149], off
	s_waitcnt lgkmcnt(8)
	s_barrier
	s_waitcnt lgkmcnt(0)
	s_setprio 1
	s_waitcnt lgkmcnt(0)
	v_mfma_f32_16x16x32_bf16 v[124:127], v[144:147], v[168:171], v[124:127]
	v_mfma_f32_16x16x32_bf16 v[120:123], v[160:163], v[168:171], v[120:123]
	v_mfma_f32_16x16x32_bf16 v[116:119], v[144:147], v[176:179], v[116:119]
	v_mfma_f32_16x16x32_bf16 v[112:115], v[160:163], v[176:179], v[112:115]
	v_mfma_f32_16x16x32_bf16 v[96:99], v[144:147], v[184:187], v[96:99]
	v_mfma_f32_16x16x32_bf16 v[88:91], v[160:163], v[184:187], v[88:91]
	v_mfma_f32_16x16x32_bf16 v[80:83], v[144:147], v[192:195], v[80:83]
	v_mfma_f32_16x16x32_bf16 v[72:75], v[160:163], v[192:195], v[72:75]
	v_mfma_f32_16x16x32_bf16 v[124:127], v[156:159], v[172:175], v[124:127]
	v_mfma_f32_16x16x32_bf16 v[120:123], v[164:167], v[172:175], v[120:123]
	v_mfma_f32_16x16x32_bf16 v[116:119], v[156:159], v[180:183], v[116:119]
	v_mfma_f32_16x16x32_bf16 v[112:115], v[164:167], v[180:183], v[112:115]
	v_mfma_f32_16x16x32_bf16 v[96:99], v[156:159], v[188:191], v[96:99]
	v_mfma_f32_16x16x32_bf16 v[88:91], v[164:167], v[188:191], v[88:91]
	v_mfma_f32_16x16x32_bf16 v[80:83], v[156:159], v[196:199], v[80:83]
	v_mfma_f32_16x16x32_bf16 v[72:75], v[164:167], v[196:199], v[72:75]
	s_setprio 0
	s_barrier
	s_add_i32 s49, s41, s33
	v_lshl_add_u64 v[148:149], s[28:29], 0, v[132:133]
	s_mov_b32 m0, s49
	ds_read_b128 v[200:203], v155
	ds_read_b128 v[204:207], v155 offset:1024
	ds_read_b128 v[208:211], v155 offset:2048
	ds_read_b128 v[212:215], v155 offset:3072
	global_load_lds_dwordx4 v[148:149], off
	v_lshl_add_u64 v[216:217], s[28:29], 0, v[128:129]
	s_add_i32 m0, s49, 0x2000
	s_nop 0
	global_load_lds_dwordx4 v[216:217], off
	s_barrier
	s_waitcnt lgkmcnt(0)
	s_setprio 1
	s_waitcnt lgkmcnt(0)
	v_mfma_f32_16x16x32_bf16 v[108:111], v[200:203], v[168:171], v[108:111]
	v_mfma_f32_16x16x32_bf16 v[104:107], v[208:211], v[168:171], v[104:107]
	v_mfma_f32_16x16x32_bf16 v[100:103], v[200:203], v[176:179], v[100:103]
	v_mfma_f32_16x16x32_bf16 v[92:95], v[208:211], v[176:179], v[92:95]
	v_mfma_f32_16x16x32_bf16 v[84:87], v[200:203], v[184:187], v[84:87]
	v_mfma_f32_16x16x32_bf16 v[76:79], v[208:211], v[184:187], v[76:79]
	v_mfma_f32_16x16x32_bf16 v[68:71], v[200:203], v[192:195], v[68:71]
	v_mfma_f32_16x16x32_bf16 v[64:67], v[208:211], v[192:195], v[64:67]
	v_mfma_f32_16x16x32_bf16 v[108:111], v[204:207], v[172:175], v[108:111]
	v_mfma_f32_16x16x32_bf16 v[104:107], v[212:215], v[172:175], v[104:107]
	v_mfma_f32_16x16x32_bf16 v[100:103], v[204:207], v[180:183], v[100:103]
	v_mfma_f32_16x16x32_bf16 v[92:95], v[212:215], v[180:183], v[92:95]
	v_mfma_f32_16x16x32_bf16 v[84:87], v[204:207], v[188:191], v[84:87]
	v_mfma_f32_16x16x32_bf16 v[76:79], v[212:215], v[188:191], v[76:79]
	v_mfma_f32_16x16x32_bf16 v[68:71], v[204:207], v[196:199], v[68:71]
	v_mfma_f32_16x16x32_bf16 v[64:67], v[212:215], v[196:199], v[64:67]
	s_setprio 0
	s_mov_b32 m0, s25
	v_lshl_add_u64 v[218:219], s[30:31], 0, v[134:135]
	s_barrier
	ds_read_b128 v[168:171], v154 offset:16384
	ds_read_b128 v[172:175], v154 offset:17408
	ds_read_b128 v[176:179], v154 offset:18432
	ds_read_b128 v[180:183], v154 offset:19456
	ds_read_b128 v[184:187], v154 offset:20480
	ds_read_b128 v[188:191], v154 offset:21504
	ds_read_b128 v[192:195], v154 offset:22528
	ds_read_b128 v[196:199], v154 offset:23552
	global_load_lds_dwordx4 v[218:219], off
	v_lshl_add_u64 v[220:221], s[30:31], 0, v[130:131]
	s_mov_b32 m0, s35
	s_nop 0
	global_load_lds_dwordx4 v[220:221], off
	s_barrier
	s_waitcnt lgkmcnt(0)
	s_setprio 1
	s_waitcnt lgkmcnt(0)
	v_mfma_f32_16x16x32_bf16 v[60:63], v[144:147], v[168:171], v[60:63]
	v_mfma_f32_16x16x32_bf16 v[56:59], v[160:163], v[168:171], v[56:59]
	v_mfma_f32_16x16x32_bf16 v[48:51], v[144:147], v[176:179], v[48:51]
	v_mfma_f32_16x16x32_bf16 v[40:43], v[160:163], v[176:179], v[40:43]
	v_mfma_f32_16x16x32_bf16 v[32:35], v[144:147], v[184:187], v[32:35]
	v_mfma_f32_16x16x32_bf16 v[24:27], v[160:163], v[184:187], v[24:27]
	v_mfma_f32_16x16x32_bf16 v[16:19], v[144:147], v[192:195], v[16:19]
	v_mfma_f32_16x16x32_bf16 v[8:11], v[160:163], v[192:195], v[8:11]
	v_mfma_f32_16x16x32_bf16 v[60:63], v[156:159], v[172:175], v[60:63]
	v_mfma_f32_16x16x32_bf16 v[56:59], v[164:167], v[172:175], v[56:59]
	v_mfma_f32_16x16x32_bf16 v[48:51], v[156:159], v[180:183], v[48:51]
	v_mfma_f32_16x16x32_bf16 v[40:43], v[164:167], v[180:183], v[40:43]
	v_mfma_f32_16x16x32_bf16 v[32:35], v[156:159], v[188:191], v[32:35]
	v_mfma_f32_16x16x32_bf16 v[24:27], v[164:167], v[188:191], v[24:27]
	v_mfma_f32_16x16x32_bf16 v[16:19], v[156:159], v[196:199], v[16:19]
	v_mfma_f32_16x16x32_bf16 v[8:11], v[164:167], v[196:199], v[8:11]
	s_setprio 0
	s_barrier
; #define PG8_STAGE(bufoff, gbase, voff) do { _Pragma("unroll") for (int _i = 0; _i < 2; ++_i) \
;         __builtin_amdgcn_global_load_lds((const unsigned*)((const char*)(gbase) + (voff)[_i]), (LAS unsigned*)(lds + (bufoff) + ldsw + _i * 8192), 16, 0, 0); } while (0)
; #define PG8_LDA(dst, b, h) do { _Pragma("unroll") for (int m = 0; m < 4; ++m) _Pragma("unroll") for (int k = 0; k < 2; ++k) dst[m][k] = *(const LAS bf16x8*)(lds + PG8_SA(b, h) + aoff + m * 2048 + k * 1024); } while (0)
; #define PG8_LDB(dst, b, h) do { _Pragma("unroll") for (int n = 0; n < 2; ++n) _Pragma("unroll") for (int k = 0; k < 2; ++k) dst[n][k] = *(const LAS bf16x8*)(lds + PG8_SB(b, h) + boff + n * 2048 + k * 1024); } while (0)
; #define PG8_MMA(ai, bj, At, Bt) do { __builtin_amdgcn_s_setprio(1); _Pragma("unroll") for (int m = 0; m < 4; ++m) _Pragma("unroll") for (int n = 0; n < 2; ++n) _Pragma("unroll") for (int k = 0; k < 2; ++k) \
;         acc[ai][bj][m][n] = __builtin_amdgcn_mfma_f32_16x16x32_bf16(Bt[n][k], At[m][k], acc[ai][bj][m][n], 0, 0, 0); __builtin_amdgcn_s_setprio(0); } while (0)
; #define PG8_WAIT_V(n) asm volatile("s_waitcnt vmcnt(" #n ")" ::: "memory")
; #define PG8_WAIT_L(n) asm volatile("s_waitcnt lgkmcnt(" #n ")" ::: "memory")
; #define PG8_BAR __builtin_amdgcn_s_barrier()
; #define PG8_SCHED __builtin_amdgcn_sched_barrier(0)
; template <class Epi>
; __device__ __forceinline__ void gemm_phase(LAS unsigned char* lds, const Gemm g, const Order& S, const Epi& E, const int tid) {
;     ...
;             PG8_STAGE(PG8_SB(0, 1), b2 + hstepB, voffB);
;             PG8_WAIT_V(6); PG8_BAR; PG8_MMA(1, 1, At, B1); PG8_BAR;
;             PG8_LDB(B0, 1, 0); PG8_SCHED; PG8_LDA(At, 1, 0); PG8_STAGE(PG8_SA(0, 1), a2 + hstepA, voffA);
;             PG8_WAIT_L(8); PG8_BAR; PG8_WAIT_L(0); PG8_MMA(0, 0, At, B0); PG8_BAR; PG8_SCHED;
;             PG8_LDB(B1, 1, 1); PG8_STAGE(PG8_SB(1, 0), b3, voffB);
;             PG8_BAR; PG8_WAIT_L(0); PG8_MMA(0, 1, At, B1); PG8_BAR;
;             PG8_LDA(At, 1, 1); PG8_STAGE(PG8_SA(1, 0), a3, voffA);
	s_add_u32 s50, s28, 0x200000
	s_addc_u32 s51, s29, 0
	s_add_i32 s49, s42, s33
	v_lshl_add_u64 v[144:145], s[50:51], 0, v[132:133]
	s_mov_b32 m0, s49
	s_nop 0
	global_load_lds_dwordx4 v[144:145], off
	v_lshl_add_u64 v[144:145], s[50:51], 0, v[128:129]
	s_add_i32 m0, s49, 0x2000
	s_nop 0
	global_load_lds_dwordx4 v[144:145], off
	s_waitcnt vmcnt(6)
	s_barrier
	s_setprio 1
	v_mfma_f32_16x16x32_bf16 v[52:55], v[200:203], v[168:171], v[52:55]
	v_mfma_f32_16x16x32_bf16 v[44:47], v[208:211], v[168:171], v[44:47]
	v_mfma_f32_16x16x32_bf16 v[36:39], v[200:203], v[176:179], v[36:39]
	v_mfma_f32_16x16x32_bf16 v[28:31], v[208:211], v[176:179], v[28:31]
	v_mfma_f32_16x16x32_bf16 v[20:23], v[200:203], v[184:187], v[20:23]
	v_mfma_f32_16x16x32_bf16 v[12:15], v[208:211], v[184:187], v[12:15]
	v_mfma_f32_16x16x32_bf16 v[4:7], v[200:203], v[192:195], v[4:7]
	v_mfma_f32_16x16x32_bf16 v[0:3], v[208:211], v[192:195], v[0:3]
	v_mfma_f32_16x16x32_bf16 v[52:55], v[204:207], v[172:175], v[52:55]
	v_mfma_f32_16x16x32_bf16 v[44:47], v[212:215], v[172:175], v[44:47]
	v_mfma_f32_16x16x32_bf16 v[36:39], v[204:207], v[180:183], v[36:39]
	v_mfma_f32_16x16x32_bf16 v[28:31], v[212:215], v[180:183], v[28:31]
	v_mfma_f32_16x16x32_bf16 v[20:23], v[204:207], v[188:191], v[20:23]
	v_mfma_f32_16x16x32_bf16 v[12:15], v[212:215], v[188:191], v[12:15]
	v_mfma_f32_16x16x32_bf16 v[4:7], v[204:207], v[196:199], v[4:7]
	v_mfma_f32_16x16x32_bf16 v[0:3], v[212:215], v[196:199], v[0:3]
	s_setprio 0
	s_add_i32 s49, 0, 0x18000
	v_add_u32_e32 v164, s49, v151
	s_barrier
	ds_read_b128 v[144:147], v164
	ds_read_b128 v[156:159], v164 offset:1024
	ds_read_b128 v[160:163], v164 offset:2048
	ds_read_b128 v[164:167], v164 offset:3072
	s_add_u32 s30, s30, 0x200000
	s_addc_u32 s31, s31, 0
	s_mov_b32 m0, s36
	v_lshl_add_u64 v[200:201], s[30:31], 0, v[134:135]
	ds_read_b128 v[168:171], v154 offset:32768
	ds_read_b128 v[172:175], v154 offset:33792
	ds_read_b128 v[176:179], v154 offset:34816
	ds_read_b128 v[180:183], v154 offset:35840
	ds_read_b128 v[184:187], v154 offset:36864
	ds_read_b128 v[188:191], v154 offset:37888
	ds_read_b128 v[192:195], v154 offset:38912
	ds_read_b128 v[196:199], v154 offset:39936
	global_load_lds_dwordx4 v[200:201], off
	v_lshl_add_u64 v[200:201], s[30:31], 0, v[130:131]
	s_mov_b32 m0, s37
	s_nop 0
	global_load_lds_dwordx4 v[200:201], off
	s_waitcnt lgkmcnt(8)
	s_barrier
	s_waitcnt lgkmcnt(0)
	s_setprio 1
	s_waitcnt lgkmcnt(0)
	v_mfma_f32_16x16x32_bf16 v[124:127], v[144:147], v[168:171], v[124:127]
	v_mfma_f32_16x16x32_bf16 v[120:123], v[160:163], v[168:171], v[120:123]
	v_mfma_f32_16x16x32_bf16 v[116:119], v[144:147], v[176:179], v[116:119]
	v_mfma_f32_16x16x32_bf16 v[112:115], v[160:163], v[176:179], v[112:115]
	v_mfma_f32_16x16x32_bf16 v[96:99], v[144:147], v[184:187], v[96:99]
	v_mfma_f32_16x16x32_bf16 v[88:91], v[160:163], v[184:187], v[88:91]
	v_mfma_f32_16x16x32_bf16 v[80:83], v[144:147], v[192:195], v[80:83]
	v_mfma_f32_16x16x32_bf16 v[72:75], v[160:163], v[192:195], v[72:75]
	v_mfma_f32_16x16x32_bf16 v[124:127], v[156:159], v[172:175], v[124:127]
	v_mfma_f32_16x16x32_bf16 v[120:123], v[164:167], v[172:175], v[120:123]
	v_mfma_f32_16x16x32_bf16 v[116:119], v[156:159], v[180:183], v[116:119]
	v_mfma_f32_16x16x32_bf16 v[112:115], v[164:167], v[180:183], v[112:115]
	v_mfma_f32_16x16x32_bf16 v[96:99], v[156:159], v[188:191], v[96:99]
	v_mfma_f32_16x16x32_bf16 v[88:91], v[164:167], v[188:191], v[88:91]
	v_mfma_f32_16x16x32_bf16 v[80:83], v[156:159], v[196:199], v[80:83]
	v_mfma_f32_16x16x32_bf16 v[72:75], v[164:167], v[196:199], v[72:75]
	s_setprio 0
	s_barrier
	s_add_i32 s30, 0, 0x1c000
	s_add_i32 s31, s49, s33
	v_add_u32_e32 v212, s30, v151
	v_lshl_add_u64 v[148:149], v[148:149], 0, s[4:5]
	s_mov_b32 m0, s31
	ds_read_b128 v[200:203], v212
	ds_read_b128 v[204:207], v212 offset:1024
	ds_read_b128 v[208:211], v212 offset:2048
	ds_read_b128 v[212:215], v212 offset:3072
	global_load_lds_dwordx4 v[148:149], off
	v_lshl_add_u64 v[148:149], v[216:217], 0, s[4:5]
	s_add_i32 m0, s31, 0x2000
	s_nop 0
	global_load_lds_dwordx4 v[148:149], off
	s_barrier
	s_waitcnt lgkmcnt(0)
	s_setprio 1
	s_waitcnt lgkmcnt(0)
	v_mfma_f32_16x16x32_bf16 v[108:111], v[200:203], v[168:171], v[108:111]
	v_mfma_f32_16x16x32_bf16 v[104:107], v[208:211], v[168:171], v[104:107]
	v_mfma_f32_16x16x32_bf16 v[100:103], v[200:203], v[176:179], v[100:103]
	v_mfma_f32_16x16x32_bf16 v[92:95], v[208:211], v[176:179], v[92:95]
	v_mfma_f32_16x16x32_bf16 v[84:87], v[200:203], v[184:187], v[84:87]
	v_mfma_f32_16x16x32_bf16 v[76:79], v[208:211], v[184:187], v[76:79]
	v_mfma_f32_16x16x32_bf16 v[68:71], v[200:203], v[192:195], v[68:71]
	v_mfma_f32_16x16x32_bf16 v[64:67], v[208:211], v[192:195], v[64:67]
	v_mfma_f32_16x16x32_bf16 v[108:111], v[204:207], v[172:175], v[108:111]
	v_mfma_f32_16x16x32_bf16 v[104:107], v[212:215], v[172:175], v[104:107]
	v_mfma_f32_16x16x32_bf16 v[100:103], v[204:207], v[180:183], v[100:103]
	v_mfma_f32_16x16x32_bf16 v[92:95], v[212:215], v[180:183], v[92:95]
	v_mfma_f32_16x16x32_bf16 v[84:87], v[204:207], v[188:191], v[84:87]
	v_mfma_f32_16x16x32_bf16 v[76:79], v[212:215], v[188:191], v[76:79]
	v_mfma_f32_16x16x32_bf16 v[68:71], v[204:207], v[196:199], v[68:71]
	v_mfma_f32_16x16x32_bf16 v[64:67], v[212:215], v[196:199], v[64:67]
	s_setprio 0
	s_mov_b32 m0, s39
	v_lshl_add_u64 v[148:149], v[218:219], 0, s[4:5]
	s_barrier
	ds_read_b128 v[168:171], v154 offset:49152
	ds_read_b128 v[172:175], v154 offset:50176
	ds_read_b128 v[176:179], v154 offset:51200
	ds_read_b128 v[180:183], v154 offset:52224
	ds_read_b128 v[184:187], v154 offset:53248
	ds_read_b128 v[188:191], v154 offset:54272
	ds_read_b128 v[192:195], v154 offset:55296
	ds_read_b128 v[196:199], v154 offset:56320
	global_load_lds_dwordx4 v[148:149], off
	v_lshl_add_u64 v[148:149], v[220:221], 0, s[4:5]
	s_mov_b32 m0, s40
	s_nop 0
	global_load_lds_dwordx4 v[148:149], off
	s_barrier
; #define PG8_STAGE(bufoff, gbase, voff) do { _Pragma("unroll") for (int _i = 0; _i < 2; ++_i) \
;         __builtin_amdgcn_global_load_lds((const unsigned*)((const char*)(gbase) + (voff)[_i]), (LAS unsigned*)(lds + (bufoff) + ldsw + _i * 8192), 16, 0, 0); } while (0)
; #define PG8_MMA(ai, bj, At, Bt) do { __builtin_amdgcn_s_setprio(1); _Pragma("unroll") for (int m = 0; m < 4; ++m) _Pragma("unroll") for (int n = 0; n < 2; ++n) _Pragma("unroll") for (int k = 0; k < 2; ++k) \
;         acc[ai][bj][m][n] = __builtin_amdgcn_mfma_f32_16x16x32_bf16(Bt[n][k], At[m][k], acc[ai][bj][m][n], 0, 0, 0); __builtin_amdgcn_s_setprio(0); } while (0)
; #define PG8_WAIT_V(n) asm volatile("s_waitcnt vmcnt(" #n ")" ::: "memory")
; #define PG8_WAIT_L(n) asm volatile("s_waitcnt lgkmcnt(" #n ")" ::: "memory")
; #define PG8_BAR __builtin_amdgcn_s_barrier()
; #define PG8_SCHED __builtin_amdgcn_sched_barrier(0)
; template <class Epi>
; __device__ __forceinline__ void gemm_phase(LAS unsigned char* lds, const Gemm g, const Order& S, const Epi& E, const int tid) {
;     ...
;             PG8_BAR; PG8_WAIT_L(0); PG8_MMA(1, 0, At, B0); PG8_BAR; PG8_SCHED;
;             PG8_STAGE(PG8_SB(1, 1), b3 + hstepB, voffB);
;             PG8_WAIT_V(6); PG8_BAR; PG8_MMA(1, 1, At, B1); PG8_BAR;
;     __device__ __forceinline__ void operator()(const f32x4 (&acc)[2][2][4][2], const Unit& u, int wr, int wc, int fr, int fq) const {
;     ...
;                 u32x4 bs[4][2];
; #pragma unroll
;                 for (int m = 0; m < 4; ++m) { const size_t off = (size_t)(row0 + ai * HALF + m * 16) * DM + col0;
; #pragma unroll
;                     for (int bj = 0; bj < 2; ++bj) bs[m][bj] = *(const u32x4*)(baseb + off + bj * HALF); }
	s_waitcnt lgkmcnt(0)
	s_setprio 1
	s_waitcnt lgkmcnt(0)
	v_mfma_f32_16x16x32_bf16 v[60:63], v[144:147], v[168:171], v[60:63]
	v_mfma_f32_16x16x32_bf16 v[56:59], v[160:163], v[168:171], v[56:59]
	v_mfma_f32_16x16x32_bf16 v[48:51], v[144:147], v[176:179], v[48:51]
	v_mfma_f32_16x16x32_bf16 v[40:43], v[160:163], v[176:179], v[40:43]
	v_mfma_f32_16x16x32_bf16 v[32:35], v[144:147], v[184:187], v[32:35]
	v_mfma_f32_16x16x32_bf16 v[24:27], v[160:163], v[184:187], v[24:27]
	v_mfma_f32_16x16x32_bf16 v[16:19], v[144:147], v[192:195], v[16:19]
	v_mfma_f32_16x16x32_bf16 v[8:11], v[160:163], v[192:195], v[8:11]
	v_mfma_f32_16x16x32_bf16 v[60:63], v[156:159], v[172:175], v[60:63]
	v_mfma_f32_16x16x32_bf16 v[56:59], v[164:167], v[172:175], v[56:59]
	v_mfma_f32_16x16x32_bf16 v[48:51], v[156:159], v[180:183], v[48:51]
	v_mfma_f32_16x16x32_bf16 v[40:43], v[164:167], v[180:183], v[40:43]
	v_mfma_f32_16x16x32_bf16 v[32:35], v[156:159], v[188:191], v[32:35]
	v_mfma_f32_16x16x32_bf16 v[24:27], v[164:167], v[188:191], v[24:27]
	v_mfma_f32_16x16x32_bf16 v[16:19], v[156:159], v[196:199], v[16:19]
	v_mfma_f32_16x16x32_bf16 v[8:11], v[164:167], v[196:199], v[8:11]
	s_setprio 0
	s_barrier
	s_add_u32 s28, s28, 0x200080
	s_addc_u32 s29, s29, 0
	s_add_i32 s30, s30, s33
	v_lshl_add_u64 v[144:145], s[28:29], 0, v[132:133]
	s_mov_b32 m0, s30
	s_nop 0
	global_load_lds_dwordx4 v[144:145], off
	v_lshl_add_u64 v[144:145], s[28:29], 0, v[128:129]
	s_add_i32 m0, s30, 0x2000
	s_nop 0
	global_load_lds_dwordx4 v[144:145], off
	s_waitcnt vmcnt(6)
	s_barrier
	s_setprio 1
	v_mfma_f32_16x16x32_bf16 v[52:55], v[200:203], v[168:171], v[52:55]
	v_mfma_f32_16x16x32_bf16 v[44:47], v[208:211], v[168:171], v[44:47]
	v_mfma_f32_16x16x32_bf16 v[36:39], v[200:203], v[176:179], v[36:39]
	v_mfma_f32_16x16x32_bf16 v[28:31], v[208:211], v[176:179], v[28:31]
	v_mfma_f32_16x16x32_bf16 v[20:23], v[200:203], v[184:187], v[20:23]
	v_mfma_f32_16x16x32_bf16 v[12:15], v[208:211], v[184:187], v[12:15]
	v_mfma_f32_16x16x32_bf16 v[4:7], v[200:203], v[192:195], v[4:7]
	v_mfma_f32_16x16x32_bf16 v[0:3], v[208:211], v[192:195], v[0:3]
	v_mfma_f32_16x16x32_bf16 v[52:55], v[204:207], v[172:175], v[52:55]
	v_mfma_f32_16x16x32_bf16 v[44:47], v[212:215], v[172:175], v[44:47]
	v_mfma_f32_16x16x32_bf16 v[36:39], v[204:207], v[180:183], v[36:39]
	v_mfma_f32_16x16x32_bf16 v[28:31], v[212:215], v[180:183], v[28:31]
	v_mfma_f32_16x16x32_bf16 v[20:23], v[204:207], v[188:191], v[20:23]
	v_mfma_f32_16x16x32_bf16 v[12:15], v[212:215], v[188:191], v[12:15]
	v_mfma_f32_16x16x32_bf16 v[4:7], v[204:207], v[196:199], v[4:7]
	v_mfma_f32_16x16x32_bf16 v[0:3], v[212:215], v[196:199], v[0:3]
	s_setprio 0
	s_add_i32 s48, s48, 2
	s_add_u32 s26, s26, 0x100
	s_addc_u32 s27, s27, 0
	s_add_u32 s46, s46, 0x100
	s_addc_u32 s47, s47, 0
	s_cmpk_gt_u32 s48, 0x7d
	s_barrier
	s_cbranch_scc0 .LBB0_938
	v_lshl_or_b32 v144, s43, 8, v152
	v_lshl_add_u32 v172, s24, 8, v150
	v_ashrrev_i32_e32 v145, 31, v144
	v_lshlrev_b64 v[144:145], 1, v[144:145]
	v_ashrrev_i32_e32 v173, 31, v172
	v_lshl_add_u64 v[146:147], s[22:23], 0, v[144:145]
	v_lshlrev_b64 v[148:149], 12, v[172:173]
	v_or_b32_e32 v164, 16, v172
	v_lshl_add_u64 v[160:161], v[146:147], 0, v[148:149]
	v_ashrrev_i32_e32 v165, 31, v164
	global_load_dwordx4 v[156:159], v[160:161], off
	s_nop 0
	global_load_dwordx4 v[160:163], v[160:161], off offset:256
	v_lshlrev_b64 v[188:189], 12, v[164:165]
	v_lshl_add_u64 v[168:169], v[146:147], 0, v[188:189]
	global_load_dwordx4 v[164:167], v[168:169], off
	s_nop 0
	global_load_dwordx4 v[168:171], v[168:169], off offset:256
	v_or_b32_e32 v174, 32, v172
	v_or_b32_e32 v172, 48, v172
	v_ashrrev_i32_e32 v175, 31, v174
	v_ashrrev_i32_e32 v173, 31, v172
	v_lshlrev_b64 v[190:191], 12, v[174:175]
	v_lshlrev_b64 v[192:193], 12, v[172:173]
	v_lshl_add_u64 v[172:173], s[22:23], 0, v[148:149]
	v_lshl_add_u64 v[176:177], v[146:147], 0, v[190:191]
	v_lshl_add_u64 v[184:185], v[146:147], 0, v[192:193]
	v_lshl_add_u64 v[194:195], v[172:173], 0, v[144:145]
	global_load_dwordx4 v[172:175], v[176:177], off
	s_nop 0
	global_load_dwordx4 v[176:179], v[176:177], off offset:256
	s_nop 0
	global_load_dwordx4 v[180:183], v[184:185], off
	s_nop 0
	global_load_dwordx4 v[184:187], v[184:185], off offset:256
	s_and_b64 vcc, exec, s[0:1]
	s_mov_b32 s43, s16
	s_mov_b32 s24, s14
	s_mov_b64 s[28:29], s[20:21]
	s_mov_b64 s[26:27], s[18:19]
	s_waitcnt vmcnt(0)
; __device__ __forceinline__ float bflo(unsigned w) { return __uint_as_float(w << 16); }
; __device__ __forceinline__ float bfhi(unsigned w) { return __uint_as_float(w & 0xffff0000u); }
;     __device__ __forceinline__ void operator()(const f32x4 (&acc)[2][2][4][2], const Unit& u, int wr, int wc, int fr, int fq) const {
;     ...
;                 u32x4 bs[4][2];
; #pragma unroll
;                 for (int m = 0; m < 4; ++m) { const size_t off = (size_t)(row0 + ai * HALF + m * 16) * DM + col0;
; #pragma unroll
;                     for (int bj = 0; bj < 2; ++bj) bs[m][bj] = *(const u32x4*)(baseb + off + bj * HALF); }
; #pragma unroll
;                 for (int m = 0; m < 4; ++m) { const size_t off = (size_t)(row0 + ai * HALF + m * 16) * DM + col0;
;                     float ss = 0.f;
; #pragma unroll
;                     for (int bj = 0; bj < 2; ++bj) { const u32x4 q = bs[m][bj]; const f32x4 a0 = acc[ai][bj][m][0], a1 = acc[ai][bj][m][1];
;                         const float h0 = bflo(q.x) + a0[0], h1 = bfhi(q.x) + a0[1], h2 = bflo(q.y) + a0[2], h3 = bfhi(q.y) + a0[3], h4 = bflo(q.z) + a1[0], h5 = bfhi(q.z) + a1[1], h6 = bflo(q.w) + a1[2], h7 = bfhi(q.w) + a1[3];
;                         ss += (h0 * h0 + h1 * h1) + (h2 * h2 + h3 * h3) + (h4 * h4 + h5 * h5) + (h6 * h6 + h7 * h7);
;                         u32x4 w; w.x = pk2(h0, h1); w.y = pk2(h2, h3); w.z = pk2(h4, h5); w.w = pk2(h6, h7);
;                         *(u32x4*)(out + off + bj * HALF) = w; }
;                     if (ssqp) { ss += __shfl_xor(ss, 16); ss += __shfl_xor(ss, 32); if (fq == 0) ssqp[(size_t)(row0 + ai * HALF + m * 16) * 32 + u.pn * 4 + wc] = ss; } }
;                 asm volatile("" ::: "memory");
	v_lshlrev_b32_e32 v196, 16, v156
	v_and_b32_e32 v156, 0xffff0000, v156
	v_lshlrev_b32_e32 v197, 16, v157
	v_and_b32_e32 v157, 0xffff0000, v157
	v_lshlrev_b32_e32 v198, 16, v158
	v_and_b32_e32 v158, 0xffff0000, v158
	v_lshlrev_b32_e32 v199, 16, v159
	v_and_b32_e32 v159, 0xffff0000, v159
	v_lshlrev_b32_e32 v200, 16, v160
	v_and_b32_e32 v160, 0xffff0000, v160
	v_lshlrev_b32_e32 v201, 16, v161
	v_and_b32_e32 v161, 0xffff0000, v161
	v_lshlrev_b32_e32 v202, 16, v162
	v_and_b32_e32 v162, 0xffff0000, v162
	v_lshlrev_b32_e32 v203, 16, v163
	v_and_b32_e32 v163, 0xffff0000, v163
	v_add_f32_e32 v124, v124, v196
	v_add_f32_e32 v125, v125, v156
	v_add_f32_e32 v126, v126, v197
	v_add_f32_e32 v127, v127, v157
	v_add_f32_e32 v120, v120, v198
	v_add_f32_e32 v121, v121, v158
	v_add_f32_e32 v122, v122, v199
	v_add_f32_e32 v123, v123, v159
	v_add_f32_e32 v108, v108, v200
	v_add_f32_e32 v109, v109, v160
	v_add_f32_e32 v110, v110, v201
	v_add_f32_e32 v111, v111, v161
	v_add_f32_e32 v156, v104, v202
	v_add_f32_e32 v157, v105, v162
	v_add_f32_e32 v158, v106, v203
	v_add_f32_e32 v159, v107, v163
	v_cvt_pk_bf16_f32 v104, v124, v125
	v_cvt_pk_bf16_f32 v105, v126, v127
	v_cvt_pk_bf16_f32 v106, v120, v121
	v_cvt_pk_bf16_f32 v107, v122, v123
	v_cvt_pk_bf16_f32 v108, v108, v109
	v_cvt_pk_bf16_f32 v109, v110, v111
	v_cvt_pk_bf16_f32 v110, v156, v157
	v_cvt_pk_bf16_f32 v111, v158, v159
	global_store_dwordx4 v[194:195], v[104:107], off sc0 sc1
	global_store_dwordx4 v[194:195], v[108:111], off offset:256 sc0 sc1
	v_lshlrev_b32_e32 v204, 16, v164
	v_lshlrev_b32_e32 v106, 16, v168
	v_add_f32_e32 v100, v100, v106
	v_and_b32_e32 v106, 0xffff0000, v168
	v_add_f32_e32 v101, v101, v106
	v_lshlrev_b32_e32 v106, 16, v169
	v_add_f32_e32 v102, v102, v106
	v_and_b32_e32 v106, 0xffff0000, v169
	v_add_f32_e32 v103, v103, v106
	v_lshlrev_b32_e32 v106, 16, v170
	v_add_f32_e32 v106, v92, v106
	v_and_b32_e32 v92, 0xffff0000, v170
	v_add_f32_e32 v107, v93, v92
	v_lshlrev_b32_e32 v92, 16, v171
	v_add_f32_e32 v108, v94, v92
	v_and_b32_e32 v92, 0xffff0000, v171
	v_lshl_add_u64 v[104:105], s[22:23], 0, v[188:189]
	v_add_f32_e32 v95, v95, v92
	v_lshl_add_u64 v[104:105], v[104:105], 0, v[144:145]
	v_cvt_pk_bf16_f32 v92, v100, v101
	v_cvt_pk_bf16_f32 v93, v102, v103
	v_cvt_pk_bf16_f32 v94, v106, v107
	v_cvt_pk_bf16_f32 v95, v108, v95
	global_store_dwordx4 v[104:105], v[92:95], off offset:256 sc0 sc1
	v_and_b32_e32 v164, 0xffff0000, v164
	v_lshlrev_b32_e32 v205, 16, v165
	v_lshlrev_b32_e32 v92, 16, v172
	v_add_f32_e32 v92, v96, v92
	v_lshlrev_b32_e32 v96, 16, v174
	v_and_b32_e32 v93, 0xffff0000, v172
	v_add_f32_e32 v96, v88, v96
	v_and_b32_e32 v88, 0xffff0000, v174
	v_add_f32_e32 v93, v97, v93
	v_lshlrev_b32_e32 v94, 16, v173
	v_add_f32_e32 v97, v89, v88
	v_lshlrev_b32_e32 v88, 16, v175
	v_add_f32_e32 v94, v98, v94
	v_and_b32_e32 v95, 0xffff0000, v173
	v_add_f32_e32 v98, v90, v88
	v_and_b32_e32 v88, 0xffff0000, v175
	v_add_f32_e32 v95, v99, v95
	v_add_f32_e32 v91, v91, v88
	v_cvt_pk_bf16_f32 v88, v92, v93
	v_lshl_add_u64 v[92:93], s[22:23], 0, v[190:191]
	v_cvt_pk_bf16_f32 v89, v94, v95
	v_cvt_pk_bf16_f32 v90, v96, v97
	v_cvt_pk_bf16_f32 v91, v98, v91
	v_lshl_add_u64 v[92:93], v[92:93], 0, v[144:145]
	global_store_dwordx4 v[92:93], v[88:91], off sc0 sc1
	v_and_b32_e32 v165, 0xffff0000, v165
	v_lshlrev_b32_e32 v206, 16, v166
	v_lshlrev_b32_e32 v88, 16, v176
	v_add_f32_e32 v84, v84, v88
	v_and_b32_e32 v88, 0xffff0000, v176
	v_add_f32_e32 v85, v85, v88
	v_lshlrev_b32_e32 v88, 16, v177
	v_add_f32_e32 v86, v86, v88
	v_and_b32_e32 v88, 0xffff0000, v177
	v_add_f32_e32 v87, v87, v88
	v_lshlrev_b32_e32 v88, 16, v178
	v_add_f32_e32 v88, v76, v88
	v_and_b32_e32 v76, 0xffff0000, v178
	v_add_f32_e32 v89, v77, v76
	v_lshlrev_b32_e32 v76, 16, v179
	v_add_f32_e32 v90, v78, v76
	v_and_b32_e32 v76, 0xffff0000, v179
	v_add_f32_e32 v79, v79, v76
	v_cvt_pk_bf16_f32 v76, v84, v85
	v_cvt_pk_bf16_f32 v77, v86, v87
	v_cvt_pk_bf16_f32 v78, v88, v89
	v_cvt_pk_bf16_f32 v79, v90, v79
	global_store_dwordx4 v[92:93], v[76:79], off offset:256 sc0 sc1
	v_and_b32_e32 v166, 0xffff0000, v166
	v_lshlrev_b32_e32 v207, 16, v167
	v_lshlrev_b32_e32 v76, 16, v180
	v_add_f32_e32 v76, v80, v76
	v_lshlrev_b32_e32 v80, 16, v182
	v_and_b32_e32 v77, 0xffff0000, v180
	v_add_f32_e32 v80, v72, v80
	v_and_b32_e32 v72, 0xffff0000, v182
	v_add_f32_e32 v77, v81, v77
	v_lshlrev_b32_e32 v78, 16, v181
	v_add_f32_e32 v81, v73, v72
	v_lshlrev_b32_e32 v72, 16, v183
	v_add_f32_e32 v78, v82, v78
	v_and_b32_e32 v79, 0xffff0000, v181
	v_add_f32_e32 v82, v74, v72
	v_and_b32_e32 v72, 0xffff0000, v183
	v_add_f32_e32 v79, v83, v79
	v_add_f32_e32 v75, v75, v72
	v_cvt_pk_bf16_f32 v72, v76, v77
	v_lshl_add_u64 v[76:77], s[22:23], 0, v[192:193]
	v_cvt_pk_bf16_f32 v73, v78, v79
	v_cvt_pk_bf16_f32 v74, v80, v81
	v_cvt_pk_bf16_f32 v75, v82, v75
	v_lshl_add_u64 v[76:77], v[76:77], 0, v[144:145]
	global_store_dwordx4 v[76:77], v[72:75], off sc0 sc1
	v_and_b32_e32 v167, 0xffff0000, v167
	v_add_f32_e32 v116, v116, v204
	v_lshlrev_b32_e32 v72, 16, v184
	v_add_f32_e32 v68, v68, v72
	v_and_b32_e32 v72, 0xffff0000, v184
	v_add_f32_e32 v69, v69, v72
	v_lshlrev_b32_e32 v72, 16, v185
	v_add_f32_e32 v70, v70, v72
	v_and_b32_e32 v72, 0xffff0000, v185
	v_add_f32_e32 v71, v71, v72
	v_lshlrev_b32_e32 v72, 16, v186
	v_add_f32_e32 v72, v64, v72
	v_and_b32_e32 v64, 0xffff0000, v186
	v_add_f32_e32 v73, v65, v64
	v_lshlrev_b32_e32 v64, 16, v187
	v_add_f32_e32 v74, v66, v64
	v_and_b32_e32 v64, 0xffff0000, v187
	v_add_f32_e32 v117, v117, v164
	v_add_f32_e32 v118, v118, v205
	v_add_f32_e32 v119, v119, v165
	v_add_f32_e32 v160, v112, v206
	v_add_f32_e32 v161, v113, v166
	v_add_f32_e32 v162, v114, v207
	v_add_f32_e32 v115, v115, v167
	v_add_f32_e32 v67, v67, v64
	v_cvt_pk_bf16_f32 v112, v116, v117
	v_cvt_pk_bf16_f32 v113, v118, v119
	v_cvt_pk_bf16_f32 v114, v160, v161
	v_cvt_pk_bf16_f32 v115, v162, v115
	v_cvt_pk_bf16_f32 v64, v68, v69
	v_cvt_pk_bf16_f32 v65, v70, v71
	v_cvt_pk_bf16_f32 v66, v72, v73
	v_cvt_pk_bf16_f32 v67, v74, v67
	global_store_dwordx4 v[104:105], v[112:115], off sc0 sc1
	global_store_dwordx4 v[76:77], v[64:67], off offset:256 sc0 sc1
	v_lshl_add_u64 v[96:97], v[148:149], 0, s[6:7]
	v_lshl_add_u64 v[68:69], v[146:147], 0, v[96:97]
	global_load_dwordx4 v[64:67], v[68:69], off
	s_nop 0
	global_load_dwordx4 v[68:71], v[68:69], off offset:256
	v_lshl_add_u64 v[98:99], v[148:149], 0, s[8:9]
	v_lshl_add_u64 v[76:77], v[146:147], 0, v[98:99]
	global_load_dwordx4 v[72:75], v[76:77], off
	s_nop 0
	global_load_dwordx4 v[76:79], v[76:77], off offset:256
	v_lshl_add_u64 v[100:101], v[148:149], 0, s[10:11]
	v_lshl_add_u64 v[84:85], v[146:147], 0, v[100:101]
	global_load_dwordx4 v[80:83], v[84:85], off
	s_nop 0
	global_load_dwordx4 v[84:87], v[84:85], off offset:256
	v_lshl_add_u64 v[102:103], v[148:149], 0, s[12:13]
	v_lshl_add_u64 v[92:93], v[146:147], 0, v[102:103]
	global_load_dwordx4 v[88:91], v[92:93], off
	s_nop 0
	global_load_dwordx4 v[92:95], v[92:93], off offset:256
	s_waitcnt vmcnt(0)
; __device__ __forceinline__ float bflo(unsigned w) { return __uint_as_float(w << 16); }
; __device__ __forceinline__ float bfhi(unsigned w) { return __uint_as_float(w & 0xffff0000u); }
;     __device__ __forceinline__ void operator()(const f32x4 (&acc)[2][2][4][2], const Unit& u, int wr, int wc, int fr, int fq) const {
;     ...
; #pragma unroll
;                 for (int m = 0; m < 4; ++m) { const size_t off = (size_t)(row0 + ai * HALF + m * 16) * DM + col0;
;                     float ss = 0.f;
; #pragma unroll
;                     for (int bj = 0; bj < 2; ++bj) { const u32x4 q = bs[m][bj]; const f32x4 a0 = acc[ai][bj][m][0], a1 = acc[ai][bj][m][1];
;                         const float h0 = bflo(q.x) + a0[0], h1 = bfhi(q.x) + a0[1], h2 = bflo(q.y) + a0[2], h3 = bfhi(q.y) + a0[3], h4 = bflo(q.z) + a1[0], h5 = bfhi(q.z) + a1[1], h6 = bflo(q.w) + a1[2], h7 = bfhi(q.w) + a1[3];
;                         ss += (h0 * h0 + h1 * h1) + (h2 * h2 + h3 * h3) + (h4 * h4 + h5 * h5) + (h6 * h6 + h7 * h7);
;                         u32x4 w; w.x = pk2(h0, h1); w.y = pk2(h2, h3); w.z = pk2(h4, h5); w.w = pk2(h6, h7);
;                         *(u32x4*)(out + off + bj * HALF) = w; }
;                     if (ssqp) { ss += __shfl_xor(ss, 16); ss += __shfl_xor(ss, 32); if (fq == 0) ssqp[(size_t)(row0 + ai * HALF + m * 16) * 32 + u.pn * 4 + wc] = ss; } }
;                 asm volatile("" ::: "memory");
	v_lshlrev_b32_e32 v104, 16, v64
	v_and_b32_e32 v64, 0xffff0000, v64
	v_add_f32_e32 v61, v61, v64
	v_lshlrev_b32_e32 v64, 16, v65
	v_add_f32_e32 v62, v62, v64
	v_and_b32_e32 v64, 0xffff0000, v65
	v_add_f32_e32 v63, v63, v64
	v_lshlrev_b32_e32 v64, 16, v66
	v_add_f32_e32 v64, v56, v64
	v_and_b32_e32 v56, 0xffff0000, v66
	v_add_f32_e32 v65, v57, v56
	v_lshlrev_b32_e32 v56, 16, v67
	v_add_f32_e32 v60, v60, v104
	v_add_f32_e32 v66, v58, v56
	v_and_b32_e32 v56, 0xffff0000, v67
	v_add_f32_e32 v59, v59, v56
	v_cvt_pk_bf16_f32 v56, v60, v61
	v_lshl_add_u64 v[60:61], s[22:23], 0, v[96:97]
	v_cvt_pk_bf16_f32 v57, v62, v63
	v_cvt_pk_bf16_f32 v58, v64, v65
	v_cvt_pk_bf16_f32 v59, v66, v59
	v_lshl_add_u64 v[60:61], v[60:61], 0, v[144:145]
	global_store_dwordx4 v[60:61], v[56:59], off sc0 sc1
	s_nop 1
	v_lshlrev_b32_e32 v56, 16, v68
	v_add_f32_e32 v52, v52, v56
	v_and_b32_e32 v56, 0xffff0000, v68
	v_add_f32_e32 v53, v53, v56
	v_lshlrev_b32_e32 v56, 16, v69
	v_add_f32_e32 v54, v54, v56
	v_and_b32_e32 v56, 0xffff0000, v69
	v_add_f32_e32 v55, v55, v56
	v_lshlrev_b32_e32 v56, 16, v70
	v_add_f32_e32 v56, v44, v56
	v_and_b32_e32 v44, 0xffff0000, v70
	v_add_f32_e32 v57, v45, v44
	v_lshlrev_b32_e32 v44, 16, v71
	v_add_f32_e32 v58, v46, v44
	v_and_b32_e32 v44, 0xffff0000, v71
	v_add_f32_e32 v47, v47, v44
	v_cvt_pk_bf16_f32 v44, v52, v53
	v_cvt_pk_bf16_f32 v45, v54, v55
	v_cvt_pk_bf16_f32 v46, v56, v57
	v_cvt_pk_bf16_f32 v47, v58, v47
	global_store_dwordx4 v[60:61], v[44:47], off offset:256 sc0 sc1
	s_nop 1
	v_lshlrev_b32_e32 v44, 16, v72
	v_add_f32_e32 v44, v48, v44
	v_lshlrev_b32_e32 v48, 16, v74
	v_and_b32_e32 v45, 0xffff0000, v72
	v_add_f32_e32 v48, v40, v48
	v_and_b32_e32 v40, 0xffff0000, v74
	v_add_f32_e32 v45, v49, v45
	v_lshlrev_b32_e32 v46, 16, v73
	v_add_f32_e32 v49, v41, v40
	v_lshlrev_b32_e32 v40, 16, v75
	v_add_f32_e32 v46, v50, v46
	v_and_b32_e32 v47, 0xffff0000, v73
	v_add_f32_e32 v50, v42, v40
	v_and_b32_e32 v40, 0xffff0000, v75
	v_add_f32_e32 v47, v51, v47
	v_add_f32_e32 v43, v43, v40
	v_cvt_pk_bf16_f32 v40, v44, v45
	v_lshl_add_u64 v[44:45], s[22:23], 0, v[98:99]
	v_cvt_pk_bf16_f32 v41, v46, v47
	v_cvt_pk_bf16_f32 v42, v48, v49
	v_cvt_pk_bf16_f32 v43, v50, v43
	v_lshl_add_u64 v[44:45], v[44:45], 0, v[144:145]
	global_store_dwordx4 v[44:45], v[40:43], off sc0 sc1
	s_nop 1
	v_lshlrev_b32_e32 v40, 16, v76
	v_add_f32_e32 v36, v36, v40
	v_and_b32_e32 v40, 0xffff0000, v76
	v_add_f32_e32 v37, v37, v40
	v_lshlrev_b32_e32 v40, 16, v77
	v_add_f32_e32 v38, v38, v40
	v_and_b32_e32 v40, 0xffff0000, v77
	v_add_f32_e32 v39, v39, v40
	v_lshlrev_b32_e32 v40, 16, v78
	v_add_f32_e32 v40, v28, v40
	v_and_b32_e32 v28, 0xffff0000, v78
	v_add_f32_e32 v41, v29, v28
	v_lshlrev_b32_e32 v28, 16, v79
	v_add_f32_e32 v42, v30, v28
	v_and_b32_e32 v28, 0xffff0000, v79
	v_add_f32_e32 v31, v31, v28
	v_cvt_pk_bf16_f32 v28, v36, v37
	v_cvt_pk_bf16_f32 v29, v38, v39
	v_cvt_pk_bf16_f32 v30, v40, v41
	v_cvt_pk_bf16_f32 v31, v42, v31
	global_store_dwordx4 v[44:45], v[28:31], off offset:256 sc0 sc1
	s_nop 1
	v_lshlrev_b32_e32 v28, 16, v80
	v_add_f32_e32 v28, v32, v28
	v_lshlrev_b32_e32 v32, 16, v82
	v_and_b32_e32 v29, 0xffff0000, v80
	v_add_f32_e32 v32, v24, v32
	v_and_b32_e32 v24, 0xffff0000, v82
	v_add_f32_e32 v29, v33, v29
	v_lshlrev_b32_e32 v30, 16, v81
	v_add_f32_e32 v33, v25, v24
	v_lshlrev_b32_e32 v24, 16, v83
	v_add_f32_e32 v30, v34, v30
	v_and_b32_e32 v31, 0xffff0000, v81
	v_add_f32_e32 v34, v26, v24
	v_and_b32_e32 v24, 0xffff0000, v83
	v_add_f32_e32 v31, v35, v31
	v_add_f32_e32 v27, v27, v24
	v_cvt_pk_bf16_f32 v24, v28, v29
	v_lshl_add_u64 v[28:29], s[22:23], 0, v[100:101]
	v_cvt_pk_bf16_f32 v25, v30, v31
	v_cvt_pk_bf16_f32 v26, v32, v33
	v_cvt_pk_bf16_f32 v27, v34, v27
	v_lshl_add_u64 v[28:29], v[28:29], 0, v[144:145]
	global_store_dwordx4 v[28:29], v[24:27], off sc0 sc1
	s_nop 1
	v_lshlrev_b32_e32 v24, 16, v84
	v_add_f32_e32 v20, v20, v24
	v_and_b32_e32 v24, 0xffff0000, v84
	v_add_f32_e32 v21, v21, v24
	v_lshlrev_b32_e32 v24, 16, v85
	v_add_f32_e32 v22, v22, v24
	v_and_b32_e32 v24, 0xffff0000, v85
	v_add_f32_e32 v23, v23, v24
	v_lshlrev_b32_e32 v24, 16, v86
	v_add_f32_e32 v24, v12, v24
	v_and_b32_e32 v12, 0xffff0000, v86
	v_add_f32_e32 v25, v13, v12
	v_lshlrev_b32_e32 v12, 16, v87
	v_add_f32_e32 v26, v14, v12
	v_and_b32_e32 v12, 0xffff0000, v87
	v_add_f32_e32 v15, v15, v12
	v_cvt_pk_bf16_f32 v12, v20, v21
	v_cvt_pk_bf16_f32 v13, v22, v23
	v_cvt_pk_bf16_f32 v14, v24, v25
	v_cvt_pk_bf16_f32 v15, v26, v15
	global_store_dwordx4 v[28:29], v[12:15], off offset:256 sc0 sc1
	s_nop 1
	v_lshlrev_b32_e32 v12, 16, v88
	v_add_f32_e32 v12, v16, v12
	v_lshlrev_b32_e32 v16, 16, v90
	v_and_b32_e32 v13, 0xffff0000, v88
	v_add_f32_e32 v16, v8, v16
	v_and_b32_e32 v8, 0xffff0000, v90
	v_add_f32_e32 v13, v17, v13
	v_lshlrev_b32_e32 v14, 16, v89
	v_add_f32_e32 v17, v9, v8
	v_lshlrev_b32_e32 v8, 16, v91
	v_add_f32_e32 v14, v18, v14
	v_and_b32_e32 v15, 0xffff0000, v89
	v_add_f32_e32 v18, v10, v8
	v_and_b32_e32 v8, 0xffff0000, v91
	v_add_f32_e32 v15, v19, v15
	v_add_f32_e32 v11, v11, v8
	v_cvt_pk_bf16_f32 v8, v12, v13
	v_lshl_add_u64 v[12:13], s[22:23], 0, v[102:103]
	v_cvt_pk_bf16_f32 v9, v14, v15
	v_cvt_pk_bf16_f32 v10, v16, v17
	v_cvt_pk_bf16_f32 v11, v18, v11
	v_lshl_add_u64 v[12:13], v[12:13], 0, v[144:145]
	global_store_dwordx4 v[12:13], v[8:11], off sc0 sc1
	s_nop 1
	v_lshlrev_b32_e32 v8, 16, v92
	v_add_f32_e32 v4, v4, v8
	v_and_b32_e32 v8, 0xffff0000, v92
	v_add_f32_e32 v5, v5, v8
	v_lshlrev_b32_e32 v8, 16, v93
	v_add_f32_e32 v6, v6, v8
	v_and_b32_e32 v8, 0xffff0000, v93
	v_add_f32_e32 v7, v7, v8
	v_lshlrev_b32_e32 v8, 16, v94
	v_add_f32_e32 v8, v0, v8
	v_and_b32_e32 v0, 0xffff0000, v94
	v_add_f32_e32 v9, v1, v0
	v_lshlrev_b32_e32 v0, 16, v95
	v_add_f32_e32 v10, v2, v0
	v_and_b32_e32 v0, 0xffff0000, v95
	v_add_f32_e32 v3, v3, v0
	v_cvt_pk_bf16_f32 v0, v4, v5
	v_cvt_pk_bf16_f32 v1, v6, v7
	v_cvt_pk_bf16_f32 v2, v8, v9
	v_cvt_pk_bf16_f32 v3, v10, v3
	global_store_dwordx4 v[12:13], v[0:3], off offset:256 sc0 sc1
	s_cbranch_vccz .LBB0_931
	s_waitcnt vmcnt(0)
	s_cmpk_gt_u32 s3, 0xff
	s_cbranch_scc1 .LBB0_942
	s_barrier
